# in-proj pair K loop: quarter-step schedule (fragment reads one quarter ahead, mid-half-step barriers, DMA stream further ahead)
# speedup vs baseline: 1.0060x; 1.0060x over previous
.Lpk_sw_pf:
	s_and_b32 s100, s100, 0xffffefff
	s_add_u32 m0, s4, 0x0
	s_nop 0
	global_load_lds_dwordx4 v98, s[6:7]
	s_add_u32 m0, s4, 0x400
	s_nop 0
	global_load_lds_dwordx4 v99, s[6:7]
	s_add_u32 m0, s4, 0x800
	s_nop 0
	global_load_lds_dwordx4 v100, s[6:7]
	s_add_u32 m0, s4, 0xc00
	s_nop 0
	global_load_lds_dwordx4 v101, s[6:7]
	v_add_u32_e32 v98, 0x80, v98
	v_add_u32_e32 v99, 0x80, v99
	v_add_u32_e32 v100, 0x80, v100
	v_add_u32_e32 v101, 0x80, v101
	s_add_u32 m0, s4, 0x8000
	s_nop 0
	global_load_lds_dwordx4 v98, s[48:49]
	s_add_u32 m0, s4, 0x8400
	s_nop 0
	global_load_lds_dwordx4 v99, s[48:49]
	s_add_u32 m0, s4, 0x8800
	s_nop 0
	global_load_lds_dwordx4 v100, s[48:49]
	s_add_u32 m0, s4, 0x8c00
	s_nop 0
	global_load_lds_dwordx4 v101, s[48:49]
	s_add_u32 m0, s4, 0x4000
	s_nop 0
	global_load_lds_dwordx4 v98, s[28:29]
	s_add_u32 m0, s4, 0x4400
	s_nop 0
	global_load_lds_dwordx4 v99, s[28:29]
	s_add_u32 m0, s4, 0x4800
	s_nop 0
	global_load_lds_dwordx4 v100, s[28:29]
	s_add_u32 m0, s4, 0x4c00
	s_nop 0
	global_load_lds_dwordx4 v101, s[28:29]
	v_mov_b32_e32 v62, 0
	v_mov_b32_e32 v106, 0
	v_mov_b32_e32 v63, 0
	v_mov_b32_e32 v107, 0
	v_mov_b32_e32 v64, 0
	v_mov_b32_e32 v108, 0
	v_mov_b32_e32 v65, 0
	v_mov_b32_e32 v109, 0
	v_mov_b32_e32 v58, 0
	v_mov_b32_e32 v110, 0
	v_mov_b32_e32 v59, 0
	v_mov_b32_e32 v111, 0
	v_mov_b32_e32 v60, 0
	v_mov_b32_e32 v112, 0
	v_mov_b32_e32 v61, 0
	v_mov_b32_e32 v113, 0
	v_mov_b32_e32 v54, 0
	v_mov_b32_e32 v114, 0
	v_mov_b32_e32 v55, 0
	v_mov_b32_e32 v115, 0
	v_mov_b32_e32 v56, 0
	v_mov_b32_e32 v116, 0
	v_mov_b32_e32 v57, 0
	v_mov_b32_e32 v117, 0
	v_mov_b32_e32 v50, 0
	v_mov_b32_e32 v118, 0
	v_mov_b32_e32 v51, 0
	v_mov_b32_e32 v119, 0
	v_mov_b32_e32 v52, 0
	v_mov_b32_e32 v120, 0
	v_mov_b32_e32 v53, 0
	v_mov_b32_e32 v121, 0
	v_mov_b32_e32 v46, 0
	v_mov_b32_e32 v122, 0
	v_mov_b32_e32 v47, 0
	v_mov_b32_e32 v123, 0
	v_mov_b32_e32 v48, 0
	v_mov_b32_e32 v124, 0
	v_mov_b32_e32 v49, 0
	v_mov_b32_e32 v125, 0
	v_mov_b32_e32 v42, 0
	v_mov_b32_e32 v126, 0
	v_mov_b32_e32 v43, 0
	v_mov_b32_e32 v127, 0
	v_mov_b32_e32 v44, 0
	v_mov_b32_e32 v128, 0
	v_mov_b32_e32 v45, 0
	v_mov_b32_e32 v129, 0
	v_mov_b32_e32 v38, 0
	v_mov_b32_e32 v130, 0
	v_mov_b32_e32 v39, 0
	v_mov_b32_e32 v131, 0
	v_mov_b32_e32 v40, 0
	v_mov_b32_e32 v132, 0
	v_mov_b32_e32 v41, 0
	v_mov_b32_e32 v133, 0
	v_mov_b32_e32 v34, 0
	v_mov_b32_e32 v134, 0
	v_mov_b32_e32 v35, 0
	v_mov_b32_e32 v135, 0
	v_mov_b32_e32 v36, 0
	v_mov_b32_e32 v136, 0
	v_mov_b32_e32 v37, 0
	v_mov_b32_e32 v137, 0
	v_mov_b32_e32 v30, 0
	v_mov_b32_e32 v138, 0
	v_mov_b32_e32 v31, 0
	v_mov_b32_e32 v139, 0
	v_mov_b32_e32 v32, 0
	v_mov_b32_e32 v140, 0
	v_mov_b32_e32 v33, 0
	v_mov_b32_e32 v141, 0
	v_mov_b32_e32 v26, 0
	v_mov_b32_e32 v142, 0
	v_mov_b32_e32 v27, 0
	v_mov_b32_e32 v143, 0
	v_mov_b32_e32 v28, 0
	v_mov_b32_e32 v144, 0
	v_mov_b32_e32 v29, 0
	v_mov_b32_e32 v145, 0
	v_mov_b32_e32 v22, 0
	v_mov_b32_e32 v154, 0
	v_mov_b32_e32 v23, 0
	v_mov_b32_e32 v155, 0
	v_mov_b32_e32 v24, 0
	v_mov_b32_e32 v156, 0
	v_mov_b32_e32 v25, 0
	v_mov_b32_e32 v157, 0
	v_mov_b32_e32 v18, 0
	v_mov_b32_e32 v158, 0
	v_mov_b32_e32 v19, 0
	v_mov_b32_e32 v159, 0
	v_mov_b32_e32 v20, 0
	v_mov_b32_e32 v160, 0
	v_mov_b32_e32 v21, 0
	v_mov_b32_e32 v161, 0
	v_mov_b32_e32 v14, 0
	v_mov_b32_e32 v162, 0
	v_mov_b32_e32 v15, 0
	v_mov_b32_e32 v163, 0
	v_mov_b32_e32 v16, 0
	v_mov_b32_e32 v164, 0
	v_mov_b32_e32 v17, 0
	v_mov_b32_e32 v165, 0
	v_mov_b32_e32 v10, 0
	v_mov_b32_e32 v166, 0
	v_mov_b32_e32 v11, 0
	v_mov_b32_e32 v167, 0
	v_mov_b32_e32 v12, 0
	v_mov_b32_e32 v168, 0
	v_mov_b32_e32 v13, 0
	v_mov_b32_e32 v169, 0
	v_mov_b32_e32 v6, 0
	v_mov_b32_e32 v170, 0
	v_mov_b32_e32 v7, 0
	v_mov_b32_e32 v171, 0
	v_mov_b32_e32 v8, 0
	v_mov_b32_e32 v172, 0
	v_mov_b32_e32 v9, 0
	v_mov_b32_e32 v173, 0
	v_mov_b32_e32 v2, 0
	v_mov_b32_e32 v174, 0
	v_mov_b32_e32 v3, 0
	v_mov_b32_e32 v175, 0
	v_mov_b32_e32 v4, 0
	v_mov_b32_e32 v176, 0
	v_mov_b32_e32 v5, 0
	v_mov_b32_e32 v177, 0
	s_waitcnt vmcnt(12)
	s_barrier
	ds_read_b128 v[218:221], v102 offset:49152
	ds_read_b128 v[222:225], v102 offset:51200
	ds_read_b128 v[226:229], v102 offset:53248
	ds_read_b128 v[230:233], v102 offset:55296
	ds_read_b128 v[66:69], v250 offset:49152
	ds_read_b128 v[70:73], v250 offset:51200
	ds_read_b128 v[74:77], v250 offset:53248
	ds_read_b128 v[78:81], v250 offset:55296
	ds_read_b128 v[234:237], v103 offset:49152
	ds_read_b128 v[238:241], v103 offset:51200
	ds_read_b128 v[242:245], v103 offset:53248
	ds_read_b128 v[246:249], v103 offset:55296
	ds_read_b128 v[82:85], v251 offset:49152
	ds_read_b128 v[86:89], v251 offset:51200
	ds_read_b128 v[90:93], v251 offset:53248
	ds_read_b128 v[94:97], v251 offset:55296
	s_waitcnt lgkmcnt(8)
	v_mfma_f32_16x16x32_bf16 v[62:65], v[66:69], v[218:221], v[62:65]
	v_mfma_f32_16x16x32_bf16 v[46:49], v[66:69], v[222:225], v[46:49]
	v_mfma_f32_16x16x32_bf16 v[30:33], v[66:69], v[226:229], v[30:33]
	v_mfma_f32_16x16x32_bf16 v[14:17], v[66:69], v[230:233], v[14:17]
	v_mfma_f32_16x16x32_bf16 v[58:61], v[70:73], v[218:221], v[58:61]
	v_mfma_f32_16x16x32_bf16 v[42:45], v[70:73], v[222:225], v[42:45]
	v_mfma_f32_16x16x32_bf16 v[26:29], v[70:73], v[226:229], v[26:29]
	v_mfma_f32_16x16x32_bf16 v[10:13], v[70:73], v[230:233], v[10:13]
	v_mfma_f32_16x16x32_bf16 v[54:57], v[74:77], v[218:221], v[54:57]
	v_mfma_f32_16x16x32_bf16 v[38:41], v[74:77], v[222:225], v[38:41]
	v_mfma_f32_16x16x32_bf16 v[22:25], v[74:77], v[226:229], v[22:25]
	v_mfma_f32_16x16x32_bf16 v[6:9], v[74:77], v[230:233], v[6:9]
	v_mfma_f32_16x16x32_bf16 v[50:53], v[78:81], v[218:221], v[50:53]
	v_mfma_f32_16x16x32_bf16 v[34:37], v[78:81], v[222:225], v[34:37]
	v_mfma_f32_16x16x32_bf16 v[18:21], v[78:81], v[226:229], v[18:21]
	v_mfma_f32_16x16x32_bf16 v[2:5], v[78:81], v[230:233], v[2:5]
	s_waitcnt lgkmcnt(0)
	s_waitcnt vmcnt(8)
	s_barrier
	ds_read_b128 v[218:221], v102 offset:0
	ds_read_b128 v[222:225], v102 offset:2048
	ds_read_b128 v[226:229], v102 offset:4096
	ds_read_b128 v[230:233], v102 offset:6144
	v_mfma_f32_16x16x32_bf16 v[62:65], v[82:85], v[234:237], v[62:65]
	s_add_u32 m0, s4, 0xc000
	v_mfma_f32_16x16x32_bf16 v[46:49], v[82:85], v[238:241], v[46:49]
	global_load_lds_dwordx4 v98, s[6:7]
	v_mfma_f32_16x16x32_bf16 v[30:33], v[82:85], v[242:245], v[30:33]
	v_mfma_f32_16x16x32_bf16 v[14:17], v[82:85], v[246:249], v[14:17]
	v_mfma_f32_16x16x32_bf16 v[58:61], v[86:89], v[234:237], v[58:61]
	s_add_u32 m0, s4, 0xc400
	v_mfma_f32_16x16x32_bf16 v[42:45], v[86:89], v[238:241], v[42:45]
	global_load_lds_dwordx4 v99, s[6:7]
	v_mfma_f32_16x16x32_bf16 v[26:29], v[86:89], v[242:245], v[26:29]
	v_mfma_f32_16x16x32_bf16 v[10:13], v[86:89], v[246:249], v[10:13]
	v_mfma_f32_16x16x32_bf16 v[54:57], v[90:93], v[234:237], v[54:57]
	s_add_u32 m0, s4, 0xc800
	v_mfma_f32_16x16x32_bf16 v[38:41], v[90:93], v[238:241], v[38:41]
	global_load_lds_dwordx4 v100, s[6:7]
	v_mfma_f32_16x16x32_bf16 v[22:25], v[90:93], v[242:245], v[22:25]
	v_mfma_f32_16x16x32_bf16 v[6:9], v[90:93], v[246:249], v[6:9]
	v_mfma_f32_16x16x32_bf16 v[50:53], v[94:97], v[234:237], v[50:53]
	s_add_u32 m0, s4, 0xcc00
	v_mfma_f32_16x16x32_bf16 v[34:37], v[94:97], v[238:241], v[34:37]
	global_load_lds_dwordx4 v101, s[6:7]
	v_mfma_f32_16x16x32_bf16 v[18:21], v[94:97], v[242:245], v[18:21]
	v_mfma_f32_16x16x32_bf16 v[2:5], v[94:97], v[246:249], v[2:5]
	v_add_u32_e32 v98, 0x80, v98
	v_add_u32_e32 v99, 0x80, v99
	v_add_u32_e32 v100, 0x80, v100
	v_add_u32_e32 v101, 0x80, v101
	ds_read_b128 v[234:237], v103 offset:0
	ds_read_b128 v[238:241], v103 offset:2048
	ds_read_b128 v[242:245], v103 offset:4096
	ds_read_b128 v[246:249], v103 offset:6144
	s_waitcnt lgkmcnt(4)
	v_mfma_f32_16x16x32_bf16 v[106:109], v[66:69], v[218:221], v[106:109]
	s_add_u32 m0, s4, 0x10000
	v_mfma_f32_16x16x32_bf16 v[122:125], v[66:69], v[222:225], v[122:125]
	global_load_lds_dwordx4 v98, s[48:49]
	v_mfma_f32_16x16x32_bf16 v[138:141], v[66:69], v[226:229], v[138:141]
	v_mfma_f32_16x16x32_bf16 v[162:165], v[66:69], v[230:233], v[162:165]
	v_mfma_f32_16x16x32_bf16 v[110:113], v[70:73], v[218:221], v[110:113]
	s_add_u32 m0, s4, 0x10400
	v_mfma_f32_16x16x32_bf16 v[126:129], v[70:73], v[222:225], v[126:129]
	global_load_lds_dwordx4 v99, s[48:49]
	v_mfma_f32_16x16x32_bf16 v[142:145], v[70:73], v[226:229], v[142:145]
	v_mfma_f32_16x16x32_bf16 v[166:169], v[70:73], v[230:233], v[166:169]
	v_mfma_f32_16x16x32_bf16 v[114:117], v[74:77], v[218:221], v[114:117]
	s_add_u32 m0, s4, 0x10800
	v_mfma_f32_16x16x32_bf16 v[130:133], v[74:77], v[222:225], v[130:133]
	global_load_lds_dwordx4 v100, s[48:49]
	v_mfma_f32_16x16x32_bf16 v[154:157], v[74:77], v[226:229], v[154:157]
	v_mfma_f32_16x16x32_bf16 v[170:173], v[74:77], v[230:233], v[170:173]
	v_mfma_f32_16x16x32_bf16 v[118:121], v[78:81], v[218:221], v[118:121]
	s_add_u32 m0, s4, 0x10c00
	v_mfma_f32_16x16x32_bf16 v[134:137], v[78:81], v[222:225], v[134:137]
	global_load_lds_dwordx4 v101, s[48:49]
	v_mfma_f32_16x16x32_bf16 v[158:161], v[78:81], v[226:229], v[158:161]
	v_mfma_f32_16x16x32_bf16 v[174:177], v[78:81], v[230:233], v[174:177]
	s_waitcnt lgkmcnt(0)
	s_waitcnt vmcnt(8)
	s_barrier
	ds_read_b128 v[218:221], v102 offset:16384
	ds_read_b128 v[222:225], v102 offset:18432
	ds_read_b128 v[226:229], v102 offset:20480
	ds_read_b128 v[230:233], v102 offset:22528
	ds_read_b128 v[66:69], v104 offset:32768
	ds_read_b128 v[70:73], v104 offset:34816
	ds_read_b128 v[74:77], v104 offset:36864
	ds_read_b128 v[78:81], v104 offset:38912
	v_mfma_f32_16x16x32_bf16 v[106:109], v[82:85], v[234:237], v[106:109]
	s_add_u32 m0, s4, 0x0
	v_mfma_f32_16x16x32_bf16 v[122:125], v[82:85], v[238:241], v[122:125]
	global_load_lds_dwordx4 v98, s[28:29]
	v_mfma_f32_16x16x32_bf16 v[138:141], v[82:85], v[242:245], v[138:141]
	v_mfma_f32_16x16x32_bf16 v[162:165], v[82:85], v[246:249], v[162:165]
	v_mfma_f32_16x16x32_bf16 v[110:113], v[86:89], v[234:237], v[110:113]
	s_add_u32 m0, s4, 0x400
	v_mfma_f32_16x16x32_bf16 v[126:129], v[86:89], v[238:241], v[126:129]
	global_load_lds_dwordx4 v99, s[28:29]
	v_mfma_f32_16x16x32_bf16 v[142:145], v[86:89], v[242:245], v[142:145]
	v_mfma_f32_16x16x32_bf16 v[166:169], v[86:89], v[246:249], v[166:169]
	v_mfma_f32_16x16x32_bf16 v[114:117], v[90:93], v[234:237], v[114:117]
	s_add_u32 m0, s4, 0x800
	v_mfma_f32_16x16x32_bf16 v[130:133], v[90:93], v[238:241], v[130:133]
	global_load_lds_dwordx4 v100, s[28:29]
	v_mfma_f32_16x16x32_bf16 v[154:157], v[90:93], v[242:245], v[154:157]
	v_mfma_f32_16x16x32_bf16 v[170:173], v[90:93], v[246:249], v[170:173]
	v_mfma_f32_16x16x32_bf16 v[118:121], v[94:97], v[234:237], v[118:121]
	s_add_u32 m0, s4, 0xc00
	v_mfma_f32_16x16x32_bf16 v[134:137], v[94:97], v[238:241], v[134:137]
	global_load_lds_dwordx4 v101, s[28:29]
	v_mfma_f32_16x16x32_bf16 v[158:161], v[94:97], v[242:245], v[158:161]
	v_mfma_f32_16x16x32_bf16 v[174:177], v[94:97], v[246:249], v[174:177]
	ds_read_b128 v[234:237], v103 offset:16384
	ds_read_b128 v[238:241], v103 offset:18432
	ds_read_b128 v[242:245], v103 offset:20480
	ds_read_b128 v[246:249], v103 offset:22528
	ds_read_b128 v[82:85], v105 offset:32768
	ds_read_b128 v[86:89], v105 offset:34816
	ds_read_b128 v[90:93], v105 offset:36864
	ds_read_b128 v[94:97], v105 offset:38912
	s_waitcnt lgkmcnt(8)
	v_mfma_f32_16x16x32_bf16 v[62:65], v[66:69], v[218:221], v[62:65]
	v_mfma_f32_16x16x32_bf16 v[46:49], v[66:69], v[222:225], v[46:49]
	v_mfma_f32_16x16x32_bf16 v[30:33], v[66:69], v[226:229], v[30:33]
	v_mfma_f32_16x16x32_bf16 v[14:17], v[66:69], v[230:233], v[14:17]
	v_mfma_f32_16x16x32_bf16 v[58:61], v[70:73], v[218:221], v[58:61]
	v_mfma_f32_16x16x32_bf16 v[42:45], v[70:73], v[222:225], v[42:45]
	v_mfma_f32_16x16x32_bf16 v[26:29], v[70:73], v[226:229], v[26:29]
	v_mfma_f32_16x16x32_bf16 v[10:13], v[70:73], v[230:233], v[10:13]
	v_mfma_f32_16x16x32_bf16 v[54:57], v[74:77], v[218:221], v[54:57]
	v_mfma_f32_16x16x32_bf16 v[38:41], v[74:77], v[222:225], v[38:41]
	v_mfma_f32_16x16x32_bf16 v[22:25], v[74:77], v[226:229], v[22:25]
	v_mfma_f32_16x16x32_bf16 v[6:9], v[74:77], v[230:233], v[6:9]
	v_mfma_f32_16x16x32_bf16 v[50:53], v[78:81], v[218:221], v[50:53]
	v_mfma_f32_16x16x32_bf16 v[34:37], v[78:81], v[222:225], v[34:37]
	v_mfma_f32_16x16x32_bf16 v[18:21], v[78:81], v[226:229], v[18:21]
	v_mfma_f32_16x16x32_bf16 v[2:5], v[78:81], v[230:233], v[2:5]
	s_waitcnt lgkmcnt(0)
	s_waitcnt vmcnt(8)
	s_barrier
	ds_read_b128 v[218:221], v102 offset:49152
	ds_read_b128 v[222:225], v102 offset:51200
	ds_read_b128 v[226:229], v102 offset:53248
	ds_read_b128 v[230:233], v102 offset:55296
	v_mfma_f32_16x16x32_bf16 v[62:65], v[82:85], v[234:237], v[62:65]
	s_add_u32 m0, s4, 0x4000
	v_mfma_f32_16x16x32_bf16 v[46:49], v[82:85], v[238:241], v[46:49]
	global_load_lds_dwordx4 v98, s[6:7]
	v_mfma_f32_16x16x32_bf16 v[30:33], v[82:85], v[242:245], v[30:33]
	v_mfma_f32_16x16x32_bf16 v[14:17], v[82:85], v[246:249], v[14:17]
	v_mfma_f32_16x16x32_bf16 v[58:61], v[86:89], v[234:237], v[58:61]
	s_add_u32 m0, s4, 0x4400
	v_mfma_f32_16x16x32_bf16 v[42:45], v[86:89], v[238:241], v[42:45]
	global_load_lds_dwordx4 v99, s[6:7]
	v_mfma_f32_16x16x32_bf16 v[26:29], v[86:89], v[242:245], v[26:29]
	v_mfma_f32_16x16x32_bf16 v[10:13], v[86:89], v[246:249], v[10:13]
	v_mfma_f32_16x16x32_bf16 v[54:57], v[90:93], v[234:237], v[54:57]
	s_add_u32 m0, s4, 0x4800
	v_mfma_f32_16x16x32_bf16 v[38:41], v[90:93], v[238:241], v[38:41]
	global_load_lds_dwordx4 v100, s[6:7]
	v_mfma_f32_16x16x32_bf16 v[22:25], v[90:93], v[242:245], v[22:25]
	v_mfma_f32_16x16x32_bf16 v[6:9], v[90:93], v[246:249], v[6:9]
	v_mfma_f32_16x16x32_bf16 v[50:53], v[94:97], v[234:237], v[50:53]
	s_add_u32 m0, s4, 0x4c00
	v_mfma_f32_16x16x32_bf16 v[34:37], v[94:97], v[238:241], v[34:37]
	global_load_lds_dwordx4 v101, s[6:7]
	v_mfma_f32_16x16x32_bf16 v[18:21], v[94:97], v[242:245], v[18:21]
	v_mfma_f32_16x16x32_bf16 v[2:5], v[94:97], v[246:249], v[2:5]
	v_add_u32_e32 v98, 0x80, v98
	v_add_u32_e32 v99, 0x80, v99
	v_add_u32_e32 v100, 0x80, v100
	v_add_u32_e32 v101, 0x80, v101
	ds_read_b128 v[234:237], v103 offset:49152
	ds_read_b128 v[238:241], v103 offset:51200
	ds_read_b128 v[242:245], v103 offset:53248
	ds_read_b128 v[246:249], v103 offset:55296
	s_waitcnt lgkmcnt(4)
	v_mfma_f32_16x16x32_bf16 v[106:109], v[66:69], v[218:221], v[106:109]
	s_add_u32 m0, s4, 0x8000
	v_mfma_f32_16x16x32_bf16 v[122:125], v[66:69], v[222:225], v[122:125]
	global_load_lds_dwordx4 v98, s[48:49]
	v_mfma_f32_16x16x32_bf16 v[138:141], v[66:69], v[226:229], v[138:141]
	v_mfma_f32_16x16x32_bf16 v[162:165], v[66:69], v[230:233], v[162:165]
	v_mfma_f32_16x16x32_bf16 v[110:113], v[70:73], v[218:221], v[110:113]
	s_add_u32 m0, s4, 0x8400
	v_mfma_f32_16x16x32_bf16 v[126:129], v[70:73], v[222:225], v[126:129]
	global_load_lds_dwordx4 v99, s[48:49]
	v_mfma_f32_16x16x32_bf16 v[142:145], v[70:73], v[226:229], v[142:145]
	v_mfma_f32_16x16x32_bf16 v[166:169], v[70:73], v[230:233], v[166:169]
	v_mfma_f32_16x16x32_bf16 v[114:117], v[74:77], v[218:221], v[114:117]
	s_add_u32 m0, s4, 0x8800
	v_mfma_f32_16x16x32_bf16 v[130:133], v[74:77], v[222:225], v[130:133]
	global_load_lds_dwordx4 v100, s[48:49]
	v_mfma_f32_16x16x32_bf16 v[154:157], v[74:77], v[226:229], v[154:157]
	v_mfma_f32_16x16x32_bf16 v[170:173], v[74:77], v[230:233], v[170:173]
	v_mfma_f32_16x16x32_bf16 v[118:121], v[78:81], v[218:221], v[118:121]
	s_add_u32 m0, s4, 0x8c00
	v_mfma_f32_16x16x32_bf16 v[134:137], v[78:81], v[222:225], v[134:137]
	global_load_lds_dwordx4 v101, s[48:49]
	v_mfma_f32_16x16x32_bf16 v[158:161], v[78:81], v[226:229], v[158:161]
	v_mfma_f32_16x16x32_bf16 v[174:177], v[78:81], v[230:233], v[174:177]
	s_waitcnt lgkmcnt(0)
	s_waitcnt vmcnt(8)
	s_barrier
	ds_read_b128 v[218:221], v102 offset:0
	ds_read_b128 v[222:225], v102 offset:2048
	ds_read_b128 v[226:229], v102 offset:4096
	ds_read_b128 v[230:233], v102 offset:6144
	ds_read_b128 v[66:69], v250 offset:49152
	ds_read_b128 v[70:73], v250 offset:51200
	ds_read_b128 v[74:77], v250 offset:53248
	ds_read_b128 v[78:81], v250 offset:55296
	v_mfma_f32_16x16x32_bf16 v[106:109], v[82:85], v[234:237], v[106:109]
	s_add_u32 m0, s4, 0xc000
	v_mfma_f32_16x16x32_bf16 v[122:125], v[82:85], v[238:241], v[122:125]
	global_load_lds_dwordx4 v98, s[28:29]
	v_mfma_f32_16x16x32_bf16 v[138:141], v[82:85], v[242:245], v[138:141]
	v_mfma_f32_16x16x32_bf16 v[162:165], v[82:85], v[246:249], v[162:165]
	v_mfma_f32_16x16x32_bf16 v[110:113], v[86:89], v[234:237], v[110:113]
	s_add_u32 m0, s4, 0xc400
	v_mfma_f32_16x16x32_bf16 v[126:129], v[86:89], v[238:241], v[126:129]
	global_load_lds_dwordx4 v99, s[28:29]
	v_mfma_f32_16x16x32_bf16 v[142:145], v[86:89], v[242:245], v[142:145]
	v_mfma_f32_16x16x32_bf16 v[166:169], v[86:89], v[246:249], v[166:169]
	v_mfma_f32_16x16x32_bf16 v[114:117], v[90:93], v[234:237], v[114:117]
	s_add_u32 m0, s4, 0xc800
	v_mfma_f32_16x16x32_bf16 v[130:133], v[90:93], v[238:241], v[130:133]
	global_load_lds_dwordx4 v100, s[28:29]
	v_mfma_f32_16x16x32_bf16 v[154:157], v[90:93], v[242:245], v[154:157]
	v_mfma_f32_16x16x32_bf16 v[170:173], v[90:93], v[246:249], v[170:173]
	v_mfma_f32_16x16x32_bf16 v[118:121], v[94:97], v[234:237], v[118:121]
	s_add_u32 m0, s4, 0xcc00
	v_mfma_f32_16x16x32_bf16 v[134:137], v[94:97], v[238:241], v[134:137]
	global_load_lds_dwordx4 v101, s[28:29]
	v_mfma_f32_16x16x32_bf16 v[158:161], v[94:97], v[242:245], v[158:161]
	v_mfma_f32_16x16x32_bf16 v[174:177], v[94:97], v[246:249], v[174:177]
	ds_read_b128 v[234:237], v103 offset:0
	ds_read_b128 v[238:241], v103 offset:2048
	ds_read_b128 v[242:245], v103 offset:4096
	ds_read_b128 v[246:249], v103 offset:6144
	ds_read_b128 v[82:85], v251 offset:49152
	ds_read_b128 v[86:89], v251 offset:51200
	ds_read_b128 v[90:93], v251 offset:53248
	ds_read_b128 v[94:97], v251 offset:55296
	s_waitcnt lgkmcnt(8)
	v_mfma_f32_16x16x32_bf16 v[62:65], v[66:69], v[218:221], v[62:65]
	v_mfma_f32_16x16x32_bf16 v[46:49], v[66:69], v[222:225], v[46:49]
	v_mfma_f32_16x16x32_bf16 v[30:33], v[66:69], v[226:229], v[30:33]
	v_mfma_f32_16x16x32_bf16 v[14:17], v[66:69], v[230:233], v[14:17]
	v_mfma_f32_16x16x32_bf16 v[58:61], v[70:73], v[218:221], v[58:61]
	v_mfma_f32_16x16x32_bf16 v[42:45], v[70:73], v[222:225], v[42:45]
	v_mfma_f32_16x16x32_bf16 v[26:29], v[70:73], v[226:229], v[26:29]
	v_mfma_f32_16x16x32_bf16 v[10:13], v[70:73], v[230:233], v[10:13]
	v_mfma_f32_16x16x32_bf16 v[54:57], v[74:77], v[218:221], v[54:57]
	v_mfma_f32_16x16x32_bf16 v[38:41], v[74:77], v[222:225], v[38:41]
	v_mfma_f32_16x16x32_bf16 v[22:25], v[74:77], v[226:229], v[22:25]
	v_mfma_f32_16x16x32_bf16 v[6:9], v[74:77], v[230:233], v[6:9]
	v_mfma_f32_16x16x32_bf16 v[50:53], v[78:81], v[218:221], v[50:53]
	v_mfma_f32_16x16x32_bf16 v[34:37], v[78:81], v[222:225], v[34:37]
	v_mfma_f32_16x16x32_bf16 v[18:21], v[78:81], v[226:229], v[18:21]
	v_mfma_f32_16x16x32_bf16 v[2:5], v[78:81], v[230:233], v[2:5]
	s_waitcnt lgkmcnt(0)
	s_waitcnt vmcnt(8)
	s_barrier
	ds_read_b128 v[218:221], v102 offset:16384
	ds_read_b128 v[222:225], v102 offset:18432
	ds_read_b128 v[226:229], v102 offset:20480
	ds_read_b128 v[230:233], v102 offset:22528
	v_mfma_f32_16x16x32_bf16 v[62:65], v[82:85], v[234:237], v[62:65]
	s_add_u32 m0, s4, 0x0
	v_mfma_f32_16x16x32_bf16 v[46:49], v[82:85], v[238:241], v[46:49]
	global_load_lds_dwordx4 v98, s[6:7]
	v_mfma_f32_16x16x32_bf16 v[30:33], v[82:85], v[242:245], v[30:33]
	v_mfma_f32_16x16x32_bf16 v[14:17], v[82:85], v[246:249], v[14:17]
	v_mfma_f32_16x16x32_bf16 v[58:61], v[86:89], v[234:237], v[58:61]
	s_add_u32 m0, s4, 0x400
	v_mfma_f32_16x16x32_bf16 v[42:45], v[86:89], v[238:241], v[42:45]
	global_load_lds_dwordx4 v99, s[6:7]
	v_mfma_f32_16x16x32_bf16 v[26:29], v[86:89], v[242:245], v[26:29]
	v_mfma_f32_16x16x32_bf16 v[10:13], v[86:89], v[246:249], v[10:13]
	v_mfma_f32_16x16x32_bf16 v[54:57], v[90:93], v[234:237], v[54:57]
	s_add_u32 m0, s4, 0x800
	v_mfma_f32_16x16x32_bf16 v[38:41], v[90:93], v[238:241], v[38:41]
	global_load_lds_dwordx4 v100, s[6:7]
	v_mfma_f32_16x16x32_bf16 v[22:25], v[90:93], v[242:245], v[22:25]
	v_mfma_f32_16x16x32_bf16 v[6:9], v[90:93], v[246:249], v[6:9]
	v_mfma_f32_16x16x32_bf16 v[50:53], v[94:97], v[234:237], v[50:53]
	s_add_u32 m0, s4, 0xc00
	v_mfma_f32_16x16x32_bf16 v[34:37], v[94:97], v[238:241], v[34:37]
	global_load_lds_dwordx4 v101, s[6:7]
	v_mfma_f32_16x16x32_bf16 v[18:21], v[94:97], v[242:245], v[18:21]
	v_mfma_f32_16x16x32_bf16 v[2:5], v[94:97], v[246:249], v[2:5]
	v_add_u32_e32 v98, 0x80, v98
	v_add_u32_e32 v99, 0x80, v99
	v_add_u32_e32 v100, 0x80, v100
	v_add_u32_e32 v101, 0x80, v101
	ds_read_b128 v[234:237], v103 offset:16384
	ds_read_b128 v[238:241], v103 offset:18432
	ds_read_b128 v[242:245], v103 offset:20480
	ds_read_b128 v[246:249], v103 offset:22528
	s_waitcnt lgkmcnt(4)
	v_mfma_f32_16x16x32_bf16 v[106:109], v[66:69], v[218:221], v[106:109]
	s_add_u32 m0, s4, 0x10000
	v_mfma_f32_16x16x32_bf16 v[122:125], v[66:69], v[222:225], v[122:125]
	global_load_lds_dwordx4 v98, s[48:49]
	v_mfma_f32_16x16x32_bf16 v[138:141], v[66:69], v[226:229], v[138:141]
	v_mfma_f32_16x16x32_bf16 v[162:165], v[66:69], v[230:233], v[162:165]
	v_mfma_f32_16x16x32_bf16 v[110:113], v[70:73], v[218:221], v[110:113]
	s_add_u32 m0, s4, 0x10400
	v_mfma_f32_16x16x32_bf16 v[126:129], v[70:73], v[222:225], v[126:129]
	global_load_lds_dwordx4 v99, s[48:49]
	v_mfma_f32_16x16x32_bf16 v[142:145], v[70:73], v[226:229], v[142:145]
	v_mfma_f32_16x16x32_bf16 v[166:169], v[70:73], v[230:233], v[166:169]
	v_mfma_f32_16x16x32_bf16 v[114:117], v[74:77], v[218:221], v[114:117]
	s_add_u32 m0, s4, 0x10800
	v_mfma_f32_16x16x32_bf16 v[130:133], v[74:77], v[222:225], v[130:133]
	global_load_lds_dwordx4 v100, s[48:49]
	v_mfma_f32_16x16x32_bf16 v[154:157], v[74:77], v[226:229], v[154:157]
	v_mfma_f32_16x16x32_bf16 v[170:173], v[74:77], v[230:233], v[170:173]
	v_mfma_f32_16x16x32_bf16 v[118:121], v[78:81], v[218:221], v[118:121]
	s_add_u32 m0, s4, 0x10c00
	v_mfma_f32_16x16x32_bf16 v[134:137], v[78:81], v[222:225], v[134:137]
	global_load_lds_dwordx4 v101, s[48:49]
	v_mfma_f32_16x16x32_bf16 v[158:161], v[78:81], v[226:229], v[158:161]
	v_mfma_f32_16x16x32_bf16 v[174:177], v[78:81], v[230:233], v[174:177]
	s_waitcnt lgkmcnt(0)
	s_waitcnt vmcnt(8)
	s_barrier
	ds_read_b128 v[218:221], v102 offset:49152
	ds_read_b128 v[222:225], v102 offset:51200
	ds_read_b128 v[226:229], v102 offset:53248
	ds_read_b128 v[230:233], v102 offset:55296
	ds_read_b128 v[66:69], v104 offset:32768
	ds_read_b128 v[70:73], v104 offset:34816
	ds_read_b128 v[74:77], v104 offset:36864
	ds_read_b128 v[78:81], v104 offset:38912
	v_mfma_f32_16x16x32_bf16 v[106:109], v[82:85], v[234:237], v[106:109]
	s_add_u32 m0, s4, 0x4000
	v_mfma_f32_16x16x32_bf16 v[122:125], v[82:85], v[238:241], v[122:125]
	global_load_lds_dwordx4 v98, s[28:29]
	v_mfma_f32_16x16x32_bf16 v[138:141], v[82:85], v[242:245], v[138:141]
	v_mfma_f32_16x16x32_bf16 v[162:165], v[82:85], v[246:249], v[162:165]
	v_mfma_f32_16x16x32_bf16 v[110:113], v[86:89], v[234:237], v[110:113]
	s_add_u32 m0, s4, 0x4400
	v_mfma_f32_16x16x32_bf16 v[126:129], v[86:89], v[238:241], v[126:129]
	global_load_lds_dwordx4 v99, s[28:29]
	v_mfma_f32_16x16x32_bf16 v[142:145], v[86:89], v[242:245], v[142:145]
	v_mfma_f32_16x16x32_bf16 v[166:169], v[86:89], v[246:249], v[166:169]
	v_mfma_f32_16x16x32_bf16 v[114:117], v[90:93], v[234:237], v[114:117]
	s_add_u32 m0, s4, 0x4800
	v_mfma_f32_16x16x32_bf16 v[130:133], v[90:93], v[238:241], v[130:133]
	global_load_lds_dwordx4 v100, s[28:29]
	v_mfma_f32_16x16x32_bf16 v[154:157], v[90:93], v[242:245], v[154:157]
	v_mfma_f32_16x16x32_bf16 v[170:173], v[90:93], v[246:249], v[170:173]
	v_mfma_f32_16x16x32_bf16 v[118:121], v[94:97], v[234:237], v[118:121]
	s_add_u32 m0, s4, 0x4c00
	v_mfma_f32_16x16x32_bf16 v[134:137], v[94:97], v[238:241], v[134:137]
	global_load_lds_dwordx4 v101, s[28:29]
	v_mfma_f32_16x16x32_bf16 v[158:161], v[94:97], v[242:245], v[158:161]
	v_mfma_f32_16x16x32_bf16 v[174:177], v[94:97], v[246:249], v[174:177]
	ds_read_b128 v[234:237], v103 offset:49152
	ds_read_b128 v[238:241], v103 offset:51200
	ds_read_b128 v[242:245], v103 offset:53248
	ds_read_b128 v[246:249], v103 offset:55296
	ds_read_b128 v[82:85], v105 offset:32768
	ds_read_b128 v[86:89], v105 offset:34816
	ds_read_b128 v[90:93], v105 offset:36864
	ds_read_b128 v[94:97], v105 offset:38912
	s_waitcnt lgkmcnt(8)
	v_mfma_f32_16x16x32_bf16 v[62:65], v[66:69], v[218:221], v[62:65]
	v_mfma_f32_16x16x32_bf16 v[46:49], v[66:69], v[222:225], v[46:49]
	v_mfma_f32_16x16x32_bf16 v[30:33], v[66:69], v[226:229], v[30:33]
	v_mfma_f32_16x16x32_bf16 v[14:17], v[66:69], v[230:233], v[14:17]
	v_mfma_f32_16x16x32_bf16 v[58:61], v[70:73], v[218:221], v[58:61]
	v_mfma_f32_16x16x32_bf16 v[42:45], v[70:73], v[222:225], v[42:45]
	v_mfma_f32_16x16x32_bf16 v[26:29], v[70:73], v[226:229], v[26:29]
	v_mfma_f32_16x16x32_bf16 v[10:13], v[70:73], v[230:233], v[10:13]
	v_mfma_f32_16x16x32_bf16 v[54:57], v[74:77], v[218:221], v[54:57]
	v_mfma_f32_16x16x32_bf16 v[38:41], v[74:77], v[222:225], v[38:41]
	v_mfma_f32_16x16x32_bf16 v[22:25], v[74:77], v[226:229], v[22:25]
	v_mfma_f32_16x16x32_bf16 v[6:9], v[74:77], v[230:233], v[6:9]
	v_mfma_f32_16x16x32_bf16 v[50:53], v[78:81], v[218:221], v[50:53]
	v_mfma_f32_16x16x32_bf16 v[34:37], v[78:81], v[222:225], v[34:37]
	v_mfma_f32_16x16x32_bf16 v[18:21], v[78:81], v[226:229], v[18:21]
	v_mfma_f32_16x16x32_bf16 v[2:5], v[78:81], v[230:233], v[2:5]
	s_waitcnt lgkmcnt(0)
	s_waitcnt vmcnt(8)
	s_barrier
	ds_read_b128 v[218:221], v102 offset:0
	ds_read_b128 v[222:225], v102 offset:2048
	ds_read_b128 v[226:229], v102 offset:4096
	ds_read_b128 v[230:233], v102 offset:6144
	v_mfma_f32_16x16x32_bf16 v[62:65], v[82:85], v[234:237], v[62:65]
	s_add_u32 m0, s4, 0xc000
	v_mfma_f32_16x16x32_bf16 v[46:49], v[82:85], v[238:241], v[46:49]
	global_load_lds_dwordx4 v98, s[6:7]
	v_mfma_f32_16x16x32_bf16 v[30:33], v[82:85], v[242:245], v[30:33]
	v_mfma_f32_16x16x32_bf16 v[14:17], v[82:85], v[246:249], v[14:17]
	v_mfma_f32_16x16x32_bf16 v[58:61], v[86:89], v[234:237], v[58:61]
	s_add_u32 m0, s4, 0xc400
	v_mfma_f32_16x16x32_bf16 v[42:45], v[86:89], v[238:241], v[42:45]
	global_load_lds_dwordx4 v99, s[6:7]
	v_mfma_f32_16x16x32_bf16 v[26:29], v[86:89], v[242:245], v[26:29]
	v_mfma_f32_16x16x32_bf16 v[10:13], v[86:89], v[246:249], v[10:13]
	v_mfma_f32_16x16x32_bf16 v[54:57], v[90:93], v[234:237], v[54:57]
	s_add_u32 m0, s4, 0xc800
	v_mfma_f32_16x16x32_bf16 v[38:41], v[90:93], v[238:241], v[38:41]
	global_load_lds_dwordx4 v100, s[6:7]
	v_mfma_f32_16x16x32_bf16 v[22:25], v[90:93], v[242:245], v[22:25]
	v_mfma_f32_16x16x32_bf16 v[6:9], v[90:93], v[246:249], v[6:9]
	v_mfma_f32_16x16x32_bf16 v[50:53], v[94:97], v[234:237], v[50:53]
	s_add_u32 m0, s4, 0xcc00
	v_mfma_f32_16x16x32_bf16 v[34:37], v[94:97], v[238:241], v[34:37]
	global_load_lds_dwordx4 v101, s[6:7]
	v_mfma_f32_16x16x32_bf16 v[18:21], v[94:97], v[242:245], v[18:21]
	v_mfma_f32_16x16x32_bf16 v[2:5], v[94:97], v[246:249], v[2:5]
	v_add_u32_e32 v98, 0x80, v98
	v_add_u32_e32 v99, 0x80, v99
	v_add_u32_e32 v100, 0x80, v100
	v_add_u32_e32 v101, 0x80, v101
	ds_read_b128 v[234:237], v103 offset:0
	ds_read_b128 v[238:241], v103 offset:2048
	ds_read_b128 v[242:245], v103 offset:4096
	ds_read_b128 v[246:249], v103 offset:6144
	s_waitcnt lgkmcnt(4)
	v_mfma_f32_16x16x32_bf16 v[106:109], v[66:69], v[218:221], v[106:109]
	s_add_u32 m0, s4, 0x8000
	v_mfma_f32_16x16x32_bf16 v[122:125], v[66:69], v[222:225], v[122:125]
	global_load_lds_dwordx4 v98, s[48:49]
	v_mfma_f32_16x16x32_bf16 v[138:141], v[66:69], v[226:229], v[138:141]
	v_mfma_f32_16x16x32_bf16 v[162:165], v[66:69], v[230:233], v[162:165]
	v_mfma_f32_16x16x32_bf16 v[110:113], v[70:73], v[218:221], v[110:113]
	s_add_u32 m0, s4, 0x8400
	v_mfma_f32_16x16x32_bf16 v[126:129], v[70:73], v[222:225], v[126:129]
	global_load_lds_dwordx4 v99, s[48:49]
	v_mfma_f32_16x16x32_bf16 v[142:145], v[70:73], v[226:229], v[142:145]
	v_mfma_f32_16x16x32_bf16 v[166:169], v[70:73], v[230:233], v[166:169]
	v_mfma_f32_16x16x32_bf16 v[114:117], v[74:77], v[218:221], v[114:117]
	s_add_u32 m0, s4, 0x8800
	v_mfma_f32_16x16x32_bf16 v[130:133], v[74:77], v[222:225], v[130:133]
	global_load_lds_dwordx4 v100, s[48:49]
	v_mfma_f32_16x16x32_bf16 v[154:157], v[74:77], v[226:229], v[154:157]
	v_mfma_f32_16x16x32_bf16 v[170:173], v[74:77], v[230:233], v[170:173]
	v_mfma_f32_16x16x32_bf16 v[118:121], v[78:81], v[218:221], v[118:121]
	s_add_u32 m0, s4, 0x8c00
	v_mfma_f32_16x16x32_bf16 v[134:137], v[78:81], v[222:225], v[134:137]
	global_load_lds_dwordx4 v101, s[48:49]
	v_mfma_f32_16x16x32_bf16 v[158:161], v[78:81], v[226:229], v[158:161]
	v_mfma_f32_16x16x32_bf16 v[174:177], v[78:81], v[230:233], v[174:177]
	s_waitcnt lgkmcnt(0)
	s_waitcnt vmcnt(8)
	s_barrier
	ds_read_b128 v[218:221], v102 offset:16384
	ds_read_b128 v[222:225], v102 offset:18432
	ds_read_b128 v[226:229], v102 offset:20480
	ds_read_b128 v[230:233], v102 offset:22528
	ds_read_b128 v[66:69], v250 offset:49152
	ds_read_b128 v[70:73], v250 offset:51200
	ds_read_b128 v[74:77], v250 offset:53248
	ds_read_b128 v[78:81], v250 offset:55296
	v_mfma_f32_16x16x32_bf16 v[106:109], v[82:85], v[234:237], v[106:109]
	s_add_u32 m0, s4, 0x0
	v_mfma_f32_16x16x32_bf16 v[122:125], v[82:85], v[238:241], v[122:125]
	global_load_lds_dwordx4 v98, s[28:29]
	v_mfma_f32_16x16x32_bf16 v[138:141], v[82:85], v[242:245], v[138:141]
	v_mfma_f32_16x16x32_bf16 v[162:165], v[82:85], v[246:249], v[162:165]
	v_mfma_f32_16x16x32_bf16 v[110:113], v[86:89], v[234:237], v[110:113]
	s_add_u32 m0, s4, 0x400
	v_mfma_f32_16x16x32_bf16 v[126:129], v[86:89], v[238:241], v[126:129]
	global_load_lds_dwordx4 v99, s[28:29]
	v_mfma_f32_16x16x32_bf16 v[142:145], v[86:89], v[242:245], v[142:145]
	v_mfma_f32_16x16x32_bf16 v[166:169], v[86:89], v[246:249], v[166:169]
	v_mfma_f32_16x16x32_bf16 v[114:117], v[90:93], v[234:237], v[114:117]
	s_add_u32 m0, s4, 0x800
	v_mfma_f32_16x16x32_bf16 v[130:133], v[90:93], v[238:241], v[130:133]
	global_load_lds_dwordx4 v100, s[28:29]
	v_mfma_f32_16x16x32_bf16 v[154:157], v[90:93], v[242:245], v[154:157]
	v_mfma_f32_16x16x32_bf16 v[170:173], v[90:93], v[246:249], v[170:173]
	v_mfma_f32_16x16x32_bf16 v[118:121], v[94:97], v[234:237], v[118:121]
	s_add_u32 m0, s4, 0xc00
	v_mfma_f32_16x16x32_bf16 v[134:137], v[94:97], v[238:241], v[134:137]
	global_load_lds_dwordx4 v101, s[28:29]
	v_mfma_f32_16x16x32_bf16 v[158:161], v[94:97], v[242:245], v[158:161]
	v_mfma_f32_16x16x32_bf16 v[174:177], v[94:97], v[246:249], v[174:177]
	ds_read_b128 v[234:237], v103 offset:16384
	ds_read_b128 v[238:241], v103 offset:18432
	ds_read_b128 v[242:245], v103 offset:20480
	ds_read_b128 v[246:249], v103 offset:22528
	ds_read_b128 v[82:85], v251 offset:49152
	ds_read_b128 v[86:89], v251 offset:51200
	ds_read_b128 v[90:93], v251 offset:53248
	ds_read_b128 v[94:97], v251 offset:55296
	s_waitcnt lgkmcnt(8)
	v_mfma_f32_16x16x32_bf16 v[62:65], v[66:69], v[218:221], v[62:65]
	v_mfma_f32_16x16x32_bf16 v[46:49], v[66:69], v[222:225], v[46:49]
	v_mfma_f32_16x16x32_bf16 v[30:33], v[66:69], v[226:229], v[30:33]
	v_mfma_f32_16x16x32_bf16 v[14:17], v[66:69], v[230:233], v[14:17]
	v_mfma_f32_16x16x32_bf16 v[58:61], v[70:73], v[218:221], v[58:61]
	v_mfma_f32_16x16x32_bf16 v[42:45], v[70:73], v[222:225], v[42:45]
	v_mfma_f32_16x16x32_bf16 v[26:29], v[70:73], v[226:229], v[26:29]
	v_mfma_f32_16x16x32_bf16 v[10:13], v[70:73], v[230:233], v[10:13]
	v_mfma_f32_16x16x32_bf16 v[54:57], v[74:77], v[218:221], v[54:57]
	v_mfma_f32_16x16x32_bf16 v[38:41], v[74:77], v[222:225], v[38:41]
	v_mfma_f32_16x16x32_bf16 v[22:25], v[74:77], v[226:229], v[22:25]
	v_mfma_f32_16x16x32_bf16 v[6:9], v[74:77], v[230:233], v[6:9]
	v_mfma_f32_16x16x32_bf16 v[50:53], v[78:81], v[218:221], v[50:53]
	v_mfma_f32_16x16x32_bf16 v[34:37], v[78:81], v[222:225], v[34:37]
	v_mfma_f32_16x16x32_bf16 v[18:21], v[78:81], v[226:229], v[18:21]
	v_mfma_f32_16x16x32_bf16 v[2:5], v[78:81], v[230:233], v[2:5]
	s_waitcnt lgkmcnt(0)
	s_waitcnt vmcnt(8)
	s_barrier
	ds_read_b128 v[218:221], v102 offset:49152
	ds_read_b128 v[222:225], v102 offset:51200
	ds_read_b128 v[226:229], v102 offset:53248
	ds_read_b128 v[230:233], v102 offset:55296
	v_mfma_f32_16x16x32_bf16 v[62:65], v[82:85], v[234:237], v[62:65]
	s_add_u32 m0, s4, 0x4000
	v_mfma_f32_16x16x32_bf16 v[46:49], v[82:85], v[238:241], v[46:49]
	global_load_lds_dwordx4 v98, s[6:7]
	v_mfma_f32_16x16x32_bf16 v[30:33], v[82:85], v[242:245], v[30:33]
	v_mfma_f32_16x16x32_bf16 v[14:17], v[82:85], v[246:249], v[14:17]
	v_mfma_f32_16x16x32_bf16 v[58:61], v[86:89], v[234:237], v[58:61]
	s_add_u32 m0, s4, 0x4400
	v_mfma_f32_16x16x32_bf16 v[42:45], v[86:89], v[238:241], v[42:45]
	global_load_lds_dwordx4 v99, s[6:7]
	v_mfma_f32_16x16x32_bf16 v[26:29], v[86:89], v[242:245], v[26:29]
	v_mfma_f32_16x16x32_bf16 v[10:13], v[86:89], v[246:249], v[10:13]
	v_mfma_f32_16x16x32_bf16 v[54:57], v[90:93], v[234:237], v[54:57]
	s_add_u32 m0, s4, 0x4800
	v_mfma_f32_16x16x32_bf16 v[38:41], v[90:93], v[238:241], v[38:41]
	global_load_lds_dwordx4 v100, s[6:7]
	v_mfma_f32_16x16x32_bf16 v[22:25], v[90:93], v[242:245], v[22:25]
	v_mfma_f32_16x16x32_bf16 v[6:9], v[90:93], v[246:249], v[6:9]
	v_mfma_f32_16x16x32_bf16 v[50:53], v[94:97], v[234:237], v[50:53]
	s_add_u32 m0, s4, 0x4c00
	v_mfma_f32_16x16x32_bf16 v[34:37], v[94:97], v[238:241], v[34:37]
	global_load_lds_dwordx4 v101, s[6:7]
	v_mfma_f32_16x16x32_bf16 v[18:21], v[94:97], v[242:245], v[18:21]
	v_mfma_f32_16x16x32_bf16 v[2:5], v[94:97], v[246:249], v[2:5]
	v_add_u32_e32 v98, 0x80, v98
	v_add_u32_e32 v99, 0x80, v99
	v_add_u32_e32 v100, 0x80, v100
	v_add_u32_e32 v101, 0x80, v101
	ds_read_b128 v[234:237], v103 offset:49152
	ds_read_b128 v[238:241], v103 offset:51200
	ds_read_b128 v[242:245], v103 offset:53248
	ds_read_b128 v[246:249], v103 offset:55296
	s_waitcnt lgkmcnt(4)
	v_mfma_f32_16x16x32_bf16 v[106:109], v[66:69], v[218:221], v[106:109]
	s_add_u32 m0, s4, 0x10000
	v_mfma_f32_16x16x32_bf16 v[122:125], v[66:69], v[222:225], v[122:125]
	global_load_lds_dwordx4 v98, s[48:49]
	v_mfma_f32_16x16x32_bf16 v[138:141], v[66:69], v[226:229], v[138:141]
	v_mfma_f32_16x16x32_bf16 v[162:165], v[66:69], v[230:233], v[162:165]
	v_mfma_f32_16x16x32_bf16 v[110:113], v[70:73], v[218:221], v[110:113]
	s_add_u32 m0, s4, 0x10400
	v_mfma_f32_16x16x32_bf16 v[126:129], v[70:73], v[222:225], v[126:129]
	global_load_lds_dwordx4 v99, s[48:49]
	v_mfma_f32_16x16x32_bf16 v[142:145], v[70:73], v[226:229], v[142:145]
	v_mfma_f32_16x16x32_bf16 v[166:169], v[70:73], v[230:233], v[166:169]
	v_mfma_f32_16x16x32_bf16 v[114:117], v[74:77], v[218:221], v[114:117]
	s_add_u32 m0, s4, 0x10800
	v_mfma_f32_16x16x32_bf16 v[130:133], v[74:77], v[222:225], v[130:133]
	global_load_lds_dwordx4 v100, s[48:49]
	v_mfma_f32_16x16x32_bf16 v[154:157], v[74:77], v[226:229], v[154:157]
	v_mfma_f32_16x16x32_bf16 v[170:173], v[74:77], v[230:233], v[170:173]
	v_mfma_f32_16x16x32_bf16 v[118:121], v[78:81], v[218:221], v[118:121]
	s_add_u32 m0, s4, 0x10c00
	v_mfma_f32_16x16x32_bf16 v[134:137], v[78:81], v[222:225], v[134:137]
	global_load_lds_dwordx4 v101, s[48:49]
	v_mfma_f32_16x16x32_bf16 v[158:161], v[78:81], v[226:229], v[158:161]
	v_mfma_f32_16x16x32_bf16 v[174:177], v[78:81], v[230:233], v[174:177]
	s_waitcnt lgkmcnt(0)
	s_waitcnt vmcnt(8)
	s_barrier
	ds_read_b128 v[218:221], v102 offset:0
	ds_read_b128 v[222:225], v102 offset:2048
	ds_read_b128 v[226:229], v102 offset:4096
	ds_read_b128 v[230:233], v102 offset:6144
	ds_read_b128 v[66:69], v104 offset:32768
	ds_read_b128 v[70:73], v104 offset:34816
	ds_read_b128 v[74:77], v104 offset:36864
	ds_read_b128 v[78:81], v104 offset:38912
	v_mfma_f32_16x16x32_bf16 v[106:109], v[82:85], v[234:237], v[106:109]
	s_add_u32 m0, s4, 0xc000
	v_mfma_f32_16x16x32_bf16 v[122:125], v[82:85], v[238:241], v[122:125]
	global_load_lds_dwordx4 v98, s[28:29]
	v_mfma_f32_16x16x32_bf16 v[138:141], v[82:85], v[242:245], v[138:141]
	v_mfma_f32_16x16x32_bf16 v[162:165], v[82:85], v[246:249], v[162:165]
	v_mfma_f32_16x16x32_bf16 v[110:113], v[86:89], v[234:237], v[110:113]
	s_add_u32 m0, s4, 0xc400
	v_mfma_f32_16x16x32_bf16 v[126:129], v[86:89], v[238:241], v[126:129]
	global_load_lds_dwordx4 v99, s[28:29]
	v_mfma_f32_16x16x32_bf16 v[142:145], v[86:89], v[242:245], v[142:145]
	v_mfma_f32_16x16x32_bf16 v[166:169], v[86:89], v[246:249], v[166:169]
	v_mfma_f32_16x16x32_bf16 v[114:117], v[90:93], v[234:237], v[114:117]
	s_add_u32 m0, s4, 0xc800
	v_mfma_f32_16x16x32_bf16 v[130:133], v[90:93], v[238:241], v[130:133]
	global_load_lds_dwordx4 v100, s[28:29]
	v_mfma_f32_16x16x32_bf16 v[154:157], v[90:93], v[242:245], v[154:157]
	v_mfma_f32_16x16x32_bf16 v[170:173], v[90:93], v[246:249], v[170:173]
	v_mfma_f32_16x16x32_bf16 v[118:121], v[94:97], v[234:237], v[118:121]
	s_add_u32 m0, s4, 0xcc00
	v_mfma_f32_16x16x32_bf16 v[134:137], v[94:97], v[238:241], v[134:137]
	global_load_lds_dwordx4 v101, s[28:29]
	v_mfma_f32_16x16x32_bf16 v[158:161], v[94:97], v[242:245], v[158:161]
	v_mfma_f32_16x16x32_bf16 v[174:177], v[94:97], v[246:249], v[174:177]
	ds_read_b128 v[234:237], v103 offset:0
	ds_read_b128 v[238:241], v103 offset:2048
	ds_read_b128 v[242:245], v103 offset:4096
	ds_read_b128 v[246:249], v103 offset:6144
	ds_read_b128 v[82:85], v105 offset:32768
	ds_read_b128 v[86:89], v105 offset:34816
	ds_read_b128 v[90:93], v105 offset:36864
	ds_read_b128 v[94:97], v105 offset:38912
	s_waitcnt lgkmcnt(8)
	v_mfma_f32_16x16x32_bf16 v[62:65], v[66:69], v[218:221], v[62:65]
	v_mfma_f32_16x16x32_bf16 v[46:49], v[66:69], v[222:225], v[46:49]
	v_mfma_f32_16x16x32_bf16 v[30:33], v[66:69], v[226:229], v[30:33]
	v_mfma_f32_16x16x32_bf16 v[14:17], v[66:69], v[230:233], v[14:17]
	v_mfma_f32_16x16x32_bf16 v[58:61], v[70:73], v[218:221], v[58:61]
	v_mfma_f32_16x16x32_bf16 v[42:45], v[70:73], v[222:225], v[42:45]
	v_mfma_f32_16x16x32_bf16 v[26:29], v[70:73], v[226:229], v[26:29]
	v_mfma_f32_16x16x32_bf16 v[10:13], v[70:73], v[230:233], v[10:13]
	v_mfma_f32_16x16x32_bf16 v[54:57], v[74:77], v[218:221], v[54:57]
	v_mfma_f32_16x16x32_bf16 v[38:41], v[74:77], v[222:225], v[38:41]
	v_mfma_f32_16x16x32_bf16 v[22:25], v[74:77], v[226:229], v[22:25]
	v_mfma_f32_16x16x32_bf16 v[6:9], v[74:77], v[230:233], v[6:9]
	v_mfma_f32_16x16x32_bf16 v[50:53], v[78:81], v[218:221], v[50:53]
	v_mfma_f32_16x16x32_bf16 v[34:37], v[78:81], v[222:225], v[34:37]
	v_mfma_f32_16x16x32_bf16 v[18:21], v[78:81], v[226:229], v[18:21]
	v_mfma_f32_16x16x32_bf16 v[2:5], v[78:81], v[230:233], v[2:5]
	s_waitcnt lgkmcnt(0)
	s_waitcnt vmcnt(8)
	s_barrier
	ds_read_b128 v[218:221], v102 offset:16384
	ds_read_b128 v[222:225], v102 offset:18432
	ds_read_b128 v[226:229], v102 offset:20480
	ds_read_b128 v[230:233], v102 offset:22528
	v_mfma_f32_16x16x32_bf16 v[62:65], v[82:85], v[234:237], v[62:65]
	s_add_u32 m0, s4, 0x0
	v_mfma_f32_16x16x32_bf16 v[46:49], v[82:85], v[238:241], v[46:49]
	global_load_lds_dwordx4 v98, s[6:7]
	v_mfma_f32_16x16x32_bf16 v[30:33], v[82:85], v[242:245], v[30:33]
	v_mfma_f32_16x16x32_bf16 v[14:17], v[82:85], v[246:249], v[14:17]
	v_mfma_f32_16x16x32_bf16 v[58:61], v[86:89], v[234:237], v[58:61]
	s_add_u32 m0, s4, 0x400
	v_mfma_f32_16x16x32_bf16 v[42:45], v[86:89], v[238:241], v[42:45]
	global_load_lds_dwordx4 v99, s[6:7]
	v_mfma_f32_16x16x32_bf16 v[26:29], v[86:89], v[242:245], v[26:29]
	v_mfma_f32_16x16x32_bf16 v[10:13], v[86:89], v[246:249], v[10:13]
	v_mfma_f32_16x16x32_bf16 v[54:57], v[90:93], v[234:237], v[54:57]
	s_add_u32 m0, s4, 0x800
	v_mfma_f32_16x16x32_bf16 v[38:41], v[90:93], v[238:241], v[38:41]
	global_load_lds_dwordx4 v100, s[6:7]
	v_mfma_f32_16x16x32_bf16 v[22:25], v[90:93], v[242:245], v[22:25]
	v_mfma_f32_16x16x32_bf16 v[6:9], v[90:93], v[246:249], v[6:9]
	v_mfma_f32_16x16x32_bf16 v[50:53], v[94:97], v[234:237], v[50:53]
	s_add_u32 m0, s4, 0xc00
	v_mfma_f32_16x16x32_bf16 v[34:37], v[94:97], v[238:241], v[34:37]
	global_load_lds_dwordx4 v101, s[6:7]
	v_mfma_f32_16x16x32_bf16 v[18:21], v[94:97], v[242:245], v[18:21]
	v_mfma_f32_16x16x32_bf16 v[2:5], v[94:97], v[246:249], v[2:5]
	v_add_u32_e32 v98, 0x80, v98
	v_add_u32_e32 v99, 0x80, v99
	v_add_u32_e32 v100, 0x80, v100
	v_add_u32_e32 v101, 0x80, v101
	ds_read_b128 v[234:237], v103 offset:16384
	ds_read_b128 v[238:241], v103 offset:18432
	ds_read_b128 v[242:245], v103 offset:20480
	ds_read_b128 v[246:249], v103 offset:22528
	s_waitcnt lgkmcnt(4)
	v_mfma_f32_16x16x32_bf16 v[106:109], v[66:69], v[218:221], v[106:109]
	s_add_u32 m0, s4, 0x8000
	v_mfma_f32_16x16x32_bf16 v[122:125], v[66:69], v[222:225], v[122:125]
	global_load_lds_dwordx4 v98, s[48:49]
	v_mfma_f32_16x16x32_bf16 v[138:141], v[66:69], v[226:229], v[138:141]
	v_mfma_f32_16x16x32_bf16 v[162:165], v[66:69], v[230:233], v[162:165]
	v_mfma_f32_16x16x32_bf16 v[110:113], v[70:73], v[218:221], v[110:113]
	s_add_u32 m0, s4, 0x8400
	v_mfma_f32_16x16x32_bf16 v[126:129], v[70:73], v[222:225], v[126:129]
	global_load_lds_dwordx4 v99, s[48:49]
	v_mfma_f32_16x16x32_bf16 v[142:145], v[70:73], v[226:229], v[142:145]
	v_mfma_f32_16x16x32_bf16 v[166:169], v[70:73], v[230:233], v[166:169]
	v_mfma_f32_16x16x32_bf16 v[114:117], v[74:77], v[218:221], v[114:117]
	s_add_u32 m0, s4, 0x8800
	v_mfma_f32_16x16x32_bf16 v[130:133], v[74:77], v[222:225], v[130:133]
	global_load_lds_dwordx4 v100, s[48:49]
	v_mfma_f32_16x16x32_bf16 v[154:157], v[74:77], v[226:229], v[154:157]
	v_mfma_f32_16x16x32_bf16 v[170:173], v[74:77], v[230:233], v[170:173]
	v_mfma_f32_16x16x32_bf16 v[118:121], v[78:81], v[218:221], v[118:121]
	s_add_u32 m0, s4, 0x8c00
	v_mfma_f32_16x16x32_bf16 v[134:137], v[78:81], v[222:225], v[134:137]
	global_load_lds_dwordx4 v101, s[48:49]
	v_mfma_f32_16x16x32_bf16 v[158:161], v[78:81], v[226:229], v[158:161]
	v_mfma_f32_16x16x32_bf16 v[174:177], v[78:81], v[230:233], v[174:177]
	s_waitcnt lgkmcnt(0)
	s_waitcnt vmcnt(8)
	s_barrier
	ds_read_b128 v[218:221], v102 offset:49152
	ds_read_b128 v[222:225], v102 offset:51200
	ds_read_b128 v[226:229], v102 offset:53248
	ds_read_b128 v[230:233], v102 offset:55296
	ds_read_b128 v[66:69], v250 offset:49152
	ds_read_b128 v[70:73], v250 offset:51200
	ds_read_b128 v[74:77], v250 offset:53248
	ds_read_b128 v[78:81], v250 offset:55296
	v_mfma_f32_16x16x32_bf16 v[106:109], v[82:85], v[234:237], v[106:109]
	s_add_u32 m0, s4, 0x4000
	v_mfma_f32_16x16x32_bf16 v[122:125], v[82:85], v[238:241], v[122:125]
	global_load_lds_dwordx4 v98, s[28:29]
	v_mfma_f32_16x16x32_bf16 v[138:141], v[82:85], v[242:245], v[138:141]
	v_mfma_f32_16x16x32_bf16 v[162:165], v[82:85], v[246:249], v[162:165]
	v_mfma_f32_16x16x32_bf16 v[110:113], v[86:89], v[234:237], v[110:113]
	s_add_u32 m0, s4, 0x4400
	v_mfma_f32_16x16x32_bf16 v[126:129], v[86:89], v[238:241], v[126:129]
	global_load_lds_dwordx4 v99, s[28:29]
	v_mfma_f32_16x16x32_bf16 v[142:145], v[86:89], v[242:245], v[142:145]
	v_mfma_f32_16x16x32_bf16 v[166:169], v[86:89], v[246:249], v[166:169]
	v_mfma_f32_16x16x32_bf16 v[114:117], v[90:93], v[234:237], v[114:117]
	s_add_u32 m0, s4, 0x4800
	v_mfma_f32_16x16x32_bf16 v[130:133], v[90:93], v[238:241], v[130:133]
	global_load_lds_dwordx4 v100, s[28:29]
	v_mfma_f32_16x16x32_bf16 v[154:157], v[90:93], v[242:245], v[154:157]
	v_mfma_f32_16x16x32_bf16 v[170:173], v[90:93], v[246:249], v[170:173]
	v_mfma_f32_16x16x32_bf16 v[118:121], v[94:97], v[234:237], v[118:121]
	s_add_u32 m0, s4, 0x4c00
	v_mfma_f32_16x16x32_bf16 v[134:137], v[94:97], v[238:241], v[134:137]
	global_load_lds_dwordx4 v101, s[28:29]
	v_mfma_f32_16x16x32_bf16 v[158:161], v[94:97], v[242:245], v[158:161]
	v_mfma_f32_16x16x32_bf16 v[174:177], v[94:97], v[246:249], v[174:177]
	ds_read_b128 v[234:237], v103 offset:49152
	ds_read_b128 v[238:241], v103 offset:51200
	ds_read_b128 v[242:245], v103 offset:53248
	ds_read_b128 v[246:249], v103 offset:55296
	ds_read_b128 v[82:85], v251 offset:49152
	ds_read_b128 v[86:89], v251 offset:51200
	ds_read_b128 v[90:93], v251 offset:53248
	ds_read_b128 v[94:97], v251 offset:55296
	s_waitcnt lgkmcnt(8)
	v_mfma_f32_16x16x32_bf16 v[62:65], v[66:69], v[218:221], v[62:65]
	v_mfma_f32_16x16x32_bf16 v[46:49], v[66:69], v[222:225], v[46:49]
	v_mfma_f32_16x16x32_bf16 v[30:33], v[66:69], v[226:229], v[30:33]
	v_mfma_f32_16x16x32_bf16 v[14:17], v[66:69], v[230:233], v[14:17]
	v_mfma_f32_16x16x32_bf16 v[58:61], v[70:73], v[218:221], v[58:61]
	v_mfma_f32_16x16x32_bf16 v[42:45], v[70:73], v[222:225], v[42:45]
	v_mfma_f32_16x16x32_bf16 v[26:29], v[70:73], v[226:229], v[26:29]
	v_mfma_f32_16x16x32_bf16 v[10:13], v[70:73], v[230:233], v[10:13]
	v_mfma_f32_16x16x32_bf16 v[54:57], v[74:77], v[218:221], v[54:57]
	v_mfma_f32_16x16x32_bf16 v[38:41], v[74:77], v[222:225], v[38:41]
	v_mfma_f32_16x16x32_bf16 v[22:25], v[74:77], v[226:229], v[22:25]
	v_mfma_f32_16x16x32_bf16 v[6:9], v[74:77], v[230:233], v[6:9]
	v_mfma_f32_16x16x32_bf16 v[50:53], v[78:81], v[218:221], v[50:53]
	v_mfma_f32_16x16x32_bf16 v[34:37], v[78:81], v[222:225], v[34:37]
	v_mfma_f32_16x16x32_bf16 v[18:21], v[78:81], v[226:229], v[18:21]
	v_mfma_f32_16x16x32_bf16 v[2:5], v[78:81], v[230:233], v[2:5]
	s_waitcnt lgkmcnt(0)
	s_waitcnt vmcnt(8)
	s_barrier
	ds_read_b128 v[218:221], v102 offset:0
	ds_read_b128 v[222:225], v102 offset:2048
	ds_read_b128 v[226:229], v102 offset:4096
	ds_read_b128 v[230:233], v102 offset:6144
	v_mfma_f32_16x16x32_bf16 v[62:65], v[82:85], v[234:237], v[62:65]
	s_add_u32 m0, s4, 0xc000
	v_mfma_f32_16x16x32_bf16 v[46:49], v[82:85], v[238:241], v[46:49]
	global_load_lds_dwordx4 v98, s[6:7]
	v_mfma_f32_16x16x32_bf16 v[30:33], v[82:85], v[242:245], v[30:33]
	v_mfma_f32_16x16x32_bf16 v[14:17], v[82:85], v[246:249], v[14:17]
	v_mfma_f32_16x16x32_bf16 v[58:61], v[86:89], v[234:237], v[58:61]
	s_add_u32 m0, s4, 0xc400
	v_mfma_f32_16x16x32_bf16 v[42:45], v[86:89], v[238:241], v[42:45]
	global_load_lds_dwordx4 v99, s[6:7]
	v_mfma_f32_16x16x32_bf16 v[26:29], v[86:89], v[242:245], v[26:29]
	v_mfma_f32_16x16x32_bf16 v[10:13], v[86:89], v[246:249], v[10:13]
	v_mfma_f32_16x16x32_bf16 v[54:57], v[90:93], v[234:237], v[54:57]
	s_add_u32 m0, s4, 0xc800
	v_mfma_f32_16x16x32_bf16 v[38:41], v[90:93], v[238:241], v[38:41]
	global_load_lds_dwordx4 v100, s[6:7]
	v_mfma_f32_16x16x32_bf16 v[22:25], v[90:93], v[242:245], v[22:25]
	v_mfma_f32_16x16x32_bf16 v[6:9], v[90:93], v[246:249], v[6:9]
	v_mfma_f32_16x16x32_bf16 v[50:53], v[94:97], v[234:237], v[50:53]
	s_add_u32 m0, s4, 0xcc00
	v_mfma_f32_16x16x32_bf16 v[34:37], v[94:97], v[238:241], v[34:37]
	global_load_lds_dwordx4 v101, s[6:7]
	v_mfma_f32_16x16x32_bf16 v[18:21], v[94:97], v[242:245], v[18:21]
	v_mfma_f32_16x16x32_bf16 v[2:5], v[94:97], v[246:249], v[2:5]
	v_add_u32_e32 v98, 0x80, v98
	v_add_u32_e32 v99, 0x80, v99
	v_add_u32_e32 v100, 0x80, v100
	v_add_u32_e32 v101, 0x80, v101
	ds_read_b128 v[234:237], v103 offset:0
	ds_read_b128 v[238:241], v103 offset:2048
	ds_read_b128 v[242:245], v103 offset:4096
	ds_read_b128 v[246:249], v103 offset:6144
	s_waitcnt lgkmcnt(4)
	v_mfma_f32_16x16x32_bf16 v[106:109], v[66:69], v[218:221], v[106:109]
	s_add_u32 m0, s4, 0x10000
	v_mfma_f32_16x16x32_bf16 v[122:125], v[66:69], v[222:225], v[122:125]
	global_load_lds_dwordx4 v98, s[48:49]
	v_mfma_f32_16x16x32_bf16 v[138:141], v[66:69], v[226:229], v[138:141]
	v_mfma_f32_16x16x32_bf16 v[162:165], v[66:69], v[230:233], v[162:165]
	v_mfma_f32_16x16x32_bf16 v[110:113], v[70:73], v[218:221], v[110:113]
	s_add_u32 m0, s4, 0x10400
	v_mfma_f32_16x16x32_bf16 v[126:129], v[70:73], v[222:225], v[126:129]
	global_load_lds_dwordx4 v99, s[48:49]
	v_mfma_f32_16x16x32_bf16 v[142:145], v[70:73], v[226:229], v[142:145]
	v_mfma_f32_16x16x32_bf16 v[166:169], v[70:73], v[230:233], v[166:169]
	v_mfma_f32_16x16x32_bf16 v[114:117], v[74:77], v[218:221], v[114:117]
	s_add_u32 m0, s4, 0x10800
	v_mfma_f32_16x16x32_bf16 v[130:133], v[74:77], v[222:225], v[130:133]
	global_load_lds_dwordx4 v100, s[48:49]
	v_mfma_f32_16x16x32_bf16 v[154:157], v[74:77], v[226:229], v[154:157]
	v_mfma_f32_16x16x32_bf16 v[170:173], v[74:77], v[230:233], v[170:173]
	v_mfma_f32_16x16x32_bf16 v[118:121], v[78:81], v[218:221], v[118:121]
	s_add_u32 m0, s4, 0x10c00
	v_mfma_f32_16x16x32_bf16 v[134:137], v[78:81], v[222:225], v[134:137]
	global_load_lds_dwordx4 v101, s[48:49]
	v_mfma_f32_16x16x32_bf16 v[158:161], v[78:81], v[226:229], v[158:161]
	v_mfma_f32_16x16x32_bf16 v[174:177], v[78:81], v[230:233], v[174:177]
	s_waitcnt lgkmcnt(0)
	s_waitcnt vmcnt(8)
	s_barrier
	ds_read_b128 v[218:221], v102 offset:16384
	ds_read_b128 v[222:225], v102 offset:18432
	ds_read_b128 v[226:229], v102 offset:20480
	ds_read_b128 v[230:233], v102 offset:22528
	ds_read_b128 v[66:69], v104 offset:32768
	ds_read_b128 v[70:73], v104 offset:34816
	ds_read_b128 v[74:77], v104 offset:36864
	ds_read_b128 v[78:81], v104 offset:38912
	v_mfma_f32_16x16x32_bf16 v[106:109], v[82:85], v[234:237], v[106:109]
	s_add_u32 m0, s4, 0x0
	v_mfma_f32_16x16x32_bf16 v[122:125], v[82:85], v[238:241], v[122:125]
	global_load_lds_dwordx4 v98, s[28:29]
	v_mfma_f32_16x16x32_bf16 v[138:141], v[82:85], v[242:245], v[138:141]
	v_mfma_f32_16x16x32_bf16 v[162:165], v[82:85], v[246:249], v[162:165]
	v_mfma_f32_16x16x32_bf16 v[110:113], v[86:89], v[234:237], v[110:113]
	s_add_u32 m0, s4, 0x400
	v_mfma_f32_16x16x32_bf16 v[126:129], v[86:89], v[238:241], v[126:129]
	global_load_lds_dwordx4 v99, s[28:29]
	v_mfma_f32_16x16x32_bf16 v[142:145], v[86:89], v[242:245], v[142:145]
	v_mfma_f32_16x16x32_bf16 v[166:169], v[86:89], v[246:249], v[166:169]
	v_mfma_f32_16x16x32_bf16 v[114:117], v[90:93], v[234:237], v[114:117]
	s_add_u32 m0, s4, 0x800
	v_mfma_f32_16x16x32_bf16 v[130:133], v[90:93], v[238:241], v[130:133]
	global_load_lds_dwordx4 v100, s[28:29]
	v_mfma_f32_16x16x32_bf16 v[154:157], v[90:93], v[242:245], v[154:157]
	v_mfma_f32_16x16x32_bf16 v[170:173], v[90:93], v[246:249], v[170:173]
	v_mfma_f32_16x16x32_bf16 v[118:121], v[94:97], v[234:237], v[118:121]
	s_add_u32 m0, s4, 0xc00
	v_mfma_f32_16x16x32_bf16 v[134:137], v[94:97], v[238:241], v[134:137]
	global_load_lds_dwordx4 v101, s[28:29]
	v_mfma_f32_16x16x32_bf16 v[158:161], v[94:97], v[242:245], v[158:161]
	v_mfma_f32_16x16x32_bf16 v[174:177], v[94:97], v[246:249], v[174:177]
	ds_read_b128 v[234:237], v103 offset:16384
	ds_read_b128 v[238:241], v103 offset:18432
	ds_read_b128 v[242:245], v103 offset:20480
	ds_read_b128 v[246:249], v103 offset:22528
	ds_read_b128 v[82:85], v105 offset:32768
	ds_read_b128 v[86:89], v105 offset:34816
	ds_read_b128 v[90:93], v105 offset:36864
	ds_read_b128 v[94:97], v105 offset:38912
	s_waitcnt lgkmcnt(8)
	v_mfma_f32_16x16x32_bf16 v[62:65], v[66:69], v[218:221], v[62:65]
	v_mfma_f32_16x16x32_bf16 v[46:49], v[66:69], v[222:225], v[46:49]
	v_mfma_f32_16x16x32_bf16 v[30:33], v[66:69], v[226:229], v[30:33]
	v_mfma_f32_16x16x32_bf16 v[14:17], v[66:69], v[230:233], v[14:17]
	v_mfma_f32_16x16x32_bf16 v[58:61], v[70:73], v[218:221], v[58:61]
	v_mfma_f32_16x16x32_bf16 v[42:45], v[70:73], v[222:225], v[42:45]
	v_mfma_f32_16x16x32_bf16 v[26:29], v[70:73], v[226:229], v[26:29]
	v_mfma_f32_16x16x32_bf16 v[10:13], v[70:73], v[230:233], v[10:13]
	v_mfma_f32_16x16x32_bf16 v[54:57], v[74:77], v[218:221], v[54:57]
	v_mfma_f32_16x16x32_bf16 v[38:41], v[74:77], v[222:225], v[38:41]
	v_mfma_f32_16x16x32_bf16 v[22:25], v[74:77], v[226:229], v[22:25]
	v_mfma_f32_16x16x32_bf16 v[6:9], v[74:77], v[230:233], v[6:9]
	v_mfma_f32_16x16x32_bf16 v[50:53], v[78:81], v[218:221], v[50:53]
	v_mfma_f32_16x16x32_bf16 v[34:37], v[78:81], v[222:225], v[34:37]
	v_mfma_f32_16x16x32_bf16 v[18:21], v[78:81], v[226:229], v[18:21]
	v_mfma_f32_16x16x32_bf16 v[2:5], v[78:81], v[230:233], v[2:5]
	s_waitcnt lgkmcnt(0)
	s_waitcnt vmcnt(8)
	s_barrier
	ds_read_b128 v[218:221], v102 offset:49152
	ds_read_b128 v[222:225], v102 offset:51200
	ds_read_b128 v[226:229], v102 offset:53248
	ds_read_b128 v[230:233], v102 offset:55296
	v_mfma_f32_16x16x32_bf16 v[62:65], v[82:85], v[234:237], v[62:65]
	s_add_u32 m0, s4, 0x4000
	v_mfma_f32_16x16x32_bf16 v[46:49], v[82:85], v[238:241], v[46:49]
	global_load_lds_dwordx4 v98, s[6:7]
	v_mfma_f32_16x16x32_bf16 v[30:33], v[82:85], v[242:245], v[30:33]
	v_mfma_f32_16x16x32_bf16 v[14:17], v[82:85], v[246:249], v[14:17]
	v_mfma_f32_16x16x32_bf16 v[58:61], v[86:89], v[234:237], v[58:61]
	s_add_u32 m0, s4, 0x4400
	v_mfma_f32_16x16x32_bf16 v[42:45], v[86:89], v[238:241], v[42:45]
	global_load_lds_dwordx4 v99, s[6:7]
	v_mfma_f32_16x16x32_bf16 v[26:29], v[86:89], v[242:245], v[26:29]
	v_mfma_f32_16x16x32_bf16 v[10:13], v[86:89], v[246:249], v[10:13]
	v_mfma_f32_16x16x32_bf16 v[54:57], v[90:93], v[234:237], v[54:57]
	s_add_u32 m0, s4, 0x4800
	v_mfma_f32_16x16x32_bf16 v[38:41], v[90:93], v[238:241], v[38:41]
	global_load_lds_dwordx4 v100, s[6:7]
	v_mfma_f32_16x16x32_bf16 v[22:25], v[90:93], v[242:245], v[22:25]
	v_mfma_f32_16x16x32_bf16 v[6:9], v[90:93], v[246:249], v[6:9]
	v_mfma_f32_16x16x32_bf16 v[50:53], v[94:97], v[234:237], v[50:53]
	s_add_u32 m0, s4, 0x4c00
	v_mfma_f32_16x16x32_bf16 v[34:37], v[94:97], v[238:241], v[34:37]
	global_load_lds_dwordx4 v101, s[6:7]
	v_mfma_f32_16x16x32_bf16 v[18:21], v[94:97], v[242:245], v[18:21]
	v_mfma_f32_16x16x32_bf16 v[2:5], v[94:97], v[246:249], v[2:5]
	v_add_u32_e32 v98, 0x80, v98
	v_add_u32_e32 v99, 0x80, v99
	v_add_u32_e32 v100, 0x80, v100
	v_add_u32_e32 v101, 0x80, v101
	ds_read_b128 v[234:237], v103 offset:49152
	ds_read_b128 v[238:241], v103 offset:51200
	ds_read_b128 v[242:245], v103 offset:53248
	ds_read_b128 v[246:249], v103 offset:55296
	s_waitcnt lgkmcnt(4)
	v_mfma_f32_16x16x32_bf16 v[106:109], v[66:69], v[218:221], v[106:109]
	s_add_u32 m0, s4, 0x8000
	v_mfma_f32_16x16x32_bf16 v[122:125], v[66:69], v[222:225], v[122:125]
	global_load_lds_dwordx4 v98, s[48:49]
	v_mfma_f32_16x16x32_bf16 v[138:141], v[66:69], v[226:229], v[138:141]
	v_mfma_f32_16x16x32_bf16 v[162:165], v[66:69], v[230:233], v[162:165]
	v_mfma_f32_16x16x32_bf16 v[110:113], v[70:73], v[218:221], v[110:113]
	s_add_u32 m0, s4, 0x8400
	v_mfma_f32_16x16x32_bf16 v[126:129], v[70:73], v[222:225], v[126:129]
	global_load_lds_dwordx4 v99, s[48:49]
	v_mfma_f32_16x16x32_bf16 v[142:145], v[70:73], v[226:229], v[142:145]
	v_mfma_f32_16x16x32_bf16 v[166:169], v[70:73], v[230:233], v[166:169]
	v_mfma_f32_16x16x32_bf16 v[114:117], v[74:77], v[218:221], v[114:117]
	s_add_u32 m0, s4, 0x8800
	v_mfma_f32_16x16x32_bf16 v[130:133], v[74:77], v[222:225], v[130:133]
	global_load_lds_dwordx4 v100, s[48:49]
	v_mfma_f32_16x16x32_bf16 v[154:157], v[74:77], v[226:229], v[154:157]
	v_mfma_f32_16x16x32_bf16 v[170:173], v[74:77], v[230:233], v[170:173]
	v_mfma_f32_16x16x32_bf16 v[118:121], v[78:81], v[218:221], v[118:121]
	s_add_u32 m0, s4, 0x8c00
	v_mfma_f32_16x16x32_bf16 v[134:137], v[78:81], v[222:225], v[134:137]
	global_load_lds_dwordx4 v101, s[48:49]
	v_mfma_f32_16x16x32_bf16 v[158:161], v[78:81], v[226:229], v[158:161]
	v_mfma_f32_16x16x32_bf16 v[174:177], v[78:81], v[230:233], v[174:177]
	s_waitcnt lgkmcnt(0)
	s_waitcnt vmcnt(8)
	s_barrier
	ds_read_b128 v[218:221], v102 offset:0
	ds_read_b128 v[222:225], v102 offset:2048
	ds_read_b128 v[226:229], v102 offset:4096
	ds_read_b128 v[230:233], v102 offset:6144
	ds_read_b128 v[66:69], v250 offset:49152
	ds_read_b128 v[70:73], v250 offset:51200
	ds_read_b128 v[74:77], v250 offset:53248
	ds_read_b128 v[78:81], v250 offset:55296
	v_mfma_f32_16x16x32_bf16 v[106:109], v[82:85], v[234:237], v[106:109]
	s_add_u32 m0, s4, 0xc000
	v_mfma_f32_16x16x32_bf16 v[122:125], v[82:85], v[238:241], v[122:125]
	global_load_lds_dwordx4 v98, s[28:29]
	v_mfma_f32_16x16x32_bf16 v[138:141], v[82:85], v[242:245], v[138:141]
	v_mfma_f32_16x16x32_bf16 v[162:165], v[82:85], v[246:249], v[162:165]
	v_mfma_f32_16x16x32_bf16 v[110:113], v[86:89], v[234:237], v[110:113]
	s_add_u32 m0, s4, 0xc400
	v_mfma_f32_16x16x32_bf16 v[126:129], v[86:89], v[238:241], v[126:129]
	global_load_lds_dwordx4 v99, s[28:29]
	v_mfma_f32_16x16x32_bf16 v[142:145], v[86:89], v[242:245], v[142:145]
	v_mfma_f32_16x16x32_bf16 v[166:169], v[86:89], v[246:249], v[166:169]
	v_mfma_f32_16x16x32_bf16 v[114:117], v[90:93], v[234:237], v[114:117]
	s_add_u32 m0, s4, 0xc800
	v_mfma_f32_16x16x32_bf16 v[130:133], v[90:93], v[238:241], v[130:133]
	global_load_lds_dwordx4 v100, s[28:29]
	v_mfma_f32_16x16x32_bf16 v[154:157], v[90:93], v[242:245], v[154:157]
	v_mfma_f32_16x16x32_bf16 v[170:173], v[90:93], v[246:249], v[170:173]
	v_mfma_f32_16x16x32_bf16 v[118:121], v[94:97], v[234:237], v[118:121]
	s_add_u32 m0, s4, 0xcc00
	v_mfma_f32_16x16x32_bf16 v[134:137], v[94:97], v[238:241], v[134:137]
	global_load_lds_dwordx4 v101, s[28:29]
	v_mfma_f32_16x16x32_bf16 v[158:161], v[94:97], v[242:245], v[158:161]
	v_mfma_f32_16x16x32_bf16 v[174:177], v[94:97], v[246:249], v[174:177]
	ds_read_b128 v[234:237], v103 offset:0
	ds_read_b128 v[238:241], v103 offset:2048
	ds_read_b128 v[242:245], v103 offset:4096
	ds_read_b128 v[246:249], v103 offset:6144
	ds_read_b128 v[82:85], v251 offset:49152
	ds_read_b128 v[86:89], v251 offset:51200
	ds_read_b128 v[90:93], v251 offset:53248
	ds_read_b128 v[94:97], v251 offset:55296
	s_waitcnt lgkmcnt(8)
	v_mfma_f32_16x16x32_bf16 v[62:65], v[66:69], v[218:221], v[62:65]
	v_mfma_f32_16x16x32_bf16 v[46:49], v[66:69], v[222:225], v[46:49]
	v_mfma_f32_16x16x32_bf16 v[30:33], v[66:69], v[226:229], v[30:33]
	v_mfma_f32_16x16x32_bf16 v[14:17], v[66:69], v[230:233], v[14:17]
	v_mfma_f32_16x16x32_bf16 v[58:61], v[70:73], v[218:221], v[58:61]
	v_mfma_f32_16x16x32_bf16 v[42:45], v[70:73], v[222:225], v[42:45]
	v_mfma_f32_16x16x32_bf16 v[26:29], v[70:73], v[226:229], v[26:29]
	v_mfma_f32_16x16x32_bf16 v[10:13], v[70:73], v[230:233], v[10:13]
	v_mfma_f32_16x16x32_bf16 v[54:57], v[74:77], v[218:221], v[54:57]
	v_mfma_f32_16x16x32_bf16 v[38:41], v[74:77], v[222:225], v[38:41]
	v_mfma_f32_16x16x32_bf16 v[22:25], v[74:77], v[226:229], v[22:25]
	v_mfma_f32_16x16x32_bf16 v[6:9], v[74:77], v[230:233], v[6:9]
	v_mfma_f32_16x16x32_bf16 v[50:53], v[78:81], v[218:221], v[50:53]
	v_mfma_f32_16x16x32_bf16 v[34:37], v[78:81], v[222:225], v[34:37]
	v_mfma_f32_16x16x32_bf16 v[18:21], v[78:81], v[226:229], v[18:21]
	v_mfma_f32_16x16x32_bf16 v[2:5], v[78:81], v[230:233], v[2:5]
	s_waitcnt lgkmcnt(0)
	s_waitcnt vmcnt(8)
	s_barrier
	ds_read_b128 v[218:221], v102 offset:16384
	ds_read_b128 v[222:225], v102 offset:18432
	ds_read_b128 v[226:229], v102 offset:20480
	ds_read_b128 v[230:233], v102 offset:22528
	v_mfma_f32_16x16x32_bf16 v[62:65], v[82:85], v[234:237], v[62:65]
	s_add_u32 m0, s4, 0x0
	v_mfma_f32_16x16x32_bf16 v[46:49], v[82:85], v[238:241], v[46:49]
	global_load_lds_dwordx4 v98, s[6:7]
	v_mfma_f32_16x16x32_bf16 v[30:33], v[82:85], v[242:245], v[30:33]
	v_mfma_f32_16x16x32_bf16 v[14:17], v[82:85], v[246:249], v[14:17]
	v_mfma_f32_16x16x32_bf16 v[58:61], v[86:89], v[234:237], v[58:61]
	s_add_u32 m0, s4, 0x400
	v_mfma_f32_16x16x32_bf16 v[42:45], v[86:89], v[238:241], v[42:45]
	global_load_lds_dwordx4 v99, s[6:7]
	v_mfma_f32_16x16x32_bf16 v[26:29], v[86:89], v[242:245], v[26:29]
	v_mfma_f32_16x16x32_bf16 v[10:13], v[86:89], v[246:249], v[10:13]
	v_mfma_f32_16x16x32_bf16 v[54:57], v[90:93], v[234:237], v[54:57]
	s_add_u32 m0, s4, 0x800
	v_mfma_f32_16x16x32_bf16 v[38:41], v[90:93], v[238:241], v[38:41]
	global_load_lds_dwordx4 v100, s[6:7]
	v_mfma_f32_16x16x32_bf16 v[22:25], v[90:93], v[242:245], v[22:25]
	v_mfma_f32_16x16x32_bf16 v[6:9], v[90:93], v[246:249], v[6:9]
	v_mfma_f32_16x16x32_bf16 v[50:53], v[94:97], v[234:237], v[50:53]
	s_add_u32 m0, s4, 0xc00
	v_mfma_f32_16x16x32_bf16 v[34:37], v[94:97], v[238:241], v[34:37]
	global_load_lds_dwordx4 v101, s[6:7]
	v_mfma_f32_16x16x32_bf16 v[18:21], v[94:97], v[242:245], v[18:21]
	v_mfma_f32_16x16x32_bf16 v[2:5], v[94:97], v[246:249], v[2:5]
	v_add_u32_e32 v98, 0x80, v98
	v_add_u32_e32 v99, 0x80, v99
	v_add_u32_e32 v100, 0x80, v100
	v_add_u32_e32 v101, 0x80, v101
	ds_read_b128 v[234:237], v103 offset:16384
	ds_read_b128 v[238:241], v103 offset:18432
	ds_read_b128 v[242:245], v103 offset:20480
	ds_read_b128 v[246:249], v103 offset:22528
	s_waitcnt lgkmcnt(4)
	v_mfma_f32_16x16x32_bf16 v[106:109], v[66:69], v[218:221], v[106:109]
	s_add_u32 m0, s4, 0x10000
	v_mfma_f32_16x16x32_bf16 v[122:125], v[66:69], v[222:225], v[122:125]
	global_load_lds_dwordx4 v98, s[48:49]
	v_mfma_f32_16x16x32_bf16 v[138:141], v[66:69], v[226:229], v[138:141]
	v_mfma_f32_16x16x32_bf16 v[162:165], v[66:69], v[230:233], v[162:165]
	v_mfma_f32_16x16x32_bf16 v[110:113], v[70:73], v[218:221], v[110:113]
	s_add_u32 m0, s4, 0x10400
	v_mfma_f32_16x16x32_bf16 v[126:129], v[70:73], v[222:225], v[126:129]
	global_load_lds_dwordx4 v99, s[48:49]
	v_mfma_f32_16x16x32_bf16 v[142:145], v[70:73], v[226:229], v[142:145]
	v_mfma_f32_16x16x32_bf16 v[166:169], v[70:73], v[230:233], v[166:169]
	v_mfma_f32_16x16x32_bf16 v[114:117], v[74:77], v[218:221], v[114:117]
	s_add_u32 m0, s4, 0x10800
	v_mfma_f32_16x16x32_bf16 v[130:133], v[74:77], v[222:225], v[130:133]
	global_load_lds_dwordx4 v100, s[48:49]
	v_mfma_f32_16x16x32_bf16 v[154:157], v[74:77], v[226:229], v[154:157]
	v_mfma_f32_16x16x32_bf16 v[170:173], v[74:77], v[230:233], v[170:173]
	v_mfma_f32_16x16x32_bf16 v[118:121], v[78:81], v[218:221], v[118:121]
	s_add_u32 m0, s4, 0x10c00
	v_mfma_f32_16x16x32_bf16 v[134:137], v[78:81], v[222:225], v[134:137]
	global_load_lds_dwordx4 v101, s[48:49]
	v_mfma_f32_16x16x32_bf16 v[158:161], v[78:81], v[226:229], v[158:161]
	v_mfma_f32_16x16x32_bf16 v[174:177], v[78:81], v[230:233], v[174:177]
	s_waitcnt lgkmcnt(0)
	s_waitcnt vmcnt(8)
	s_barrier
	ds_read_b128 v[218:221], v102 offset:49152
	ds_read_b128 v[222:225], v102 offset:51200
	ds_read_b128 v[226:229], v102 offset:53248
	ds_read_b128 v[230:233], v102 offset:55296
	ds_read_b128 v[66:69], v104 offset:32768
	ds_read_b128 v[70:73], v104 offset:34816
	ds_read_b128 v[74:77], v104 offset:36864
	ds_read_b128 v[78:81], v104 offset:38912
	v_mfma_f32_16x16x32_bf16 v[106:109], v[82:85], v[234:237], v[106:109]
	s_add_u32 m0, s4, 0x4000
	v_mfma_f32_16x16x32_bf16 v[122:125], v[82:85], v[238:241], v[122:125]
	global_load_lds_dwordx4 v98, s[28:29]
	v_mfma_f32_16x16x32_bf16 v[138:141], v[82:85], v[242:245], v[138:141]
	v_mfma_f32_16x16x32_bf16 v[162:165], v[82:85], v[246:249], v[162:165]
	v_mfma_f32_16x16x32_bf16 v[110:113], v[86:89], v[234:237], v[110:113]
	s_add_u32 m0, s4, 0x4400
	v_mfma_f32_16x16x32_bf16 v[126:129], v[86:89], v[238:241], v[126:129]
	global_load_lds_dwordx4 v99, s[28:29]
	v_mfma_f32_16x16x32_bf16 v[142:145], v[86:89], v[242:245], v[142:145]
	v_mfma_f32_16x16x32_bf16 v[166:169], v[86:89], v[246:249], v[166:169]
	v_mfma_f32_16x16x32_bf16 v[114:117], v[90:93], v[234:237], v[114:117]
	s_add_u32 m0, s4, 0x4800
	v_mfma_f32_16x16x32_bf16 v[130:133], v[90:93], v[238:241], v[130:133]
	global_load_lds_dwordx4 v100, s[28:29]
	v_mfma_f32_16x16x32_bf16 v[154:157], v[90:93], v[242:245], v[154:157]
	v_mfma_f32_16x16x32_bf16 v[170:173], v[90:93], v[246:249], v[170:173]
	v_mfma_f32_16x16x32_bf16 v[118:121], v[94:97], v[234:237], v[118:121]
	s_add_u32 m0, s4, 0x4c00
	v_mfma_f32_16x16x32_bf16 v[134:137], v[94:97], v[238:241], v[134:137]
	global_load_lds_dwordx4 v101, s[28:29]
	v_mfma_f32_16x16x32_bf16 v[158:161], v[94:97], v[242:245], v[158:161]
	v_mfma_f32_16x16x32_bf16 v[174:177], v[94:97], v[246:249], v[174:177]
	ds_read_b128 v[234:237], v103 offset:49152
	ds_read_b128 v[238:241], v103 offset:51200
	ds_read_b128 v[242:245], v103 offset:53248
	ds_read_b128 v[246:249], v103 offset:55296
	ds_read_b128 v[82:85], v105 offset:32768
	ds_read_b128 v[86:89], v105 offset:34816
	ds_read_b128 v[90:93], v105 offset:36864
	ds_read_b128 v[94:97], v105 offset:38912
	s_waitcnt lgkmcnt(8)
	v_mfma_f32_16x16x32_bf16 v[62:65], v[66:69], v[218:221], v[62:65]
	v_mfma_f32_16x16x32_bf16 v[46:49], v[66:69], v[222:225], v[46:49]
	v_mfma_f32_16x16x32_bf16 v[30:33], v[66:69], v[226:229], v[30:33]
	v_mfma_f32_16x16x32_bf16 v[14:17], v[66:69], v[230:233], v[14:17]
	v_mfma_f32_16x16x32_bf16 v[58:61], v[70:73], v[218:221], v[58:61]
	v_mfma_f32_16x16x32_bf16 v[42:45], v[70:73], v[222:225], v[42:45]
	v_mfma_f32_16x16x32_bf16 v[26:29], v[70:73], v[226:229], v[26:29]
	v_mfma_f32_16x16x32_bf16 v[10:13], v[70:73], v[230:233], v[10:13]
	v_mfma_f32_16x16x32_bf16 v[54:57], v[74:77], v[218:221], v[54:57]
	v_mfma_f32_16x16x32_bf16 v[38:41], v[74:77], v[222:225], v[38:41]
	v_mfma_f32_16x16x32_bf16 v[22:25], v[74:77], v[226:229], v[22:25]
	v_mfma_f32_16x16x32_bf16 v[6:9], v[74:77], v[230:233], v[6:9]
	v_mfma_f32_16x16x32_bf16 v[50:53], v[78:81], v[218:221], v[50:53]
	v_mfma_f32_16x16x32_bf16 v[34:37], v[78:81], v[222:225], v[34:37]
	v_mfma_f32_16x16x32_bf16 v[18:21], v[78:81], v[226:229], v[18:21]
	v_mfma_f32_16x16x32_bf16 v[2:5], v[78:81], v[230:233], v[2:5]
	s_waitcnt lgkmcnt(0)
	s_waitcnt vmcnt(8)
	s_barrier
	ds_read_b128 v[218:221], v102 offset:0
	ds_read_b128 v[222:225], v102 offset:2048
	ds_read_b128 v[226:229], v102 offset:4096
	ds_read_b128 v[230:233], v102 offset:6144
	v_mfma_f32_16x16x32_bf16 v[62:65], v[82:85], v[234:237], v[62:65]
	s_add_u32 m0, s4, 0xc000
	v_mfma_f32_16x16x32_bf16 v[46:49], v[82:85], v[238:241], v[46:49]
	global_load_lds_dwordx4 v98, s[6:7]
	v_mfma_f32_16x16x32_bf16 v[30:33], v[82:85], v[242:245], v[30:33]
	v_mfma_f32_16x16x32_bf16 v[14:17], v[82:85], v[246:249], v[14:17]
	v_mfma_f32_16x16x32_bf16 v[58:61], v[86:89], v[234:237], v[58:61]
	s_add_u32 m0, s4, 0xc400
	v_mfma_f32_16x16x32_bf16 v[42:45], v[86:89], v[238:241], v[42:45]
	global_load_lds_dwordx4 v99, s[6:7]
	v_mfma_f32_16x16x32_bf16 v[26:29], v[86:89], v[242:245], v[26:29]
	v_mfma_f32_16x16x32_bf16 v[10:13], v[86:89], v[246:249], v[10:13]
	v_mfma_f32_16x16x32_bf16 v[54:57], v[90:93], v[234:237], v[54:57]
	s_add_u32 m0, s4, 0xc800
	v_mfma_f32_16x16x32_bf16 v[38:41], v[90:93], v[238:241], v[38:41]
	global_load_lds_dwordx4 v100, s[6:7]
	v_mfma_f32_16x16x32_bf16 v[22:25], v[90:93], v[242:245], v[22:25]
	v_mfma_f32_16x16x32_bf16 v[6:9], v[90:93], v[246:249], v[6:9]
	v_mfma_f32_16x16x32_bf16 v[50:53], v[94:97], v[234:237], v[50:53]
	s_add_u32 m0, s4, 0xcc00
	v_mfma_f32_16x16x32_bf16 v[34:37], v[94:97], v[238:241], v[34:37]
	global_load_lds_dwordx4 v101, s[6:7]
	v_mfma_f32_16x16x32_bf16 v[18:21], v[94:97], v[242:245], v[18:21]
	v_mfma_f32_16x16x32_bf16 v[2:5], v[94:97], v[246:249], v[2:5]
	v_add_u32_e32 v98, 0x80, v98
	v_add_u32_e32 v99, 0x80, v99
	v_add_u32_e32 v100, 0x80, v100
	v_add_u32_e32 v101, 0x80, v101
	ds_read_b128 v[234:237], v103 offset:0
	ds_read_b128 v[238:241], v103 offset:2048
	ds_read_b128 v[242:245], v103 offset:4096
	ds_read_b128 v[246:249], v103 offset:6144
	s_waitcnt lgkmcnt(4)
	v_mfma_f32_16x16x32_bf16 v[106:109], v[66:69], v[218:221], v[106:109]
	s_add_u32 m0, s4, 0x8000
	v_mfma_f32_16x16x32_bf16 v[122:125], v[66:69], v[222:225], v[122:125]
	global_load_lds_dwordx4 v98, s[48:49]
	v_mfma_f32_16x16x32_bf16 v[138:141], v[66:69], v[226:229], v[138:141]
	v_mfma_f32_16x16x32_bf16 v[162:165], v[66:69], v[230:233], v[162:165]
	v_mfma_f32_16x16x32_bf16 v[110:113], v[70:73], v[218:221], v[110:113]
	s_add_u32 m0, s4, 0x8400
	v_mfma_f32_16x16x32_bf16 v[126:129], v[70:73], v[222:225], v[126:129]
	global_load_lds_dwordx4 v99, s[48:49]
	v_mfma_f32_16x16x32_bf16 v[142:145], v[70:73], v[226:229], v[142:145]
	v_mfma_f32_16x16x32_bf16 v[166:169], v[70:73], v[230:233], v[166:169]
	v_mfma_f32_16x16x32_bf16 v[114:117], v[74:77], v[218:221], v[114:117]
	s_add_u32 m0, s4, 0x8800
	v_mfma_f32_16x16x32_bf16 v[130:133], v[74:77], v[222:225], v[130:133]
	global_load_lds_dwordx4 v100, s[48:49]
	v_mfma_f32_16x16x32_bf16 v[154:157], v[74:77], v[226:229], v[154:157]
	v_mfma_f32_16x16x32_bf16 v[170:173], v[74:77], v[230:233], v[170:173]
	v_mfma_f32_16x16x32_bf16 v[118:121], v[78:81], v[218:221], v[118:121]
	s_add_u32 m0, s4, 0x8c00
	v_mfma_f32_16x16x32_bf16 v[134:137], v[78:81], v[222:225], v[134:137]
	global_load_lds_dwordx4 v101, s[48:49]
	v_mfma_f32_16x16x32_bf16 v[158:161], v[78:81], v[226:229], v[158:161]
	v_mfma_f32_16x16x32_bf16 v[174:177], v[78:81], v[230:233], v[174:177]
	s_waitcnt lgkmcnt(0)
	s_waitcnt vmcnt(8)
	s_barrier
	ds_read_b128 v[218:221], v102 offset:16384
	ds_read_b128 v[222:225], v102 offset:18432
	ds_read_b128 v[226:229], v102 offset:20480
	ds_read_b128 v[230:233], v102 offset:22528
	ds_read_b128 v[66:69], v250 offset:49152
	ds_read_b128 v[70:73], v250 offset:51200
	ds_read_b128 v[74:77], v250 offset:53248
	ds_read_b128 v[78:81], v250 offset:55296
	v_mfma_f32_16x16x32_bf16 v[106:109], v[82:85], v[234:237], v[106:109]
	s_add_u32 m0, s4, 0x0
	v_mfma_f32_16x16x32_bf16 v[122:125], v[82:85], v[238:241], v[122:125]
	global_load_lds_dwordx4 v98, s[28:29]
	v_mfma_f32_16x16x32_bf16 v[138:141], v[82:85], v[242:245], v[138:141]
	v_mfma_f32_16x16x32_bf16 v[162:165], v[82:85], v[246:249], v[162:165]
	v_mfma_f32_16x16x32_bf16 v[110:113], v[86:89], v[234:237], v[110:113]
	s_add_u32 m0, s4, 0x400
	v_mfma_f32_16x16x32_bf16 v[126:129], v[86:89], v[238:241], v[126:129]
	global_load_lds_dwordx4 v99, s[28:29]
	v_mfma_f32_16x16x32_bf16 v[142:145], v[86:89], v[242:245], v[142:145]
	v_mfma_f32_16x16x32_bf16 v[166:169], v[86:89], v[246:249], v[166:169]
	v_mfma_f32_16x16x32_bf16 v[114:117], v[90:93], v[234:237], v[114:117]
	s_add_u32 m0, s4, 0x800
	v_mfma_f32_16x16x32_bf16 v[130:133], v[90:93], v[238:241], v[130:133]
	global_load_lds_dwordx4 v100, s[28:29]
	v_mfma_f32_16x16x32_bf16 v[154:157], v[90:93], v[242:245], v[154:157]
	v_mfma_f32_16x16x32_bf16 v[170:173], v[90:93], v[246:249], v[170:173]
	v_mfma_f32_16x16x32_bf16 v[118:121], v[94:97], v[234:237], v[118:121]
	s_add_u32 m0, s4, 0xc00
	v_mfma_f32_16x16x32_bf16 v[134:137], v[94:97], v[238:241], v[134:137]
	global_load_lds_dwordx4 v101, s[28:29]
	v_mfma_f32_16x16x32_bf16 v[158:161], v[94:97], v[242:245], v[158:161]
	v_mfma_f32_16x16x32_bf16 v[174:177], v[94:97], v[246:249], v[174:177]
	ds_read_b128 v[234:237], v103 offset:16384
	ds_read_b128 v[238:241], v103 offset:18432
	ds_read_b128 v[242:245], v103 offset:20480
	ds_read_b128 v[246:249], v103 offset:22528
	ds_read_b128 v[82:85], v251 offset:49152
	ds_read_b128 v[86:89], v251 offset:51200
	ds_read_b128 v[90:93], v251 offset:53248
	ds_read_b128 v[94:97], v251 offset:55296
	s_waitcnt lgkmcnt(8)
	v_mfma_f32_16x16x32_bf16 v[62:65], v[66:69], v[218:221], v[62:65]
	v_mfma_f32_16x16x32_bf16 v[46:49], v[66:69], v[222:225], v[46:49]
	v_mfma_f32_16x16x32_bf16 v[30:33], v[66:69], v[226:229], v[30:33]
	v_mfma_f32_16x16x32_bf16 v[14:17], v[66:69], v[230:233], v[14:17]
	v_mfma_f32_16x16x32_bf16 v[58:61], v[70:73], v[218:221], v[58:61]
	v_mfma_f32_16x16x32_bf16 v[42:45], v[70:73], v[222:225], v[42:45]
	v_mfma_f32_16x16x32_bf16 v[26:29], v[70:73], v[226:229], v[26:29]
	v_mfma_f32_16x16x32_bf16 v[10:13], v[70:73], v[230:233], v[10:13]
	v_mfma_f32_16x16x32_bf16 v[54:57], v[74:77], v[218:221], v[54:57]
	v_mfma_f32_16x16x32_bf16 v[38:41], v[74:77], v[222:225], v[38:41]
	v_mfma_f32_16x16x32_bf16 v[22:25], v[74:77], v[226:229], v[22:25]
	v_mfma_f32_16x16x32_bf16 v[6:9], v[74:77], v[230:233], v[6:9]
	v_mfma_f32_16x16x32_bf16 v[50:53], v[78:81], v[218:221], v[50:53]
	v_mfma_f32_16x16x32_bf16 v[34:37], v[78:81], v[222:225], v[34:37]
	v_mfma_f32_16x16x32_bf16 v[18:21], v[78:81], v[226:229], v[18:21]
	v_mfma_f32_16x16x32_bf16 v[2:5], v[78:81], v[230:233], v[2:5]
	s_waitcnt lgkmcnt(0)
	s_waitcnt vmcnt(8)
	s_barrier
	ds_read_b128 v[218:221], v102 offset:49152
	ds_read_b128 v[222:225], v102 offset:51200
	ds_read_b128 v[226:229], v102 offset:53248
	ds_read_b128 v[230:233], v102 offset:55296
	v_mfma_f32_16x16x32_bf16 v[62:65], v[82:85], v[234:237], v[62:65]
	s_add_u32 m0, s4, 0x4000
	v_mfma_f32_16x16x32_bf16 v[46:49], v[82:85], v[238:241], v[46:49]
	global_load_lds_dwordx4 v98, s[6:7]
	v_mfma_f32_16x16x32_bf16 v[30:33], v[82:85], v[242:245], v[30:33]
	v_mfma_f32_16x16x32_bf16 v[14:17], v[82:85], v[246:249], v[14:17]
	v_mfma_f32_16x16x32_bf16 v[58:61], v[86:89], v[234:237], v[58:61]
	s_add_u32 m0, s4, 0x4400
	v_mfma_f32_16x16x32_bf16 v[42:45], v[86:89], v[238:241], v[42:45]
	global_load_lds_dwordx4 v99, s[6:7]
	v_mfma_f32_16x16x32_bf16 v[26:29], v[86:89], v[242:245], v[26:29]
	v_mfma_f32_16x16x32_bf16 v[10:13], v[86:89], v[246:249], v[10:13]
	v_mfma_f32_16x16x32_bf16 v[54:57], v[90:93], v[234:237], v[54:57]
	s_add_u32 m0, s4, 0x4800
	v_mfma_f32_16x16x32_bf16 v[38:41], v[90:93], v[238:241], v[38:41]
	global_load_lds_dwordx4 v100, s[6:7]
	v_mfma_f32_16x16x32_bf16 v[22:25], v[90:93], v[242:245], v[22:25]
	v_mfma_f32_16x16x32_bf16 v[6:9], v[90:93], v[246:249], v[6:9]
	v_mfma_f32_16x16x32_bf16 v[50:53], v[94:97], v[234:237], v[50:53]
	s_add_u32 m0, s4, 0x4c00
	v_mfma_f32_16x16x32_bf16 v[34:37], v[94:97], v[238:241], v[34:37]
	global_load_lds_dwordx4 v101, s[6:7]
	v_mfma_f32_16x16x32_bf16 v[18:21], v[94:97], v[242:245], v[18:21]
	v_mfma_f32_16x16x32_bf16 v[2:5], v[94:97], v[246:249], v[2:5]
	v_add_u32_e32 v98, 0x80, v98
	v_add_u32_e32 v99, 0x80, v99
	v_add_u32_e32 v100, 0x80, v100
	v_add_u32_e32 v101, 0x80, v101
	ds_read_b128 v[234:237], v103 offset:49152
	ds_read_b128 v[238:241], v103 offset:51200
	ds_read_b128 v[242:245], v103 offset:53248
	ds_read_b128 v[246:249], v103 offset:55296
	s_waitcnt lgkmcnt(4)
	v_mfma_f32_16x16x32_bf16 v[106:109], v[66:69], v[218:221], v[106:109]
	s_add_u32 m0, s4, 0x10000
	v_mfma_f32_16x16x32_bf16 v[122:125], v[66:69], v[222:225], v[122:125]
	global_load_lds_dwordx4 v98, s[48:49]
	v_mfma_f32_16x16x32_bf16 v[138:141], v[66:69], v[226:229], v[138:141]
	v_mfma_f32_16x16x32_bf16 v[162:165], v[66:69], v[230:233], v[162:165]
	v_mfma_f32_16x16x32_bf16 v[110:113], v[70:73], v[218:221], v[110:113]
	s_add_u32 m0, s4, 0x10400
	v_mfma_f32_16x16x32_bf16 v[126:129], v[70:73], v[222:225], v[126:129]
	global_load_lds_dwordx4 v99, s[48:49]
	v_mfma_f32_16x16x32_bf16 v[142:145], v[70:73], v[226:229], v[142:145]
	v_mfma_f32_16x16x32_bf16 v[166:169], v[70:73], v[230:233], v[166:169]
	v_mfma_f32_16x16x32_bf16 v[114:117], v[74:77], v[218:221], v[114:117]
	s_add_u32 m0, s4, 0x10800
	v_mfma_f32_16x16x32_bf16 v[130:133], v[74:77], v[222:225], v[130:133]
	global_load_lds_dwordx4 v100, s[48:49]
	v_mfma_f32_16x16x32_bf16 v[154:157], v[74:77], v[226:229], v[154:157]
	v_mfma_f32_16x16x32_bf16 v[170:173], v[74:77], v[230:233], v[170:173]
	v_mfma_f32_16x16x32_bf16 v[118:121], v[78:81], v[218:221], v[118:121]
	s_add_u32 m0, s4, 0x10c00
	v_mfma_f32_16x16x32_bf16 v[134:137], v[78:81], v[222:225], v[134:137]
	global_load_lds_dwordx4 v101, s[48:49]
	v_mfma_f32_16x16x32_bf16 v[158:161], v[78:81], v[226:229], v[158:161]
	v_mfma_f32_16x16x32_bf16 v[174:177], v[78:81], v[230:233], v[174:177]
	s_waitcnt lgkmcnt(0)
	s_waitcnt vmcnt(8)
	s_barrier
	ds_read_b128 v[218:221], v102 offset:0
	ds_read_b128 v[222:225], v102 offset:2048
	ds_read_b128 v[226:229], v102 offset:4096
	ds_read_b128 v[230:233], v102 offset:6144
	ds_read_b128 v[66:69], v104 offset:32768
	ds_read_b128 v[70:73], v104 offset:34816
	ds_read_b128 v[74:77], v104 offset:36864
	ds_read_b128 v[78:81], v104 offset:38912
	v_mfma_f32_16x16x32_bf16 v[106:109], v[82:85], v[234:237], v[106:109]
	s_add_u32 m0, s4, 0xc000
	v_mfma_f32_16x16x32_bf16 v[122:125], v[82:85], v[238:241], v[122:125]
	global_load_lds_dwordx4 v98, s[28:29]
	v_mfma_f32_16x16x32_bf16 v[138:141], v[82:85], v[242:245], v[138:141]
	v_mfma_f32_16x16x32_bf16 v[162:165], v[82:85], v[246:249], v[162:165]
	v_mfma_f32_16x16x32_bf16 v[110:113], v[86:89], v[234:237], v[110:113]
	s_add_u32 m0, s4, 0xc400
	v_mfma_f32_16x16x32_bf16 v[126:129], v[86:89], v[238:241], v[126:129]
	global_load_lds_dwordx4 v99, s[28:29]
	v_mfma_f32_16x16x32_bf16 v[142:145], v[86:89], v[242:245], v[142:145]
	v_mfma_f32_16x16x32_bf16 v[166:169], v[86:89], v[246:249], v[166:169]
	v_mfma_f32_16x16x32_bf16 v[114:117], v[90:93], v[234:237], v[114:117]
	s_add_u32 m0, s4, 0xc800
	v_mfma_f32_16x16x32_bf16 v[130:133], v[90:93], v[238:241], v[130:133]
	global_load_lds_dwordx4 v100, s[28:29]
	v_mfma_f32_16x16x32_bf16 v[154:157], v[90:93], v[242:245], v[154:157]
	v_mfma_f32_16x16x32_bf16 v[170:173], v[90:93], v[246:249], v[170:173]
	v_mfma_f32_16x16x32_bf16 v[118:121], v[94:97], v[234:237], v[118:121]
	s_add_u32 m0, s4, 0xcc00
	v_mfma_f32_16x16x32_bf16 v[134:137], v[94:97], v[238:241], v[134:137]
	global_load_lds_dwordx4 v101, s[28:29]
	v_mfma_f32_16x16x32_bf16 v[158:161], v[94:97], v[242:245], v[158:161]
	v_mfma_f32_16x16x32_bf16 v[174:177], v[94:97], v[246:249], v[174:177]
	ds_read_b128 v[234:237], v103 offset:0
	ds_read_b128 v[238:241], v103 offset:2048
	ds_read_b128 v[242:245], v103 offset:4096
	ds_read_b128 v[246:249], v103 offset:6144
	ds_read_b128 v[82:85], v105 offset:32768
	ds_read_b128 v[86:89], v105 offset:34816
	ds_read_b128 v[90:93], v105 offset:36864
	ds_read_b128 v[94:97], v105 offset:38912
	s_waitcnt lgkmcnt(8)
	v_mfma_f32_16x16x32_bf16 v[62:65], v[66:69], v[218:221], v[62:65]
	v_mfma_f32_16x16x32_bf16 v[46:49], v[66:69], v[222:225], v[46:49]
	v_mfma_f32_16x16x32_bf16 v[30:33], v[66:69], v[226:229], v[30:33]
	v_mfma_f32_16x16x32_bf16 v[14:17], v[66:69], v[230:233], v[14:17]
	v_mfma_f32_16x16x32_bf16 v[58:61], v[70:73], v[218:221], v[58:61]
	v_mfma_f32_16x16x32_bf16 v[42:45], v[70:73], v[222:225], v[42:45]
	v_mfma_f32_16x16x32_bf16 v[26:29], v[70:73], v[226:229], v[26:29]
	v_mfma_f32_16x16x32_bf16 v[10:13], v[70:73], v[230:233], v[10:13]
	v_mfma_f32_16x16x32_bf16 v[54:57], v[74:77], v[218:221], v[54:57]
	v_mfma_f32_16x16x32_bf16 v[38:41], v[74:77], v[222:225], v[38:41]
	v_mfma_f32_16x16x32_bf16 v[22:25], v[74:77], v[226:229], v[22:25]
	v_mfma_f32_16x16x32_bf16 v[6:9], v[74:77], v[230:233], v[6:9]
	v_mfma_f32_16x16x32_bf16 v[50:53], v[78:81], v[218:221], v[50:53]
	v_mfma_f32_16x16x32_bf16 v[34:37], v[78:81], v[222:225], v[34:37]
	v_mfma_f32_16x16x32_bf16 v[18:21], v[78:81], v[226:229], v[18:21]
	v_mfma_f32_16x16x32_bf16 v[2:5], v[78:81], v[230:233], v[2:5]
	s_waitcnt lgkmcnt(0)
	s_waitcnt vmcnt(8)
	s_barrier
	ds_read_b128 v[218:221], v102 offset:16384
	ds_read_b128 v[222:225], v102 offset:18432
	ds_read_b128 v[226:229], v102 offset:20480
	ds_read_b128 v[230:233], v102 offset:22528
	v_mfma_f32_16x16x32_bf16 v[62:65], v[82:85], v[234:237], v[62:65]
	s_add_u32 m0, s4, 0x0
	v_mfma_f32_16x16x32_bf16 v[46:49], v[82:85], v[238:241], v[46:49]
	global_load_lds_dwordx4 v98, s[6:7]
	v_mfma_f32_16x16x32_bf16 v[30:33], v[82:85], v[242:245], v[30:33]
	v_mfma_f32_16x16x32_bf16 v[14:17], v[82:85], v[246:249], v[14:17]
	v_mfma_f32_16x16x32_bf16 v[58:61], v[86:89], v[234:237], v[58:61]
	s_add_u32 m0, s4, 0x400
	v_mfma_f32_16x16x32_bf16 v[42:45], v[86:89], v[238:241], v[42:45]
	global_load_lds_dwordx4 v99, s[6:7]
	v_mfma_f32_16x16x32_bf16 v[26:29], v[86:89], v[242:245], v[26:29]
	v_mfma_f32_16x16x32_bf16 v[10:13], v[86:89], v[246:249], v[10:13]
	v_mfma_f32_16x16x32_bf16 v[54:57], v[90:93], v[234:237], v[54:57]
	s_add_u32 m0, s4, 0x800
	v_mfma_f32_16x16x32_bf16 v[38:41], v[90:93], v[238:241], v[38:41]
	global_load_lds_dwordx4 v100, s[6:7]
	v_mfma_f32_16x16x32_bf16 v[22:25], v[90:93], v[242:245], v[22:25]
	v_mfma_f32_16x16x32_bf16 v[6:9], v[90:93], v[246:249], v[6:9]
	v_mfma_f32_16x16x32_bf16 v[50:53], v[94:97], v[234:237], v[50:53]
	s_add_u32 m0, s4, 0xc00
	v_mfma_f32_16x16x32_bf16 v[34:37], v[94:97], v[238:241], v[34:37]
	global_load_lds_dwordx4 v101, s[6:7]
	v_mfma_f32_16x16x32_bf16 v[18:21], v[94:97], v[242:245], v[18:21]
	v_mfma_f32_16x16x32_bf16 v[2:5], v[94:97], v[246:249], v[2:5]
	v_add_u32_e32 v98, 0x80, v98
	v_add_u32_e32 v99, 0x80, v99
	v_add_u32_e32 v100, 0x80, v100
	v_add_u32_e32 v101, 0x80, v101
	ds_read_b128 v[234:237], v103 offset:16384
	ds_read_b128 v[238:241], v103 offset:18432
	ds_read_b128 v[242:245], v103 offset:20480
	ds_read_b128 v[246:249], v103 offset:22528
	s_waitcnt lgkmcnt(4)
	v_mfma_f32_16x16x32_bf16 v[106:109], v[66:69], v[218:221], v[106:109]
	s_add_u32 m0, s4, 0x8000
	v_mfma_f32_16x16x32_bf16 v[122:125], v[66:69], v[222:225], v[122:125]
	global_load_lds_dwordx4 v98, s[48:49]
	v_mfma_f32_16x16x32_bf16 v[138:141], v[66:69], v[226:229], v[138:141]
	v_mfma_f32_16x16x32_bf16 v[162:165], v[66:69], v[230:233], v[162:165]
	v_mfma_f32_16x16x32_bf16 v[110:113], v[70:73], v[218:221], v[110:113]
	s_add_u32 m0, s4, 0x8400
	v_mfma_f32_16x16x32_bf16 v[126:129], v[70:73], v[222:225], v[126:129]
	global_load_lds_dwordx4 v99, s[48:49]
	v_mfma_f32_16x16x32_bf16 v[142:145], v[70:73], v[226:229], v[142:145]
	v_mfma_f32_16x16x32_bf16 v[166:169], v[70:73], v[230:233], v[166:169]
	v_mfma_f32_16x16x32_bf16 v[114:117], v[74:77], v[218:221], v[114:117]
	s_add_u32 m0, s4, 0x8800
	v_mfma_f32_16x16x32_bf16 v[130:133], v[74:77], v[222:225], v[130:133]
	global_load_lds_dwordx4 v100, s[48:49]
	v_mfma_f32_16x16x32_bf16 v[154:157], v[74:77], v[226:229], v[154:157]
	v_mfma_f32_16x16x32_bf16 v[170:173], v[74:77], v[230:233], v[170:173]
	v_mfma_f32_16x16x32_bf16 v[118:121], v[78:81], v[218:221], v[118:121]
	s_add_u32 m0, s4, 0x8c00
	v_mfma_f32_16x16x32_bf16 v[134:137], v[78:81], v[222:225], v[134:137]
	global_load_lds_dwordx4 v101, s[48:49]
	v_mfma_f32_16x16x32_bf16 v[158:161], v[78:81], v[226:229], v[158:161]
	v_mfma_f32_16x16x32_bf16 v[174:177], v[78:81], v[230:233], v[174:177]
	s_waitcnt lgkmcnt(0)
	s_waitcnt vmcnt(8)
	s_barrier
	ds_read_b128 v[218:221], v102 offset:49152
	ds_read_b128 v[222:225], v102 offset:51200
	ds_read_b128 v[226:229], v102 offset:53248
	ds_read_b128 v[230:233], v102 offset:55296
	ds_read_b128 v[66:69], v250 offset:49152
	ds_read_b128 v[70:73], v250 offset:51200
	ds_read_b128 v[74:77], v250 offset:53248
	ds_read_b128 v[78:81], v250 offset:55296
	v_mfma_f32_16x16x32_bf16 v[106:109], v[82:85], v[234:237], v[106:109]
	s_add_u32 m0, s4, 0x4000
	v_mfma_f32_16x16x32_bf16 v[122:125], v[82:85], v[238:241], v[122:125]
	global_load_lds_dwordx4 v98, s[28:29]
	v_mfma_f32_16x16x32_bf16 v[138:141], v[82:85], v[242:245], v[138:141]
	v_mfma_f32_16x16x32_bf16 v[162:165], v[82:85], v[246:249], v[162:165]
	v_mfma_f32_16x16x32_bf16 v[110:113], v[86:89], v[234:237], v[110:113]
	s_add_u32 m0, s4, 0x4400
	v_mfma_f32_16x16x32_bf16 v[126:129], v[86:89], v[238:241], v[126:129]
	global_load_lds_dwordx4 v99, s[28:29]
	v_mfma_f32_16x16x32_bf16 v[142:145], v[86:89], v[242:245], v[142:145]
	v_mfma_f32_16x16x32_bf16 v[166:169], v[86:89], v[246:249], v[166:169]
	v_mfma_f32_16x16x32_bf16 v[114:117], v[90:93], v[234:237], v[114:117]
	s_add_u32 m0, s4, 0x4800
	v_mfma_f32_16x16x32_bf16 v[130:133], v[90:93], v[238:241], v[130:133]
	global_load_lds_dwordx4 v100, s[28:29]
	v_mfma_f32_16x16x32_bf16 v[154:157], v[90:93], v[242:245], v[154:157]
	v_mfma_f32_16x16x32_bf16 v[170:173], v[90:93], v[246:249], v[170:173]
	v_mfma_f32_16x16x32_bf16 v[118:121], v[94:97], v[234:237], v[118:121]
	s_add_u32 m0, s4, 0x4c00
	v_mfma_f32_16x16x32_bf16 v[134:137], v[94:97], v[238:241], v[134:137]
	global_load_lds_dwordx4 v101, s[28:29]
	v_mfma_f32_16x16x32_bf16 v[158:161], v[94:97], v[242:245], v[158:161]
	v_mfma_f32_16x16x32_bf16 v[174:177], v[94:97], v[246:249], v[174:177]
	ds_read_b128 v[234:237], v103 offset:49152
	ds_read_b128 v[238:241], v103 offset:51200
	ds_read_b128 v[242:245], v103 offset:53248
	ds_read_b128 v[246:249], v103 offset:55296
	ds_read_b128 v[82:85], v251 offset:49152
	ds_read_b128 v[86:89], v251 offset:51200
	ds_read_b128 v[90:93], v251 offset:53248
	ds_read_b128 v[94:97], v251 offset:55296
	s_waitcnt lgkmcnt(8)
	v_mfma_f32_16x16x32_bf16 v[62:65], v[66:69], v[218:221], v[62:65]
	v_mfma_f32_16x16x32_bf16 v[46:49], v[66:69], v[222:225], v[46:49]
	v_mfma_f32_16x16x32_bf16 v[30:33], v[66:69], v[226:229], v[30:33]
	v_mfma_f32_16x16x32_bf16 v[14:17], v[66:69], v[230:233], v[14:17]
	v_mfma_f32_16x16x32_bf16 v[58:61], v[70:73], v[218:221], v[58:61]
	v_mfma_f32_16x16x32_bf16 v[42:45], v[70:73], v[222:225], v[42:45]
	v_mfma_f32_16x16x32_bf16 v[26:29], v[70:73], v[226:229], v[26:29]
	v_mfma_f32_16x16x32_bf16 v[10:13], v[70:73], v[230:233], v[10:13]
	v_mfma_f32_16x16x32_bf16 v[54:57], v[74:77], v[218:221], v[54:57]
	v_mfma_f32_16x16x32_bf16 v[38:41], v[74:77], v[222:225], v[38:41]
	v_mfma_f32_16x16x32_bf16 v[22:25], v[74:77], v[226:229], v[22:25]
	v_mfma_f32_16x16x32_bf16 v[6:9], v[74:77], v[230:233], v[6:9]
	v_mfma_f32_16x16x32_bf16 v[50:53], v[78:81], v[218:221], v[50:53]
	v_mfma_f32_16x16x32_bf16 v[34:37], v[78:81], v[222:225], v[34:37]
	v_mfma_f32_16x16x32_bf16 v[18:21], v[78:81], v[226:229], v[18:21]
	v_mfma_f32_16x16x32_bf16 v[2:5], v[78:81], v[230:233], v[2:5]
	s_waitcnt lgkmcnt(0)
	s_waitcnt vmcnt(8)
	s_barrier
	ds_read_b128 v[218:221], v102 offset:0
	ds_read_b128 v[222:225], v102 offset:2048
	ds_read_b128 v[226:229], v102 offset:4096
	ds_read_b128 v[230:233], v102 offset:6144
	v_mfma_f32_16x16x32_bf16 v[62:65], v[82:85], v[234:237], v[62:65]
	s_add_u32 m0, s4, 0xc000
	v_mfma_f32_16x16x32_bf16 v[46:49], v[82:85], v[238:241], v[46:49]
	global_load_lds_dwordx4 v98, s[6:7]
	v_mfma_f32_16x16x32_bf16 v[30:33], v[82:85], v[242:245], v[30:33]
	v_mfma_f32_16x16x32_bf16 v[14:17], v[82:85], v[246:249], v[14:17]
	v_mfma_f32_16x16x32_bf16 v[58:61], v[86:89], v[234:237], v[58:61]
	s_add_u32 m0, s4, 0xc400
	v_mfma_f32_16x16x32_bf16 v[42:45], v[86:89], v[238:241], v[42:45]
	global_load_lds_dwordx4 v99, s[6:7]
	v_mfma_f32_16x16x32_bf16 v[26:29], v[86:89], v[242:245], v[26:29]
	v_mfma_f32_16x16x32_bf16 v[10:13], v[86:89], v[246:249], v[10:13]
	v_mfma_f32_16x16x32_bf16 v[54:57], v[90:93], v[234:237], v[54:57]
	s_add_u32 m0, s4, 0xc800
	v_mfma_f32_16x16x32_bf16 v[38:41], v[90:93], v[238:241], v[38:41]
	global_load_lds_dwordx4 v100, s[6:7]
	v_mfma_f32_16x16x32_bf16 v[22:25], v[90:93], v[242:245], v[22:25]
	v_mfma_f32_16x16x32_bf16 v[6:9], v[90:93], v[246:249], v[6:9]
	v_mfma_f32_16x16x32_bf16 v[50:53], v[94:97], v[234:237], v[50:53]
	s_add_u32 m0, s4, 0xcc00
	v_mfma_f32_16x16x32_bf16 v[34:37], v[94:97], v[238:241], v[34:37]
	global_load_lds_dwordx4 v101, s[6:7]
	v_mfma_f32_16x16x32_bf16 v[18:21], v[94:97], v[242:245], v[18:21]
	v_mfma_f32_16x16x32_bf16 v[2:5], v[94:97], v[246:249], v[2:5]
	v_add_u32_e32 v98, 0x80, v98
	v_add_u32_e32 v99, 0x80, v99
	v_add_u32_e32 v100, 0x80, v100
	v_add_u32_e32 v101, 0x80, v101
	ds_read_b128 v[234:237], v103 offset:0
	ds_read_b128 v[238:241], v103 offset:2048
	ds_read_b128 v[242:245], v103 offset:4096
	ds_read_b128 v[246:249], v103 offset:6144
	s_waitcnt lgkmcnt(4)
	v_mfma_f32_16x16x32_bf16 v[106:109], v[66:69], v[218:221], v[106:109]
	s_add_u32 m0, s4, 0x10000
	v_mfma_f32_16x16x32_bf16 v[122:125], v[66:69], v[222:225], v[122:125]
	global_load_lds_dwordx4 v98, s[48:49]
	v_mfma_f32_16x16x32_bf16 v[138:141], v[66:69], v[226:229], v[138:141]
	v_mfma_f32_16x16x32_bf16 v[162:165], v[66:69], v[230:233], v[162:165]
	v_mfma_f32_16x16x32_bf16 v[110:113], v[70:73], v[218:221], v[110:113]
	s_add_u32 m0, s4, 0x10400
	v_mfma_f32_16x16x32_bf16 v[126:129], v[70:73], v[222:225], v[126:129]
	global_load_lds_dwordx4 v99, s[48:49]
	v_mfma_f32_16x16x32_bf16 v[142:145], v[70:73], v[226:229], v[142:145]
	v_mfma_f32_16x16x32_bf16 v[166:169], v[70:73], v[230:233], v[166:169]
	v_mfma_f32_16x16x32_bf16 v[114:117], v[74:77], v[218:221], v[114:117]
	s_add_u32 m0, s4, 0x10800
	v_mfma_f32_16x16x32_bf16 v[130:133], v[74:77], v[222:225], v[130:133]
	global_load_lds_dwordx4 v100, s[48:49]
	v_mfma_f32_16x16x32_bf16 v[154:157], v[74:77], v[226:229], v[154:157]
	v_mfma_f32_16x16x32_bf16 v[170:173], v[74:77], v[230:233], v[170:173]
	v_mfma_f32_16x16x32_bf16 v[118:121], v[78:81], v[218:221], v[118:121]
	s_add_u32 m0, s4, 0x10c00
	v_mfma_f32_16x16x32_bf16 v[134:137], v[78:81], v[222:225], v[134:137]
	global_load_lds_dwordx4 v101, s[48:49]
	v_mfma_f32_16x16x32_bf16 v[158:161], v[78:81], v[226:229], v[158:161]
	v_mfma_f32_16x16x32_bf16 v[174:177], v[78:81], v[230:233], v[174:177]
	s_waitcnt lgkmcnt(0)
	s_waitcnt vmcnt(8)
	s_barrier
	ds_read_b128 v[218:221], v102 offset:16384
	ds_read_b128 v[222:225], v102 offset:18432
	ds_read_b128 v[226:229], v102 offset:20480
	ds_read_b128 v[230:233], v102 offset:22528
	ds_read_b128 v[66:69], v104 offset:32768
	ds_read_b128 v[70:73], v104 offset:34816
	ds_read_b128 v[74:77], v104 offset:36864
	ds_read_b128 v[78:81], v104 offset:38912
	v_mfma_f32_16x16x32_bf16 v[106:109], v[82:85], v[234:237], v[106:109]
	s_add_u32 m0, s4, 0x0
	v_mfma_f32_16x16x32_bf16 v[122:125], v[82:85], v[238:241], v[122:125]
	global_load_lds_dwordx4 v98, s[28:29]
	v_mfma_f32_16x16x32_bf16 v[138:141], v[82:85], v[242:245], v[138:141]
	v_mfma_f32_16x16x32_bf16 v[162:165], v[82:85], v[246:249], v[162:165]
	v_mfma_f32_16x16x32_bf16 v[110:113], v[86:89], v[234:237], v[110:113]
	s_add_u32 m0, s4, 0x400
	v_mfma_f32_16x16x32_bf16 v[126:129], v[86:89], v[238:241], v[126:129]
	global_load_lds_dwordx4 v99, s[28:29]
	v_mfma_f32_16x16x32_bf16 v[142:145], v[86:89], v[242:245], v[142:145]
	v_mfma_f32_16x16x32_bf16 v[166:169], v[86:89], v[246:249], v[166:169]
	v_mfma_f32_16x16x32_bf16 v[114:117], v[90:93], v[234:237], v[114:117]
	s_add_u32 m0, s4, 0x800
	v_mfma_f32_16x16x32_bf16 v[130:133], v[90:93], v[238:241], v[130:133]
	global_load_lds_dwordx4 v100, s[28:29]
	v_mfma_f32_16x16x32_bf16 v[154:157], v[90:93], v[242:245], v[154:157]
	v_mfma_f32_16x16x32_bf16 v[170:173], v[90:93], v[246:249], v[170:173]
	v_mfma_f32_16x16x32_bf16 v[118:121], v[94:97], v[234:237], v[118:121]
	s_add_u32 m0, s4, 0xc00
	v_mfma_f32_16x16x32_bf16 v[134:137], v[94:97], v[238:241], v[134:137]
	global_load_lds_dwordx4 v101, s[28:29]
	v_mfma_f32_16x16x32_bf16 v[158:161], v[94:97], v[242:245], v[158:161]
	v_mfma_f32_16x16x32_bf16 v[174:177], v[94:97], v[246:249], v[174:177]
	ds_read_b128 v[234:237], v103 offset:16384
	ds_read_b128 v[238:241], v103 offset:18432
	ds_read_b128 v[242:245], v103 offset:20480
	ds_read_b128 v[246:249], v103 offset:22528
	ds_read_b128 v[82:85], v105 offset:32768
	ds_read_b128 v[86:89], v105 offset:34816
	ds_read_b128 v[90:93], v105 offset:36864
	ds_read_b128 v[94:97], v105 offset:38912
	s_waitcnt lgkmcnt(8)
	v_mfma_f32_16x16x32_bf16 v[62:65], v[66:69], v[218:221], v[62:65]
	v_mfma_f32_16x16x32_bf16 v[46:49], v[66:69], v[222:225], v[46:49]
	v_mfma_f32_16x16x32_bf16 v[30:33], v[66:69], v[226:229], v[30:33]
	v_mfma_f32_16x16x32_bf16 v[14:17], v[66:69], v[230:233], v[14:17]
	v_mfma_f32_16x16x32_bf16 v[58:61], v[70:73], v[218:221], v[58:61]
	v_mfma_f32_16x16x32_bf16 v[42:45], v[70:73], v[222:225], v[42:45]
	v_mfma_f32_16x16x32_bf16 v[26:29], v[70:73], v[226:229], v[26:29]
	v_mfma_f32_16x16x32_bf16 v[10:13], v[70:73], v[230:233], v[10:13]
	v_mfma_f32_16x16x32_bf16 v[54:57], v[74:77], v[218:221], v[54:57]
	v_mfma_f32_16x16x32_bf16 v[38:41], v[74:77], v[222:225], v[38:41]
	v_mfma_f32_16x16x32_bf16 v[22:25], v[74:77], v[226:229], v[22:25]
	v_mfma_f32_16x16x32_bf16 v[6:9], v[74:77], v[230:233], v[6:9]
	v_mfma_f32_16x16x32_bf16 v[50:53], v[78:81], v[218:221], v[50:53]
	v_mfma_f32_16x16x32_bf16 v[34:37], v[78:81], v[222:225], v[34:37]
	v_mfma_f32_16x16x32_bf16 v[18:21], v[78:81], v[226:229], v[18:21]
	v_mfma_f32_16x16x32_bf16 v[2:5], v[78:81], v[230:233], v[2:5]
	s_waitcnt lgkmcnt(0)
	s_waitcnt vmcnt(8)
	s_barrier
	ds_read_b128 v[218:221], v102 offset:49152
	ds_read_b128 v[222:225], v102 offset:51200
	ds_read_b128 v[226:229], v102 offset:53248
	ds_read_b128 v[230:233], v102 offset:55296
	v_mfma_f32_16x16x32_bf16 v[62:65], v[82:85], v[234:237], v[62:65]
	s_add_u32 m0, s4, 0x4000
	v_mfma_f32_16x16x32_bf16 v[46:49], v[82:85], v[238:241], v[46:49]
	global_load_lds_dwordx4 v98, s[6:7]
	v_mfma_f32_16x16x32_bf16 v[30:33], v[82:85], v[242:245], v[30:33]
	v_mfma_f32_16x16x32_bf16 v[14:17], v[82:85], v[246:249], v[14:17]
	v_mfma_f32_16x16x32_bf16 v[58:61], v[86:89], v[234:237], v[58:61]
	s_add_u32 m0, s4, 0x4400
	v_mfma_f32_16x16x32_bf16 v[42:45], v[86:89], v[238:241], v[42:45]
	global_load_lds_dwordx4 v99, s[6:7]
	v_mfma_f32_16x16x32_bf16 v[26:29], v[86:89], v[242:245], v[26:29]
	v_mfma_f32_16x16x32_bf16 v[10:13], v[86:89], v[246:249], v[10:13]
	v_mfma_f32_16x16x32_bf16 v[54:57], v[90:93], v[234:237], v[54:57]
	s_add_u32 m0, s4, 0x4800
	v_mfma_f32_16x16x32_bf16 v[38:41], v[90:93], v[238:241], v[38:41]
	global_load_lds_dwordx4 v100, s[6:7]
	v_mfma_f32_16x16x32_bf16 v[22:25], v[90:93], v[242:245], v[22:25]
	v_mfma_f32_16x16x32_bf16 v[6:9], v[90:93], v[246:249], v[6:9]
	v_mfma_f32_16x16x32_bf16 v[50:53], v[94:97], v[234:237], v[50:53]
	s_add_u32 m0, s4, 0x4c00
	v_mfma_f32_16x16x32_bf16 v[34:37], v[94:97], v[238:241], v[34:37]
	global_load_lds_dwordx4 v101, s[6:7]
	v_mfma_f32_16x16x32_bf16 v[18:21], v[94:97], v[242:245], v[18:21]
	v_mfma_f32_16x16x32_bf16 v[2:5], v[94:97], v[246:249], v[2:5]
	v_add_u32_e32 v98, 0x80, v98
	v_add_u32_e32 v99, 0x80, v99
	v_add_u32_e32 v100, 0x80, v100
	v_add_u32_e32 v101, 0x80, v101
	ds_read_b128 v[234:237], v103 offset:49152
	ds_read_b128 v[238:241], v103 offset:51200
	ds_read_b128 v[242:245], v103 offset:53248
	ds_read_b128 v[246:249], v103 offset:55296
	s_waitcnt lgkmcnt(4)
	v_mfma_f32_16x16x32_bf16 v[106:109], v[66:69], v[218:221], v[106:109]
	s_add_u32 m0, s4, 0x8000
	v_mfma_f32_16x16x32_bf16 v[122:125], v[66:69], v[222:225], v[122:125]
	global_load_lds_dwordx4 v98, s[48:49]
	v_mfma_f32_16x16x32_bf16 v[138:141], v[66:69], v[226:229], v[138:141]
	v_mfma_f32_16x16x32_bf16 v[162:165], v[66:69], v[230:233], v[162:165]
	v_mfma_f32_16x16x32_bf16 v[110:113], v[70:73], v[218:221], v[110:113]
	s_add_u32 m0, s4, 0x8400
	v_mfma_f32_16x16x32_bf16 v[126:129], v[70:73], v[222:225], v[126:129]
	global_load_lds_dwordx4 v99, s[48:49]
	v_mfma_f32_16x16x32_bf16 v[142:145], v[70:73], v[226:229], v[142:145]
	v_mfma_f32_16x16x32_bf16 v[166:169], v[70:73], v[230:233], v[166:169]
	v_mfma_f32_16x16x32_bf16 v[114:117], v[74:77], v[218:221], v[114:117]
	s_add_u32 m0, s4, 0x8800
	v_mfma_f32_16x16x32_bf16 v[130:133], v[74:77], v[222:225], v[130:133]
	global_load_lds_dwordx4 v100, s[48:49]
	v_mfma_f32_16x16x32_bf16 v[154:157], v[74:77], v[226:229], v[154:157]
	v_mfma_f32_16x16x32_bf16 v[170:173], v[74:77], v[230:233], v[170:173]
	v_mfma_f32_16x16x32_bf16 v[118:121], v[78:81], v[218:221], v[118:121]
	s_add_u32 m0, s4, 0x8c00
	v_mfma_f32_16x16x32_bf16 v[134:137], v[78:81], v[222:225], v[134:137]
	global_load_lds_dwordx4 v101, s[48:49]
	v_mfma_f32_16x16x32_bf16 v[158:161], v[78:81], v[226:229], v[158:161]
	v_mfma_f32_16x16x32_bf16 v[174:177], v[78:81], v[230:233], v[174:177]
	s_waitcnt lgkmcnt(0)
	s_waitcnt vmcnt(8)
	s_barrier
	ds_read_b128 v[218:221], v102 offset:0
	ds_read_b128 v[222:225], v102 offset:2048
	ds_read_b128 v[226:229], v102 offset:4096
	ds_read_b128 v[230:233], v102 offset:6144
	ds_read_b128 v[66:69], v250 offset:49152
	ds_read_b128 v[70:73], v250 offset:51200
	ds_read_b128 v[74:77], v250 offset:53248
	ds_read_b128 v[78:81], v250 offset:55296
	v_mfma_f32_16x16x32_bf16 v[106:109], v[82:85], v[234:237], v[106:109]
	s_add_u32 m0, s4, 0xc000
	v_mfma_f32_16x16x32_bf16 v[122:125], v[82:85], v[238:241], v[122:125]
	global_load_lds_dwordx4 v98, s[28:29]
	v_mfma_f32_16x16x32_bf16 v[138:141], v[82:85], v[242:245], v[138:141]
	v_mfma_f32_16x16x32_bf16 v[162:165], v[82:85], v[246:249], v[162:165]
	v_mfma_f32_16x16x32_bf16 v[110:113], v[86:89], v[234:237], v[110:113]
	s_add_u32 m0, s4, 0xc400
	v_mfma_f32_16x16x32_bf16 v[126:129], v[86:89], v[238:241], v[126:129]
	global_load_lds_dwordx4 v99, s[28:29]
	v_mfma_f32_16x16x32_bf16 v[142:145], v[86:89], v[242:245], v[142:145]
	v_mfma_f32_16x16x32_bf16 v[166:169], v[86:89], v[246:249], v[166:169]
	v_mfma_f32_16x16x32_bf16 v[114:117], v[90:93], v[234:237], v[114:117]
	s_add_u32 m0, s4, 0xc800
	v_mfma_f32_16x16x32_bf16 v[130:133], v[90:93], v[238:241], v[130:133]
	global_load_lds_dwordx4 v100, s[28:29]
	v_mfma_f32_16x16x32_bf16 v[154:157], v[90:93], v[242:245], v[154:157]
	v_mfma_f32_16x16x32_bf16 v[170:173], v[90:93], v[246:249], v[170:173]
	v_mfma_f32_16x16x32_bf16 v[118:121], v[94:97], v[234:237], v[118:121]
	s_add_u32 m0, s4, 0xcc00
	v_mfma_f32_16x16x32_bf16 v[134:137], v[94:97], v[238:241], v[134:137]
	global_load_lds_dwordx4 v101, s[28:29]
	v_mfma_f32_16x16x32_bf16 v[158:161], v[94:97], v[242:245], v[158:161]
	v_mfma_f32_16x16x32_bf16 v[174:177], v[94:97], v[246:249], v[174:177]
	ds_read_b128 v[234:237], v103 offset:0
	ds_read_b128 v[238:241], v103 offset:2048
	ds_read_b128 v[242:245], v103 offset:4096
	ds_read_b128 v[246:249], v103 offset:6144
	ds_read_b128 v[82:85], v251 offset:49152
	ds_read_b128 v[86:89], v251 offset:51200
	ds_read_b128 v[90:93], v251 offset:53248
	ds_read_b128 v[94:97], v251 offset:55296
	s_waitcnt lgkmcnt(8)
	v_mfma_f32_16x16x32_bf16 v[62:65], v[66:69], v[218:221], v[62:65]
	v_mfma_f32_16x16x32_bf16 v[46:49], v[66:69], v[222:225], v[46:49]
	v_mfma_f32_16x16x32_bf16 v[30:33], v[66:69], v[226:229], v[30:33]
	v_mfma_f32_16x16x32_bf16 v[14:17], v[66:69], v[230:233], v[14:17]
	v_mfma_f32_16x16x32_bf16 v[58:61], v[70:73], v[218:221], v[58:61]
	v_mfma_f32_16x16x32_bf16 v[42:45], v[70:73], v[222:225], v[42:45]
	v_mfma_f32_16x16x32_bf16 v[26:29], v[70:73], v[226:229], v[26:29]
	v_mfma_f32_16x16x32_bf16 v[10:13], v[70:73], v[230:233], v[10:13]
	v_mfma_f32_16x16x32_bf16 v[54:57], v[74:77], v[218:221], v[54:57]
	v_mfma_f32_16x16x32_bf16 v[38:41], v[74:77], v[222:225], v[38:41]
	v_mfma_f32_16x16x32_bf16 v[22:25], v[74:77], v[226:229], v[22:25]
	v_mfma_f32_16x16x32_bf16 v[6:9], v[74:77], v[230:233], v[6:9]
	v_mfma_f32_16x16x32_bf16 v[50:53], v[78:81], v[218:221], v[50:53]
	v_mfma_f32_16x16x32_bf16 v[34:37], v[78:81], v[222:225], v[34:37]
	v_mfma_f32_16x16x32_bf16 v[18:21], v[78:81], v[226:229], v[18:21]
	v_mfma_f32_16x16x32_bf16 v[2:5], v[78:81], v[230:233], v[2:5]
	s_waitcnt lgkmcnt(0)
	s_waitcnt vmcnt(8)
	s_barrier
	ds_read_b128 v[218:221], v102 offset:16384
	ds_read_b128 v[222:225], v102 offset:18432
	ds_read_b128 v[226:229], v102 offset:20480
	ds_read_b128 v[230:233], v102 offset:22528
	v_mfma_f32_16x16x32_bf16 v[62:65], v[82:85], v[234:237], v[62:65]
	s_add_u32 m0, s4, 0x0
	v_mfma_f32_16x16x32_bf16 v[46:49], v[82:85], v[238:241], v[46:49]
	global_load_lds_dwordx4 v98, s[6:7]
	v_mfma_f32_16x16x32_bf16 v[30:33], v[82:85], v[242:245], v[30:33]
	v_mfma_f32_16x16x32_bf16 v[14:17], v[82:85], v[246:249], v[14:17]
	v_mfma_f32_16x16x32_bf16 v[58:61], v[86:89], v[234:237], v[58:61]
	s_add_u32 m0, s4, 0x400
	v_mfma_f32_16x16x32_bf16 v[42:45], v[86:89], v[238:241], v[42:45]
	global_load_lds_dwordx4 v99, s[6:7]
	v_mfma_f32_16x16x32_bf16 v[26:29], v[86:89], v[242:245], v[26:29]
	v_mfma_f32_16x16x32_bf16 v[10:13], v[86:89], v[246:249], v[10:13]
	v_mfma_f32_16x16x32_bf16 v[54:57], v[90:93], v[234:237], v[54:57]
	s_add_u32 m0, s4, 0x800
	v_mfma_f32_16x16x32_bf16 v[38:41], v[90:93], v[238:241], v[38:41]
	global_load_lds_dwordx4 v100, s[6:7]
	v_mfma_f32_16x16x32_bf16 v[22:25], v[90:93], v[242:245], v[22:25]
	v_mfma_f32_16x16x32_bf16 v[6:9], v[90:93], v[246:249], v[6:9]
	v_mfma_f32_16x16x32_bf16 v[50:53], v[94:97], v[234:237], v[50:53]
	s_add_u32 m0, s4, 0xc00
	v_mfma_f32_16x16x32_bf16 v[34:37], v[94:97], v[238:241], v[34:37]
	global_load_lds_dwordx4 v101, s[6:7]
	v_mfma_f32_16x16x32_bf16 v[18:21], v[94:97], v[242:245], v[18:21]
	v_mfma_f32_16x16x32_bf16 v[2:5], v[94:97], v[246:249], v[2:5]
	v_add_u32_e32 v98, 0x80, v98
	v_add_u32_e32 v99, 0x80, v99
	v_add_u32_e32 v100, 0x80, v100
	v_add_u32_e32 v101, 0x80, v101
	ds_read_b128 v[234:237], v103 offset:16384
	ds_read_b128 v[238:241], v103 offset:18432
	ds_read_b128 v[242:245], v103 offset:20480
	ds_read_b128 v[246:249], v103 offset:22528
	s_waitcnt lgkmcnt(4)
	v_mfma_f32_16x16x32_bf16 v[106:109], v[66:69], v[218:221], v[106:109]
	v_mfma_f32_16x16x32_bf16 v[122:125], v[66:69], v[222:225], v[122:125]
	v_mfma_f32_16x16x32_bf16 v[138:141], v[66:69], v[226:229], v[138:141]
	v_mfma_f32_16x16x32_bf16 v[162:165], v[66:69], v[230:233], v[162:165]
	v_mfma_f32_16x16x32_bf16 v[110:113], v[70:73], v[218:221], v[110:113]
	v_mfma_f32_16x16x32_bf16 v[126:129], v[70:73], v[222:225], v[126:129]
	v_mfma_f32_16x16x32_bf16 v[142:145], v[70:73], v[226:229], v[142:145]
	v_mfma_f32_16x16x32_bf16 v[166:169], v[70:73], v[230:233], v[166:169]
	v_mfma_f32_16x16x32_bf16 v[114:117], v[74:77], v[218:221], v[114:117]
	v_mfma_f32_16x16x32_bf16 v[130:133], v[74:77], v[222:225], v[130:133]
	v_mfma_f32_16x16x32_bf16 v[154:157], v[74:77], v[226:229], v[154:157]
	v_mfma_f32_16x16x32_bf16 v[170:173], v[74:77], v[230:233], v[170:173]
	v_mfma_f32_16x16x32_bf16 v[118:121], v[78:81], v[218:221], v[118:121]
	v_mfma_f32_16x16x32_bf16 v[134:137], v[78:81], v[222:225], v[134:137]
	v_mfma_f32_16x16x32_bf16 v[158:161], v[78:81], v[226:229], v[158:161]
	v_mfma_f32_16x16x32_bf16 v[174:177], v[78:81], v[230:233], v[174:177]
	s_waitcnt lgkmcnt(0)
	s_waitcnt vmcnt(4)
	s_barrier
	ds_read_b128 v[218:221], v102 offset:49152
	ds_read_b128 v[222:225], v102 offset:51200
	ds_read_b128 v[226:229], v102 offset:53248
	ds_read_b128 v[230:233], v102 offset:55296
	ds_read_b128 v[66:69], v104 offset:32768
	ds_read_b128 v[70:73], v104 offset:34816
	ds_read_b128 v[74:77], v104 offset:36864
	ds_read_b128 v[78:81], v104 offset:38912
	v_mfma_f32_16x16x32_bf16 v[106:109], v[82:85], v[234:237], v[106:109]
	v_mfma_f32_16x16x32_bf16 v[122:125], v[82:85], v[238:241], v[122:125]
	v_mfma_f32_16x16x32_bf16 v[138:141], v[82:85], v[242:245], v[138:141]
	v_mfma_f32_16x16x32_bf16 v[162:165], v[82:85], v[246:249], v[162:165]
	v_mfma_f32_16x16x32_bf16 v[110:113], v[86:89], v[234:237], v[110:113]
	v_mfma_f32_16x16x32_bf16 v[126:129], v[86:89], v[238:241], v[126:129]
	v_mfma_f32_16x16x32_bf16 v[142:145], v[86:89], v[242:245], v[142:145]
	v_mfma_f32_16x16x32_bf16 v[166:169], v[86:89], v[246:249], v[166:169]
	v_mfma_f32_16x16x32_bf16 v[114:117], v[90:93], v[234:237], v[114:117]
	v_mfma_f32_16x16x32_bf16 v[130:133], v[90:93], v[238:241], v[130:133]
	v_mfma_f32_16x16x32_bf16 v[154:157], v[90:93], v[242:245], v[154:157]
	v_mfma_f32_16x16x32_bf16 v[170:173], v[90:93], v[246:249], v[170:173]
	v_mfma_f32_16x16x32_bf16 v[118:121], v[94:97], v[234:237], v[118:121]
	v_mfma_f32_16x16x32_bf16 v[134:137], v[94:97], v[238:241], v[134:137]
	v_mfma_f32_16x16x32_bf16 v[158:161], v[94:97], v[242:245], v[158:161]
	v_mfma_f32_16x16x32_bf16 v[174:177], v[94:97], v[246:249], v[174:177]
	ds_read_b128 v[234:237], v103 offset:49152
	ds_read_b128 v[238:241], v103 offset:51200
	ds_read_b128 v[242:245], v103 offset:53248
	ds_read_b128 v[246:249], v103 offset:55296
	ds_read_b128 v[82:85], v105 offset:32768
	ds_read_b128 v[86:89], v105 offset:34816
	ds_read_b128 v[90:93], v105 offset:36864
	ds_read_b128 v[94:97], v105 offset:38912
	s_waitcnt lgkmcnt(8)
	v_mfma_f32_16x16x32_bf16 v[62:65], v[66:69], v[218:221], v[62:65]
	v_mfma_f32_16x16x32_bf16 v[46:49], v[66:69], v[222:225], v[46:49]
	v_mfma_f32_16x16x32_bf16 v[30:33], v[66:69], v[226:229], v[30:33]
	v_mfma_f32_16x16x32_bf16 v[14:17], v[66:69], v[230:233], v[14:17]
	v_mfma_f32_16x16x32_bf16 v[58:61], v[70:73], v[218:221], v[58:61]
	v_mfma_f32_16x16x32_bf16 v[42:45], v[70:73], v[222:225], v[42:45]
	v_mfma_f32_16x16x32_bf16 v[26:29], v[70:73], v[226:229], v[26:29]
	v_mfma_f32_16x16x32_bf16 v[10:13], v[70:73], v[230:233], v[10:13]
	v_mfma_f32_16x16x32_bf16 v[54:57], v[74:77], v[218:221], v[54:57]
	v_mfma_f32_16x16x32_bf16 v[38:41], v[74:77], v[222:225], v[38:41]
	v_mfma_f32_16x16x32_bf16 v[22:25], v[74:77], v[226:229], v[22:25]
	v_mfma_f32_16x16x32_bf16 v[6:9], v[74:77], v[230:233], v[6:9]
	v_mfma_f32_16x16x32_bf16 v[50:53], v[78:81], v[218:221], v[50:53]
	v_mfma_f32_16x16x32_bf16 v[34:37], v[78:81], v[222:225], v[34:37]
	v_mfma_f32_16x16x32_bf16 v[18:21], v[78:81], v[226:229], v[18:21]
	v_mfma_f32_16x16x32_bf16 v[2:5], v[78:81], v[230:233], v[2:5]
	s_waitcnt lgkmcnt(0)
	s_waitcnt vmcnt(0)
	s_barrier
	ds_read_b128 v[218:221], v102 offset:0
	ds_read_b128 v[222:225], v102 offset:2048
	ds_read_b128 v[226:229], v102 offset:4096
	ds_read_b128 v[230:233], v102 offset:6144
	v_mfma_f32_16x16x32_bf16 v[62:65], v[82:85], v[234:237], v[62:65]
	v_mfma_f32_16x16x32_bf16 v[46:49], v[82:85], v[238:241], v[46:49]
	v_mfma_f32_16x16x32_bf16 v[30:33], v[82:85], v[242:245], v[30:33]
	v_mfma_f32_16x16x32_bf16 v[14:17], v[82:85], v[246:249], v[14:17]
	v_mfma_f32_16x16x32_bf16 v[58:61], v[86:89], v[234:237], v[58:61]
	v_mfma_f32_16x16x32_bf16 v[42:45], v[86:89], v[238:241], v[42:45]
	v_mfma_f32_16x16x32_bf16 v[26:29], v[86:89], v[242:245], v[26:29]
	v_mfma_f32_16x16x32_bf16 v[10:13], v[86:89], v[246:249], v[10:13]
	v_mfma_f32_16x16x32_bf16 v[54:57], v[90:93], v[234:237], v[54:57]
	v_mfma_f32_16x16x32_bf16 v[38:41], v[90:93], v[238:241], v[38:41]
	v_mfma_f32_16x16x32_bf16 v[22:25], v[90:93], v[242:245], v[22:25]
	v_mfma_f32_16x16x32_bf16 v[6:9], v[90:93], v[246:249], v[6:9]
	v_mfma_f32_16x16x32_bf16 v[50:53], v[94:97], v[234:237], v[50:53]
	v_mfma_f32_16x16x32_bf16 v[34:37], v[94:97], v[238:241], v[34:37]
	v_mfma_f32_16x16x32_bf16 v[18:21], v[94:97], v[242:245], v[18:21]
	v_mfma_f32_16x16x32_bf16 v[2:5], v[94:97], v[246:249], v[2:5]
	ds_read_b128 v[234:237], v103 offset:0
	ds_read_b128 v[238:241], v103 offset:2048
	ds_read_b128 v[242:245], v103 offset:4096
	ds_read_b128 v[246:249], v103 offset:6144
	s_waitcnt lgkmcnt(4)
	v_mfma_f32_16x16x32_bf16 v[106:109], v[66:69], v[218:221], v[106:109]
	v_mfma_f32_16x16x32_bf16 v[122:125], v[66:69], v[222:225], v[122:125]
	v_mfma_f32_16x16x32_bf16 v[138:141], v[66:69], v[226:229], v[138:141]
	v_mfma_f32_16x16x32_bf16 v[162:165], v[66:69], v[230:233], v[162:165]
	v_mfma_f32_16x16x32_bf16 v[110:113], v[70:73], v[218:221], v[110:113]
	v_mfma_f32_16x16x32_bf16 v[126:129], v[70:73], v[222:225], v[126:129]
	v_mfma_f32_16x16x32_bf16 v[142:145], v[70:73], v[226:229], v[142:145]
	v_mfma_f32_16x16x32_bf16 v[166:169], v[70:73], v[230:233], v[166:169]
	v_mfma_f32_16x16x32_bf16 v[114:117], v[74:77], v[218:221], v[114:117]
	v_mfma_f32_16x16x32_bf16 v[130:133], v[74:77], v[222:225], v[130:133]
	v_mfma_f32_16x16x32_bf16 v[154:157], v[74:77], v[226:229], v[154:157]
	v_mfma_f32_16x16x32_bf16 v[170:173], v[74:77], v[230:233], v[170:173]
	v_mfma_f32_16x16x32_bf16 v[118:121], v[78:81], v[218:221], v[118:121]
	v_mfma_f32_16x16x32_bf16 v[134:137], v[78:81], v[222:225], v[134:137]
	v_mfma_f32_16x16x32_bf16 v[158:161], v[78:81], v[226:229], v[158:161]
	v_mfma_f32_16x16x32_bf16 v[174:177], v[78:81], v[230:233], v[174:177]
	s_waitcnt lgkmcnt(0)
	v_mfma_f32_16x16x32_bf16 v[106:109], v[82:85], v[234:237], v[106:109]
	v_mfma_f32_16x16x32_bf16 v[122:125], v[82:85], v[238:241], v[122:125]
	v_mfma_f32_16x16x32_bf16 v[138:141], v[82:85], v[242:245], v[138:141]
	v_mfma_f32_16x16x32_bf16 v[162:165], v[82:85], v[246:249], v[162:165]
	v_mfma_f32_16x16x32_bf16 v[110:113], v[86:89], v[234:237], v[110:113]
	v_mfma_f32_16x16x32_bf16 v[126:129], v[86:89], v[238:241], v[126:129]
	v_mfma_f32_16x16x32_bf16 v[142:145], v[86:89], v[242:245], v[142:145]
	v_mfma_f32_16x16x32_bf16 v[166:169], v[86:89], v[246:249], v[166:169]
	v_mfma_f32_16x16x32_bf16 v[114:117], v[90:93], v[234:237], v[114:117]
	v_mfma_f32_16x16x32_bf16 v[130:133], v[90:93], v[238:241], v[130:133]
	v_mfma_f32_16x16x32_bf16 v[154:157], v[90:93], v[242:245], v[154:157]
	v_mfma_f32_16x16x32_bf16 v[170:173], v[90:93], v[246:249], v[170:173]
	v_mfma_f32_16x16x32_bf16 v[118:121], v[94:97], v[234:237], v[118:121]
	v_mfma_f32_16x16x32_bf16 v[134:137], v[94:97], v[238:241], v[134:137]
	v_mfma_f32_16x16x32_bf16 v[158:161], v[94:97], v[242:245], v[158:161]
	v_mfma_f32_16x16x32_bf16 v[174:177], v[94:97], v[246:249], v[174:177]
	s_nop 7
	s_barrier
	s_and_b32 s5, s100, 0xff
	s_cmp_lt_u32 s5, 4
	s_cbranch_scc0 .Lpk_sw_nopf
	s_add_i32 s5, s5, 1
	s_lshl_b32 s5, s5, 6
	v_readlane_b32 s6, v254, 7
	s_add_i32 s5, s5, s6
	s_mul_hi_u32 s6, s5, 0x924924a
	s_mul_i32 s7, s6, 28
	s_sub_u32 s5, s5, s7
	s_mul_hi_u32 s7, s5, 0x24924925
	s_mul_i32 s28, s7, 7
	s_sub_u32 s5, s5, s28
	s_and_b32 s28, s6, 3
	s_mul_i32 s28, s28, 7
	s_add_i32 s28, s28, s5
	s_lshl_b32 s48, s28, 18
	s_add_u32 s48, s12, s48
	s_addc_u32 s49, s13, 0
	s_lshr_b32 s6, s6, 2
	s_lshl_b32 s6, s6, 3
	v_readlane_b32 s5, v254, 6
	s_or_b32 s6, s6, s5
	s_lshl_b32 s6, s6, 3
	s_lshl_b32 s7, s7, 1
	s_add_i32 s6, s6, s7
	s_lshl_b32 s6, s6, 18
	s_add_u32 s28, s94, s6
	s_addc_u32 s29, s95, 0
	v_add_u32_e32 v98, 0xfffff800, v98
	v_add_u32_e32 v99, 0xfffff800, v99
	v_add_u32_e32 v100, 0xfffff800, v100
	v_add_u32_e32 v101, 0xfffff800, v101
	s_add_u32 m0, s4, 0xc000
	s_nop 0
	global_load_lds_dwordx4 v98, s[28:29]
	s_add_u32 m0, s4, 0xc400
	s_nop 0
	global_load_lds_dwordx4 v99, s[28:29]
	s_add_u32 m0, s4, 0xc800
	s_nop 0
	global_load_lds_dwordx4 v100, s[28:29]
	s_add_u32 m0, s4, 0xcc00
	s_nop 0
	global_load_lds_dwordx4 v101, s[28:29]
	s_add_u32 m0, s4, 0x10000
	s_nop 0
	global_load_lds_dwordx4 v98, s[48:49]
	s_add_u32 m0, s4, 0x10400
	s_nop 0
	global_load_lds_dwordx4 v99, s[48:49]
	s_add_u32 m0, s4, 0x10800
	s_nop 0
	global_load_lds_dwordx4 v100, s[48:49]
	s_add_u32 m0, s4, 0x10c00
	s_nop 0
	global_load_lds_dwordx4 v101, s[48:49]
	s_or_b32 s100, s100, 0x1000
	s_branch .Lpk_sw_end

.Lpk_tt_pf:
	s_and_b32 s100, s100, 0xffffefff
	s_add_u32 m0, s4, 0x0
	s_nop 0
	global_load_lds_dwordx4 v98, s[6:7]
	s_add_u32 m0, s4, 0x400
	s_nop 0
	global_load_lds_dwordx4 v99, s[6:7]
	s_add_u32 m0, s4, 0x800
	s_nop 0
	global_load_lds_dwordx4 v100, s[6:7]
	s_add_u32 m0, s4, 0xc00
	s_nop 0
	global_load_lds_dwordx4 v101, s[6:7]
	v_add_u32_e32 v98, 0x80, v98
	v_add_u32_e32 v99, 0x80, v99
	v_add_u32_e32 v100, 0x80, v100
	v_add_u32_e32 v101, 0x80, v101
	s_add_u32 m0, s4, 0x8000
	s_nop 0
	global_load_lds_dwordx4 v98, s[48:49]
	s_add_u32 m0, s4, 0x8400
	s_nop 0
	global_load_lds_dwordx4 v99, s[48:49]
	s_add_u32 m0, s4, 0x8800
	s_nop 0
	global_load_lds_dwordx4 v100, s[48:49]
	s_add_u32 m0, s4, 0x8c00
	s_nop 0
	global_load_lds_dwordx4 v101, s[48:49]
	s_add_u32 m0, s4, 0x4000
	s_nop 0
	global_load_lds_dwordx4 v98, s[28:29]
	s_add_u32 m0, s4, 0x4400
	s_nop 0
	global_load_lds_dwordx4 v99, s[28:29]
	s_add_u32 m0, s4, 0x4800
	s_nop 0
	global_load_lds_dwordx4 v100, s[28:29]
	s_add_u32 m0, s4, 0x4c00
	s_nop 0
	global_load_lds_dwordx4 v101, s[28:29]
	v_mov_b32_e32 v62, 0
	v_mov_b32_e32 v106, 0
	v_mov_b32_e32 v63, 0
	v_mov_b32_e32 v107, 0
	v_mov_b32_e32 v64, 0
	v_mov_b32_e32 v108, 0
	v_mov_b32_e32 v65, 0
	v_mov_b32_e32 v109, 0
	v_mov_b32_e32 v58, 0
	v_mov_b32_e32 v110, 0
	v_mov_b32_e32 v59, 0
	v_mov_b32_e32 v111, 0
	v_mov_b32_e32 v60, 0
	v_mov_b32_e32 v112, 0
	v_mov_b32_e32 v61, 0
	v_mov_b32_e32 v113, 0
	v_mov_b32_e32 v54, 0
	v_mov_b32_e32 v114, 0
	v_mov_b32_e32 v55, 0
	v_mov_b32_e32 v115, 0
	v_mov_b32_e32 v56, 0
	v_mov_b32_e32 v116, 0
	v_mov_b32_e32 v57, 0
	v_mov_b32_e32 v117, 0
	v_mov_b32_e32 v50, 0
	v_mov_b32_e32 v118, 0
	v_mov_b32_e32 v51, 0
	v_mov_b32_e32 v119, 0
	v_mov_b32_e32 v52, 0
	v_mov_b32_e32 v120, 0
	v_mov_b32_e32 v53, 0
	v_mov_b32_e32 v121, 0
	v_mov_b32_e32 v46, 0
	v_mov_b32_e32 v122, 0
	v_mov_b32_e32 v47, 0
	v_mov_b32_e32 v123, 0
	v_mov_b32_e32 v48, 0
	v_mov_b32_e32 v124, 0
	v_mov_b32_e32 v49, 0
	v_mov_b32_e32 v125, 0
	v_mov_b32_e32 v42, 0
	v_mov_b32_e32 v126, 0
	v_mov_b32_e32 v43, 0
	v_mov_b32_e32 v127, 0
	v_mov_b32_e32 v44, 0
	v_mov_b32_e32 v128, 0
	v_mov_b32_e32 v45, 0
	v_mov_b32_e32 v129, 0
	v_mov_b32_e32 v38, 0
	v_mov_b32_e32 v130, 0
	v_mov_b32_e32 v39, 0
	v_mov_b32_e32 v131, 0
	v_mov_b32_e32 v40, 0
	v_mov_b32_e32 v132, 0
	v_mov_b32_e32 v41, 0
	v_mov_b32_e32 v133, 0
	v_mov_b32_e32 v34, 0
	v_mov_b32_e32 v134, 0
	v_mov_b32_e32 v35, 0
	v_mov_b32_e32 v135, 0
	v_mov_b32_e32 v36, 0
	v_mov_b32_e32 v136, 0
	v_mov_b32_e32 v37, 0
	v_mov_b32_e32 v137, 0
	v_mov_b32_e32 v30, 0
	v_mov_b32_e32 v138, 0
	v_mov_b32_e32 v31, 0
	v_mov_b32_e32 v139, 0
	v_mov_b32_e32 v32, 0
	v_mov_b32_e32 v140, 0
	v_mov_b32_e32 v33, 0
	v_mov_b32_e32 v141, 0
	v_mov_b32_e32 v26, 0
	v_mov_b32_e32 v142, 0
	v_mov_b32_e32 v27, 0
	v_mov_b32_e32 v143, 0
	v_mov_b32_e32 v28, 0
	v_mov_b32_e32 v144, 0
	v_mov_b32_e32 v29, 0
	v_mov_b32_e32 v145, 0
	v_mov_b32_e32 v22, 0
	v_mov_b32_e32 v154, 0
	v_mov_b32_e32 v23, 0
	v_mov_b32_e32 v155, 0
	v_mov_b32_e32 v24, 0
	v_mov_b32_e32 v156, 0
	v_mov_b32_e32 v25, 0
	v_mov_b32_e32 v157, 0
	v_mov_b32_e32 v18, 0
	v_mov_b32_e32 v158, 0
	v_mov_b32_e32 v19, 0
	v_mov_b32_e32 v159, 0
	v_mov_b32_e32 v20, 0
	v_mov_b32_e32 v160, 0
	v_mov_b32_e32 v21, 0
	v_mov_b32_e32 v161, 0
	v_mov_b32_e32 v14, 0
	v_mov_b32_e32 v162, 0
	v_mov_b32_e32 v15, 0
	v_mov_b32_e32 v163, 0
	v_mov_b32_e32 v16, 0
	v_mov_b32_e32 v164, 0
	v_mov_b32_e32 v17, 0
	v_mov_b32_e32 v165, 0
	v_mov_b32_e32 v10, 0
	v_mov_b32_e32 v166, 0
	v_mov_b32_e32 v11, 0
	v_mov_b32_e32 v167, 0
	v_mov_b32_e32 v12, 0
	v_mov_b32_e32 v168, 0
	v_mov_b32_e32 v13, 0
	v_mov_b32_e32 v169, 0
	v_mov_b32_e32 v6, 0
	v_mov_b32_e32 v170, 0
	v_mov_b32_e32 v7, 0
	v_mov_b32_e32 v171, 0
	v_mov_b32_e32 v8, 0
	v_mov_b32_e32 v172, 0
	v_mov_b32_e32 v9, 0
	v_mov_b32_e32 v173, 0
	v_mov_b32_e32 v2, 0
	v_mov_b32_e32 v174, 0
	v_mov_b32_e32 v3, 0
	v_mov_b32_e32 v175, 0
	v_mov_b32_e32 v4, 0
	v_mov_b32_e32 v176, 0
	v_mov_b32_e32 v5, 0
	v_mov_b32_e32 v177, 0
	s_waitcnt vmcnt(12)
	s_barrier
	ds_read_b128 v[218:221], v102 offset:49152
	ds_read_b128 v[222:225], v102 offset:51200
	ds_read_b128 v[226:229], v102 offset:53248
	ds_read_b128 v[230:233], v102 offset:55296
	ds_read_b128 v[66:69], v250 offset:49152
	ds_read_b128 v[70:73], v250 offset:51200
	ds_read_b128 v[74:77], v250 offset:53248
	ds_read_b128 v[78:81], v250 offset:55296
	ds_read_b128 v[234:237], v103 offset:49152
	ds_read_b128 v[238:241], v103 offset:51200
	ds_read_b128 v[242:245], v103 offset:53248
	ds_read_b128 v[246:249], v103 offset:55296
	ds_read_b128 v[82:85], v251 offset:49152
	ds_read_b128 v[86:89], v251 offset:51200
	ds_read_b128 v[90:93], v251 offset:53248
	ds_read_b128 v[94:97], v251 offset:55296
	s_waitcnt lgkmcnt(8)
	v_mfma_f32_16x16x32_bf16 v[62:65], v[218:221], v[66:69], v[62:65]
	v_mfma_f32_16x16x32_bf16 v[46:49], v[222:225], v[66:69], v[46:49]
	v_mfma_f32_16x16x32_bf16 v[30:33], v[226:229], v[66:69], v[30:33]
	v_mfma_f32_16x16x32_bf16 v[14:17], v[230:233], v[66:69], v[14:17]
	v_mfma_f32_16x16x32_bf16 v[58:61], v[218:221], v[70:73], v[58:61]
	v_mfma_f32_16x16x32_bf16 v[42:45], v[222:225], v[70:73], v[42:45]
	v_mfma_f32_16x16x32_bf16 v[26:29], v[226:229], v[70:73], v[26:29]
	v_mfma_f32_16x16x32_bf16 v[10:13], v[230:233], v[70:73], v[10:13]
	v_mfma_f32_16x16x32_bf16 v[54:57], v[218:221], v[74:77], v[54:57]
	v_mfma_f32_16x16x32_bf16 v[38:41], v[222:225], v[74:77], v[38:41]
	v_mfma_f32_16x16x32_bf16 v[22:25], v[226:229], v[74:77], v[22:25]
	v_mfma_f32_16x16x32_bf16 v[6:9], v[230:233], v[74:77], v[6:9]
	v_mfma_f32_16x16x32_bf16 v[50:53], v[218:221], v[78:81], v[50:53]
	v_mfma_f32_16x16x32_bf16 v[34:37], v[222:225], v[78:81], v[34:37]
	v_mfma_f32_16x16x32_bf16 v[18:21], v[226:229], v[78:81], v[18:21]
	v_mfma_f32_16x16x32_bf16 v[2:5], v[230:233], v[78:81], v[2:5]
	s_waitcnt lgkmcnt(0)
	s_waitcnt vmcnt(8)
	s_barrier
	ds_read_b128 v[218:221], v102 offset:0
	ds_read_b128 v[222:225], v102 offset:2048
	ds_read_b128 v[226:229], v102 offset:4096
	ds_read_b128 v[230:233], v102 offset:6144
	v_mfma_f32_16x16x32_bf16 v[62:65], v[234:237], v[82:85], v[62:65]
	s_add_u32 m0, s4, 0xc000
	v_mfma_f32_16x16x32_bf16 v[46:49], v[238:241], v[82:85], v[46:49]
	global_load_lds_dwordx4 v98, s[6:7]
	v_mfma_f32_16x16x32_bf16 v[30:33], v[242:245], v[82:85], v[30:33]
	v_mfma_f32_16x16x32_bf16 v[14:17], v[246:249], v[82:85], v[14:17]
	v_mfma_f32_16x16x32_bf16 v[58:61], v[234:237], v[86:89], v[58:61]
	s_add_u32 m0, s4, 0xc400
	v_mfma_f32_16x16x32_bf16 v[42:45], v[238:241], v[86:89], v[42:45]
	global_load_lds_dwordx4 v99, s[6:7]
	v_mfma_f32_16x16x32_bf16 v[26:29], v[242:245], v[86:89], v[26:29]
	v_mfma_f32_16x16x32_bf16 v[10:13], v[246:249], v[86:89], v[10:13]
	v_mfma_f32_16x16x32_bf16 v[54:57], v[234:237], v[90:93], v[54:57]
	s_add_u32 m0, s4, 0xc800
	v_mfma_f32_16x16x32_bf16 v[38:41], v[238:241], v[90:93], v[38:41]
	global_load_lds_dwordx4 v100, s[6:7]
	v_mfma_f32_16x16x32_bf16 v[22:25], v[242:245], v[90:93], v[22:25]
	v_mfma_f32_16x16x32_bf16 v[6:9], v[246:249], v[90:93], v[6:9]
	v_mfma_f32_16x16x32_bf16 v[50:53], v[234:237], v[94:97], v[50:53]
	s_add_u32 m0, s4, 0xcc00
	v_mfma_f32_16x16x32_bf16 v[34:37], v[238:241], v[94:97], v[34:37]
	global_load_lds_dwordx4 v101, s[6:7]
	v_mfma_f32_16x16x32_bf16 v[18:21], v[242:245], v[94:97], v[18:21]
	v_mfma_f32_16x16x32_bf16 v[2:5], v[246:249], v[94:97], v[2:5]
	v_add_u32_e32 v98, 0x80, v98
	v_add_u32_e32 v99, 0x80, v99
	v_add_u32_e32 v100, 0x80, v100
	v_add_u32_e32 v101, 0x80, v101
	ds_read_b128 v[234:237], v103 offset:0
	ds_read_b128 v[238:241], v103 offset:2048
	ds_read_b128 v[242:245], v103 offset:4096
	ds_read_b128 v[246:249], v103 offset:6144
	s_waitcnt lgkmcnt(4)
	v_mfma_f32_16x16x32_bf16 v[106:109], v[218:221], v[66:69], v[106:109]
	s_add_u32 m0, s4, 0x10000
	v_mfma_f32_16x16x32_bf16 v[122:125], v[222:225], v[66:69], v[122:125]
	global_load_lds_dwordx4 v98, s[48:49]
	v_mfma_f32_16x16x32_bf16 v[138:141], v[226:229], v[66:69], v[138:141]
	v_mfma_f32_16x16x32_bf16 v[162:165], v[230:233], v[66:69], v[162:165]
	v_mfma_f32_16x16x32_bf16 v[110:113], v[218:221], v[70:73], v[110:113]
	s_add_u32 m0, s4, 0x10400
	v_mfma_f32_16x16x32_bf16 v[126:129], v[222:225], v[70:73], v[126:129]
	global_load_lds_dwordx4 v99, s[48:49]
	v_mfma_f32_16x16x32_bf16 v[142:145], v[226:229], v[70:73], v[142:145]
	v_mfma_f32_16x16x32_bf16 v[166:169], v[230:233], v[70:73], v[166:169]
	v_mfma_f32_16x16x32_bf16 v[114:117], v[218:221], v[74:77], v[114:117]
	s_add_u32 m0, s4, 0x10800
	v_mfma_f32_16x16x32_bf16 v[130:133], v[222:225], v[74:77], v[130:133]
	global_load_lds_dwordx4 v100, s[48:49]
	v_mfma_f32_16x16x32_bf16 v[154:157], v[226:229], v[74:77], v[154:157]
	v_mfma_f32_16x16x32_bf16 v[170:173], v[230:233], v[74:77], v[170:173]
	v_mfma_f32_16x16x32_bf16 v[118:121], v[218:221], v[78:81], v[118:121]
	s_add_u32 m0, s4, 0x10c00
	v_mfma_f32_16x16x32_bf16 v[134:137], v[222:225], v[78:81], v[134:137]
	global_load_lds_dwordx4 v101, s[48:49]
	v_mfma_f32_16x16x32_bf16 v[158:161], v[226:229], v[78:81], v[158:161]
	v_mfma_f32_16x16x32_bf16 v[174:177], v[230:233], v[78:81], v[174:177]
	s_waitcnt lgkmcnt(0)
	s_waitcnt vmcnt(8)
	s_barrier
	ds_read_b128 v[218:221], v102 offset:16384
	ds_read_b128 v[222:225], v102 offset:18432
	ds_read_b128 v[226:229], v102 offset:20480
	ds_read_b128 v[230:233], v102 offset:22528
	ds_read_b128 v[66:69], v104 offset:32768
	ds_read_b128 v[70:73], v104 offset:34816
	ds_read_b128 v[74:77], v104 offset:36864
	ds_read_b128 v[78:81], v104 offset:38912
	v_mfma_f32_16x16x32_bf16 v[106:109], v[234:237], v[82:85], v[106:109]
	s_add_u32 m0, s4, 0x0
	v_mfma_f32_16x16x32_bf16 v[122:125], v[238:241], v[82:85], v[122:125]
	global_load_lds_dwordx4 v98, s[28:29]
	v_mfma_f32_16x16x32_bf16 v[138:141], v[242:245], v[82:85], v[138:141]
	v_mfma_f32_16x16x32_bf16 v[162:165], v[246:249], v[82:85], v[162:165]
	v_mfma_f32_16x16x32_bf16 v[110:113], v[234:237], v[86:89], v[110:113]
	s_add_u32 m0, s4, 0x400
	v_mfma_f32_16x16x32_bf16 v[126:129], v[238:241], v[86:89], v[126:129]
	global_load_lds_dwordx4 v99, s[28:29]
	v_mfma_f32_16x16x32_bf16 v[142:145], v[242:245], v[86:89], v[142:145]
	v_mfma_f32_16x16x32_bf16 v[166:169], v[246:249], v[86:89], v[166:169]
	v_mfma_f32_16x16x32_bf16 v[114:117], v[234:237], v[90:93], v[114:117]
	s_add_u32 m0, s4, 0x800
	v_mfma_f32_16x16x32_bf16 v[130:133], v[238:241], v[90:93], v[130:133]
	global_load_lds_dwordx4 v100, s[28:29]
	v_mfma_f32_16x16x32_bf16 v[154:157], v[242:245], v[90:93], v[154:157]
	v_mfma_f32_16x16x32_bf16 v[170:173], v[246:249], v[90:93], v[170:173]
	v_mfma_f32_16x16x32_bf16 v[118:121], v[234:237], v[94:97], v[118:121]
	s_add_u32 m0, s4, 0xc00
	v_mfma_f32_16x16x32_bf16 v[134:137], v[238:241], v[94:97], v[134:137]
	global_load_lds_dwordx4 v101, s[28:29]
	v_mfma_f32_16x16x32_bf16 v[158:161], v[242:245], v[94:97], v[158:161]
	v_mfma_f32_16x16x32_bf16 v[174:177], v[246:249], v[94:97], v[174:177]
	ds_read_b128 v[234:237], v103 offset:16384
	ds_read_b128 v[238:241], v103 offset:18432
	ds_read_b128 v[242:245], v103 offset:20480
	ds_read_b128 v[246:249], v103 offset:22528
	ds_read_b128 v[82:85], v105 offset:32768
	ds_read_b128 v[86:89], v105 offset:34816
	ds_read_b128 v[90:93], v105 offset:36864
	ds_read_b128 v[94:97], v105 offset:38912
	s_waitcnt lgkmcnt(8)
	v_mfma_f32_16x16x32_bf16 v[62:65], v[218:221], v[66:69], v[62:65]
	v_mfma_f32_16x16x32_bf16 v[46:49], v[222:225], v[66:69], v[46:49]
	v_mfma_f32_16x16x32_bf16 v[30:33], v[226:229], v[66:69], v[30:33]
	v_mfma_f32_16x16x32_bf16 v[14:17], v[230:233], v[66:69], v[14:17]
	v_mfma_f32_16x16x32_bf16 v[58:61], v[218:221], v[70:73], v[58:61]
	v_mfma_f32_16x16x32_bf16 v[42:45], v[222:225], v[70:73], v[42:45]
	v_mfma_f32_16x16x32_bf16 v[26:29], v[226:229], v[70:73], v[26:29]
	v_mfma_f32_16x16x32_bf16 v[10:13], v[230:233], v[70:73], v[10:13]
	v_mfma_f32_16x16x32_bf16 v[54:57], v[218:221], v[74:77], v[54:57]
	v_mfma_f32_16x16x32_bf16 v[38:41], v[222:225], v[74:77], v[38:41]
	v_mfma_f32_16x16x32_bf16 v[22:25], v[226:229], v[74:77], v[22:25]
	v_mfma_f32_16x16x32_bf16 v[6:9], v[230:233], v[74:77], v[6:9]
	v_mfma_f32_16x16x32_bf16 v[50:53], v[218:221], v[78:81], v[50:53]
	v_mfma_f32_16x16x32_bf16 v[34:37], v[222:225], v[78:81], v[34:37]
	v_mfma_f32_16x16x32_bf16 v[18:21], v[226:229], v[78:81], v[18:21]
	v_mfma_f32_16x16x32_bf16 v[2:5], v[230:233], v[78:81], v[2:5]
	s_waitcnt lgkmcnt(0)
	s_waitcnt vmcnt(8)
	s_barrier
	ds_read_b128 v[218:221], v102 offset:49152
	ds_read_b128 v[222:225], v102 offset:51200
	ds_read_b128 v[226:229], v102 offset:53248
	ds_read_b128 v[230:233], v102 offset:55296
	v_mfma_f32_16x16x32_bf16 v[62:65], v[234:237], v[82:85], v[62:65]
	s_add_u32 m0, s4, 0x4000
	v_mfma_f32_16x16x32_bf16 v[46:49], v[238:241], v[82:85], v[46:49]
	global_load_lds_dwordx4 v98, s[6:7]
	v_mfma_f32_16x16x32_bf16 v[30:33], v[242:245], v[82:85], v[30:33]
	v_mfma_f32_16x16x32_bf16 v[14:17], v[246:249], v[82:85], v[14:17]
	v_mfma_f32_16x16x32_bf16 v[58:61], v[234:237], v[86:89], v[58:61]
	s_add_u32 m0, s4, 0x4400
	v_mfma_f32_16x16x32_bf16 v[42:45], v[238:241], v[86:89], v[42:45]
	global_load_lds_dwordx4 v99, s[6:7]
	v_mfma_f32_16x16x32_bf16 v[26:29], v[242:245], v[86:89], v[26:29]
	v_mfma_f32_16x16x32_bf16 v[10:13], v[246:249], v[86:89], v[10:13]
	v_mfma_f32_16x16x32_bf16 v[54:57], v[234:237], v[90:93], v[54:57]
	s_add_u32 m0, s4, 0x4800
	v_mfma_f32_16x16x32_bf16 v[38:41], v[238:241], v[90:93], v[38:41]
	global_load_lds_dwordx4 v100, s[6:7]
	v_mfma_f32_16x16x32_bf16 v[22:25], v[242:245], v[90:93], v[22:25]
	v_mfma_f32_16x16x32_bf16 v[6:9], v[246:249], v[90:93], v[6:9]
	v_mfma_f32_16x16x32_bf16 v[50:53], v[234:237], v[94:97], v[50:53]
	s_add_u32 m0, s4, 0x4c00
	v_mfma_f32_16x16x32_bf16 v[34:37], v[238:241], v[94:97], v[34:37]
	global_load_lds_dwordx4 v101, s[6:7]
	v_mfma_f32_16x16x32_bf16 v[18:21], v[242:245], v[94:97], v[18:21]
	v_mfma_f32_16x16x32_bf16 v[2:5], v[246:249], v[94:97], v[2:5]
	v_add_u32_e32 v98, 0x80, v98
	v_add_u32_e32 v99, 0x80, v99
	v_add_u32_e32 v100, 0x80, v100
	v_add_u32_e32 v101, 0x80, v101
	ds_read_b128 v[234:237], v103 offset:49152
	ds_read_b128 v[238:241], v103 offset:51200
	ds_read_b128 v[242:245], v103 offset:53248
	ds_read_b128 v[246:249], v103 offset:55296
	s_waitcnt lgkmcnt(4)
	v_mfma_f32_16x16x32_bf16 v[106:109], v[218:221], v[66:69], v[106:109]
	s_add_u32 m0, s4, 0x8000
	v_mfma_f32_16x16x32_bf16 v[122:125], v[222:225], v[66:69], v[122:125]
	global_load_lds_dwordx4 v98, s[48:49]
	v_mfma_f32_16x16x32_bf16 v[138:141], v[226:229], v[66:69], v[138:141]
	v_mfma_f32_16x16x32_bf16 v[162:165], v[230:233], v[66:69], v[162:165]
	v_mfma_f32_16x16x32_bf16 v[110:113], v[218:221], v[70:73], v[110:113]
	s_add_u32 m0, s4, 0x8400
	v_mfma_f32_16x16x32_bf16 v[126:129], v[222:225], v[70:73], v[126:129]
	global_load_lds_dwordx4 v99, s[48:49]
	v_mfma_f32_16x16x32_bf16 v[142:145], v[226:229], v[70:73], v[142:145]
	v_mfma_f32_16x16x32_bf16 v[166:169], v[230:233], v[70:73], v[166:169]
	v_mfma_f32_16x16x32_bf16 v[114:117], v[218:221], v[74:77], v[114:117]
	s_add_u32 m0, s4, 0x8800
	v_mfma_f32_16x16x32_bf16 v[130:133], v[222:225], v[74:77], v[130:133]
	global_load_lds_dwordx4 v100, s[48:49]
	v_mfma_f32_16x16x32_bf16 v[154:157], v[226:229], v[74:77], v[154:157]
	v_mfma_f32_16x16x32_bf16 v[170:173], v[230:233], v[74:77], v[170:173]
	v_mfma_f32_16x16x32_bf16 v[118:121], v[218:221], v[78:81], v[118:121]
	s_add_u32 m0, s4, 0x8c00
	v_mfma_f32_16x16x32_bf16 v[134:137], v[222:225], v[78:81], v[134:137]
	global_load_lds_dwordx4 v101, s[48:49]
	v_mfma_f32_16x16x32_bf16 v[158:161], v[226:229], v[78:81], v[158:161]
	v_mfma_f32_16x16x32_bf16 v[174:177], v[230:233], v[78:81], v[174:177]
	s_waitcnt lgkmcnt(0)
	s_waitcnt vmcnt(8)
	s_barrier
	ds_read_b128 v[218:221], v102 offset:0
	ds_read_b128 v[222:225], v102 offset:2048
	ds_read_b128 v[226:229], v102 offset:4096
	ds_read_b128 v[230:233], v102 offset:6144
	ds_read_b128 v[66:69], v250 offset:49152
	ds_read_b128 v[70:73], v250 offset:51200
	ds_read_b128 v[74:77], v250 offset:53248
	ds_read_b128 v[78:81], v250 offset:55296
	v_mfma_f32_16x16x32_bf16 v[106:109], v[234:237], v[82:85], v[106:109]
	s_add_u32 m0, s4, 0xc000
	v_mfma_f32_16x16x32_bf16 v[122:125], v[238:241], v[82:85], v[122:125]
	global_load_lds_dwordx4 v98, s[28:29]
	v_mfma_f32_16x16x32_bf16 v[138:141], v[242:245], v[82:85], v[138:141]
	v_mfma_f32_16x16x32_bf16 v[162:165], v[246:249], v[82:85], v[162:165]
	v_mfma_f32_16x16x32_bf16 v[110:113], v[234:237], v[86:89], v[110:113]
	s_add_u32 m0, s4, 0xc400
	v_mfma_f32_16x16x32_bf16 v[126:129], v[238:241], v[86:89], v[126:129]
	global_load_lds_dwordx4 v99, s[28:29]
	v_mfma_f32_16x16x32_bf16 v[142:145], v[242:245], v[86:89], v[142:145]
	v_mfma_f32_16x16x32_bf16 v[166:169], v[246:249], v[86:89], v[166:169]
	v_mfma_f32_16x16x32_bf16 v[114:117], v[234:237], v[90:93], v[114:117]
	s_add_u32 m0, s4, 0xc800
	v_mfma_f32_16x16x32_bf16 v[130:133], v[238:241], v[90:93], v[130:133]
	global_load_lds_dwordx4 v100, s[28:29]
	v_mfma_f32_16x16x32_bf16 v[154:157], v[242:245], v[90:93], v[154:157]
	v_mfma_f32_16x16x32_bf16 v[170:173], v[246:249], v[90:93], v[170:173]
	v_mfma_f32_16x16x32_bf16 v[118:121], v[234:237], v[94:97], v[118:121]
	s_add_u32 m0, s4, 0xcc00
	v_mfma_f32_16x16x32_bf16 v[134:137], v[238:241], v[94:97], v[134:137]
	global_load_lds_dwordx4 v101, s[28:29]
	v_mfma_f32_16x16x32_bf16 v[158:161], v[242:245], v[94:97], v[158:161]
	v_mfma_f32_16x16x32_bf16 v[174:177], v[246:249], v[94:97], v[174:177]
	ds_read_b128 v[234:237], v103 offset:0
	ds_read_b128 v[238:241], v103 offset:2048
	ds_read_b128 v[242:245], v103 offset:4096
	ds_read_b128 v[246:249], v103 offset:6144
	ds_read_b128 v[82:85], v251 offset:49152
	ds_read_b128 v[86:89], v251 offset:51200
	ds_read_b128 v[90:93], v251 offset:53248
	ds_read_b128 v[94:97], v251 offset:55296
	s_waitcnt lgkmcnt(8)
	v_mfma_f32_16x16x32_bf16 v[62:65], v[218:221], v[66:69], v[62:65]
	v_mfma_f32_16x16x32_bf16 v[46:49], v[222:225], v[66:69], v[46:49]
	v_mfma_f32_16x16x32_bf16 v[30:33], v[226:229], v[66:69], v[30:33]
	v_mfma_f32_16x16x32_bf16 v[14:17], v[230:233], v[66:69], v[14:17]
	v_mfma_f32_16x16x32_bf16 v[58:61], v[218:221], v[70:73], v[58:61]
	v_mfma_f32_16x16x32_bf16 v[42:45], v[222:225], v[70:73], v[42:45]
	v_mfma_f32_16x16x32_bf16 v[26:29], v[226:229], v[70:73], v[26:29]
	v_mfma_f32_16x16x32_bf16 v[10:13], v[230:233], v[70:73], v[10:13]
	v_mfma_f32_16x16x32_bf16 v[54:57], v[218:221], v[74:77], v[54:57]
	v_mfma_f32_16x16x32_bf16 v[38:41], v[222:225], v[74:77], v[38:41]
	v_mfma_f32_16x16x32_bf16 v[22:25], v[226:229], v[74:77], v[22:25]
	v_mfma_f32_16x16x32_bf16 v[6:9], v[230:233], v[74:77], v[6:9]
	v_mfma_f32_16x16x32_bf16 v[50:53], v[218:221], v[78:81], v[50:53]
	v_mfma_f32_16x16x32_bf16 v[34:37], v[222:225], v[78:81], v[34:37]
	v_mfma_f32_16x16x32_bf16 v[18:21], v[226:229], v[78:81], v[18:21]
	v_mfma_f32_16x16x32_bf16 v[2:5], v[230:233], v[78:81], v[2:5]
	s_waitcnt lgkmcnt(0)
	s_waitcnt vmcnt(8)
	s_barrier
	ds_read_b128 v[218:221], v102 offset:16384
	ds_read_b128 v[222:225], v102 offset:18432
	ds_read_b128 v[226:229], v102 offset:20480
	ds_read_b128 v[230:233], v102 offset:22528
	v_mfma_f32_16x16x32_bf16 v[62:65], v[234:237], v[82:85], v[62:65]
	s_add_u32 m0, s4, 0x0
	v_mfma_f32_16x16x32_bf16 v[46:49], v[238:241], v[82:85], v[46:49]
	global_load_lds_dwordx4 v98, s[6:7]
	v_mfma_f32_16x16x32_bf16 v[30:33], v[242:245], v[82:85], v[30:33]
	v_mfma_f32_16x16x32_bf16 v[14:17], v[246:249], v[82:85], v[14:17]
	v_mfma_f32_16x16x32_bf16 v[58:61], v[234:237], v[86:89], v[58:61]
	s_add_u32 m0, s4, 0x400
	v_mfma_f32_16x16x32_bf16 v[42:45], v[238:241], v[86:89], v[42:45]
	global_load_lds_dwordx4 v99, s[6:7]
	v_mfma_f32_16x16x32_bf16 v[26:29], v[242:245], v[86:89], v[26:29]
	v_mfma_f32_16x16x32_bf16 v[10:13], v[246:249], v[86:89], v[10:13]
	v_mfma_f32_16x16x32_bf16 v[54:57], v[234:237], v[90:93], v[54:57]
	s_add_u32 m0, s4, 0x800
	v_mfma_f32_16x16x32_bf16 v[38:41], v[238:241], v[90:93], v[38:41]
	global_load_lds_dwordx4 v100, s[6:7]
	v_mfma_f32_16x16x32_bf16 v[22:25], v[242:245], v[90:93], v[22:25]
	v_mfma_f32_16x16x32_bf16 v[6:9], v[246:249], v[90:93], v[6:9]
	v_mfma_f32_16x16x32_bf16 v[50:53], v[234:237], v[94:97], v[50:53]
	s_add_u32 m0, s4, 0xc00
	v_mfma_f32_16x16x32_bf16 v[34:37], v[238:241], v[94:97], v[34:37]
	global_load_lds_dwordx4 v101, s[6:7]
	v_mfma_f32_16x16x32_bf16 v[18:21], v[242:245], v[94:97], v[18:21]
	v_mfma_f32_16x16x32_bf16 v[2:5], v[246:249], v[94:97], v[2:5]
	v_add_u32_e32 v98, 0x80, v98
	v_add_u32_e32 v99, 0x80, v99
	v_add_u32_e32 v100, 0x80, v100
	v_add_u32_e32 v101, 0x80, v101
	ds_read_b128 v[234:237], v103 offset:16384
	ds_read_b128 v[238:241], v103 offset:18432
	ds_read_b128 v[242:245], v103 offset:20480
	ds_read_b128 v[246:249], v103 offset:22528
	s_waitcnt lgkmcnt(4)
	v_mfma_f32_16x16x32_bf16 v[106:109], v[218:221], v[66:69], v[106:109]
	s_add_u32 m0, s4, 0x10000
	v_mfma_f32_16x16x32_bf16 v[122:125], v[222:225], v[66:69], v[122:125]
	global_load_lds_dwordx4 v98, s[48:49]
	v_mfma_f32_16x16x32_bf16 v[138:141], v[226:229], v[66:69], v[138:141]
	v_mfma_f32_16x16x32_bf16 v[162:165], v[230:233], v[66:69], v[162:165]
	v_mfma_f32_16x16x32_bf16 v[110:113], v[218:221], v[70:73], v[110:113]
	s_add_u32 m0, s4, 0x10400
	v_mfma_f32_16x16x32_bf16 v[126:129], v[222:225], v[70:73], v[126:129]
	global_load_lds_dwordx4 v99, s[48:49]
	v_mfma_f32_16x16x32_bf16 v[142:145], v[226:229], v[70:73], v[142:145]
	v_mfma_f32_16x16x32_bf16 v[166:169], v[230:233], v[70:73], v[166:169]
	v_mfma_f32_16x16x32_bf16 v[114:117], v[218:221], v[74:77], v[114:117]
	s_add_u32 m0, s4, 0x10800
	v_mfma_f32_16x16x32_bf16 v[130:133], v[222:225], v[74:77], v[130:133]
	global_load_lds_dwordx4 v100, s[48:49]
	v_mfma_f32_16x16x32_bf16 v[154:157], v[226:229], v[74:77], v[154:157]
	v_mfma_f32_16x16x32_bf16 v[170:173], v[230:233], v[74:77], v[170:173]
	v_mfma_f32_16x16x32_bf16 v[118:121], v[218:221], v[78:81], v[118:121]
	s_add_u32 m0, s4, 0x10c00
	v_mfma_f32_16x16x32_bf16 v[134:137], v[222:225], v[78:81], v[134:137]
	global_load_lds_dwordx4 v101, s[48:49]
	v_mfma_f32_16x16x32_bf16 v[158:161], v[226:229], v[78:81], v[158:161]
	v_mfma_f32_16x16x32_bf16 v[174:177], v[230:233], v[78:81], v[174:177]
	s_waitcnt lgkmcnt(0)
	s_waitcnt vmcnt(8)
	s_barrier
	ds_read_b128 v[218:221], v102 offset:49152
	ds_read_b128 v[222:225], v102 offset:51200
	ds_read_b128 v[226:229], v102 offset:53248
	ds_read_b128 v[230:233], v102 offset:55296
	ds_read_b128 v[66:69], v104 offset:32768
	ds_read_b128 v[70:73], v104 offset:34816
	ds_read_b128 v[74:77], v104 offset:36864
	ds_read_b128 v[78:81], v104 offset:38912
	v_mfma_f32_16x16x32_bf16 v[106:109], v[234:237], v[82:85], v[106:109]
	s_add_u32 m0, s4, 0x4000
	v_mfma_f32_16x16x32_bf16 v[122:125], v[238:241], v[82:85], v[122:125]
	global_load_lds_dwordx4 v98, s[28:29]
	v_mfma_f32_16x16x32_bf16 v[138:141], v[242:245], v[82:85], v[138:141]
	v_mfma_f32_16x16x32_bf16 v[162:165], v[246:249], v[82:85], v[162:165]
	v_mfma_f32_16x16x32_bf16 v[110:113], v[234:237], v[86:89], v[110:113]
	s_add_u32 m0, s4, 0x4400
	v_mfma_f32_16x16x32_bf16 v[126:129], v[238:241], v[86:89], v[126:129]
	global_load_lds_dwordx4 v99, s[28:29]
	v_mfma_f32_16x16x32_bf16 v[142:145], v[242:245], v[86:89], v[142:145]
	v_mfma_f32_16x16x32_bf16 v[166:169], v[246:249], v[86:89], v[166:169]
	v_mfma_f32_16x16x32_bf16 v[114:117], v[234:237], v[90:93], v[114:117]
	s_add_u32 m0, s4, 0x4800
	v_mfma_f32_16x16x32_bf16 v[130:133], v[238:241], v[90:93], v[130:133]
	global_load_lds_dwordx4 v100, s[28:29]
	v_mfma_f32_16x16x32_bf16 v[154:157], v[242:245], v[90:93], v[154:157]
	v_mfma_f32_16x16x32_bf16 v[170:173], v[246:249], v[90:93], v[170:173]
	v_mfma_f32_16x16x32_bf16 v[118:121], v[234:237], v[94:97], v[118:121]
	s_add_u32 m0, s4, 0x4c00
	v_mfma_f32_16x16x32_bf16 v[134:137], v[238:241], v[94:97], v[134:137]
	global_load_lds_dwordx4 v101, s[28:29]
	v_mfma_f32_16x16x32_bf16 v[158:161], v[242:245], v[94:97], v[158:161]
	v_mfma_f32_16x16x32_bf16 v[174:177], v[246:249], v[94:97], v[174:177]
	ds_read_b128 v[234:237], v103 offset:49152
	ds_read_b128 v[238:241], v103 offset:51200
	ds_read_b128 v[242:245], v103 offset:53248
	ds_read_b128 v[246:249], v103 offset:55296
	ds_read_b128 v[82:85], v105 offset:32768
	ds_read_b128 v[86:89], v105 offset:34816
	ds_read_b128 v[90:93], v105 offset:36864
	ds_read_b128 v[94:97], v105 offset:38912
	s_waitcnt lgkmcnt(8)
	v_mfma_f32_16x16x32_bf16 v[62:65], v[218:221], v[66:69], v[62:65]
	v_mfma_f32_16x16x32_bf16 v[46:49], v[222:225], v[66:69], v[46:49]
	v_mfma_f32_16x16x32_bf16 v[30:33], v[226:229], v[66:69], v[30:33]
	v_mfma_f32_16x16x32_bf16 v[14:17], v[230:233], v[66:69], v[14:17]
	v_mfma_f32_16x16x32_bf16 v[58:61], v[218:221], v[70:73], v[58:61]
	v_mfma_f32_16x16x32_bf16 v[42:45], v[222:225], v[70:73], v[42:45]
	v_mfma_f32_16x16x32_bf16 v[26:29], v[226:229], v[70:73], v[26:29]
	v_mfma_f32_16x16x32_bf16 v[10:13], v[230:233], v[70:73], v[10:13]
	v_mfma_f32_16x16x32_bf16 v[54:57], v[218:221], v[74:77], v[54:57]
	v_mfma_f32_16x16x32_bf16 v[38:41], v[222:225], v[74:77], v[38:41]
	v_mfma_f32_16x16x32_bf16 v[22:25], v[226:229], v[74:77], v[22:25]
	v_mfma_f32_16x16x32_bf16 v[6:9], v[230:233], v[74:77], v[6:9]
	v_mfma_f32_16x16x32_bf16 v[50:53], v[218:221], v[78:81], v[50:53]
	v_mfma_f32_16x16x32_bf16 v[34:37], v[222:225], v[78:81], v[34:37]
	v_mfma_f32_16x16x32_bf16 v[18:21], v[226:229], v[78:81], v[18:21]
	v_mfma_f32_16x16x32_bf16 v[2:5], v[230:233], v[78:81], v[2:5]
	s_waitcnt lgkmcnt(0)
	s_waitcnt vmcnt(8)
	s_barrier
	ds_read_b128 v[218:221], v102 offset:0
	ds_read_b128 v[222:225], v102 offset:2048
	ds_read_b128 v[226:229], v102 offset:4096
	ds_read_b128 v[230:233], v102 offset:6144
	v_mfma_f32_16x16x32_bf16 v[62:65], v[234:237], v[82:85], v[62:65]
	s_add_u32 m0, s4, 0xc000
	v_mfma_f32_16x16x32_bf16 v[46:49], v[238:241], v[82:85], v[46:49]
	global_load_lds_dwordx4 v98, s[6:7]
	v_mfma_f32_16x16x32_bf16 v[30:33], v[242:245], v[82:85], v[30:33]
	v_mfma_f32_16x16x32_bf16 v[14:17], v[246:249], v[82:85], v[14:17]
	v_mfma_f32_16x16x32_bf16 v[58:61], v[234:237], v[86:89], v[58:61]
	s_add_u32 m0, s4, 0xc400
	v_mfma_f32_16x16x32_bf16 v[42:45], v[238:241], v[86:89], v[42:45]
	global_load_lds_dwordx4 v99, s[6:7]
	v_mfma_f32_16x16x32_bf16 v[26:29], v[242:245], v[86:89], v[26:29]
	v_mfma_f32_16x16x32_bf16 v[10:13], v[246:249], v[86:89], v[10:13]
	v_mfma_f32_16x16x32_bf16 v[54:57], v[234:237], v[90:93], v[54:57]
	s_add_u32 m0, s4, 0xc800
	v_mfma_f32_16x16x32_bf16 v[38:41], v[238:241], v[90:93], v[38:41]
	global_load_lds_dwordx4 v100, s[6:7]
	v_mfma_f32_16x16x32_bf16 v[22:25], v[242:245], v[90:93], v[22:25]
	v_mfma_f32_16x16x32_bf16 v[6:9], v[246:249], v[90:93], v[6:9]
	v_mfma_f32_16x16x32_bf16 v[50:53], v[234:237], v[94:97], v[50:53]
	s_add_u32 m0, s4, 0xcc00
	v_mfma_f32_16x16x32_bf16 v[34:37], v[238:241], v[94:97], v[34:37]
	global_load_lds_dwordx4 v101, s[6:7]
	v_mfma_f32_16x16x32_bf16 v[18:21], v[242:245], v[94:97], v[18:21]
	v_mfma_f32_16x16x32_bf16 v[2:5], v[246:249], v[94:97], v[2:5]
	v_add_u32_e32 v98, 0x80, v98
	v_add_u32_e32 v99, 0x80, v99
	v_add_u32_e32 v100, 0x80, v100
	v_add_u32_e32 v101, 0x80, v101
	ds_read_b128 v[234:237], v103 offset:0
	ds_read_b128 v[238:241], v103 offset:2048
	ds_read_b128 v[242:245], v103 offset:4096
	ds_read_b128 v[246:249], v103 offset:6144
	s_waitcnt lgkmcnt(4)
	v_mfma_f32_16x16x32_bf16 v[106:109], v[218:221], v[66:69], v[106:109]
	s_add_u32 m0, s4, 0x8000
	v_mfma_f32_16x16x32_bf16 v[122:125], v[222:225], v[66:69], v[122:125]
	global_load_lds_dwordx4 v98, s[48:49]
	v_mfma_f32_16x16x32_bf16 v[138:141], v[226:229], v[66:69], v[138:141]
	v_mfma_f32_16x16x32_bf16 v[162:165], v[230:233], v[66:69], v[162:165]
	v_mfma_f32_16x16x32_bf16 v[110:113], v[218:221], v[70:73], v[110:113]
	s_add_u32 m0, s4, 0x8400
	v_mfma_f32_16x16x32_bf16 v[126:129], v[222:225], v[70:73], v[126:129]
	global_load_lds_dwordx4 v99, s[48:49]
	v_mfma_f32_16x16x32_bf16 v[142:145], v[226:229], v[70:73], v[142:145]
	v_mfma_f32_16x16x32_bf16 v[166:169], v[230:233], v[70:73], v[166:169]
	v_mfma_f32_16x16x32_bf16 v[114:117], v[218:221], v[74:77], v[114:117]
	s_add_u32 m0, s4, 0x8800
	v_mfma_f32_16x16x32_bf16 v[130:133], v[222:225], v[74:77], v[130:133]
	global_load_lds_dwordx4 v100, s[48:49]
	v_mfma_f32_16x16x32_bf16 v[154:157], v[226:229], v[74:77], v[154:157]
	v_mfma_f32_16x16x32_bf16 v[170:173], v[230:233], v[74:77], v[170:173]
	v_mfma_f32_16x16x32_bf16 v[118:121], v[218:221], v[78:81], v[118:121]
	s_add_u32 m0, s4, 0x8c00
	v_mfma_f32_16x16x32_bf16 v[134:137], v[222:225], v[78:81], v[134:137]
	global_load_lds_dwordx4 v101, s[48:49]
	v_mfma_f32_16x16x32_bf16 v[158:161], v[226:229], v[78:81], v[158:161]
	v_mfma_f32_16x16x32_bf16 v[174:177], v[230:233], v[78:81], v[174:177]
	s_waitcnt lgkmcnt(0)
	s_waitcnt vmcnt(8)
	s_barrier
	ds_read_b128 v[218:221], v102 offset:16384
	ds_read_b128 v[222:225], v102 offset:18432
	ds_read_b128 v[226:229], v102 offset:20480
	ds_read_b128 v[230:233], v102 offset:22528
	ds_read_b128 v[66:69], v250 offset:49152
	ds_read_b128 v[70:73], v250 offset:51200
	ds_read_b128 v[74:77], v250 offset:53248
	ds_read_b128 v[78:81], v250 offset:55296
	v_mfma_f32_16x16x32_bf16 v[106:109], v[234:237], v[82:85], v[106:109]
	s_add_u32 m0, s4, 0x0
	v_mfma_f32_16x16x32_bf16 v[122:125], v[238:241], v[82:85], v[122:125]
	global_load_lds_dwordx4 v98, s[28:29]
	v_mfma_f32_16x16x32_bf16 v[138:141], v[242:245], v[82:85], v[138:141]
	v_mfma_f32_16x16x32_bf16 v[162:165], v[246:249], v[82:85], v[162:165]
	v_mfma_f32_16x16x32_bf16 v[110:113], v[234:237], v[86:89], v[110:113]
	s_add_u32 m0, s4, 0x400
	v_mfma_f32_16x16x32_bf16 v[126:129], v[238:241], v[86:89], v[126:129]
	global_load_lds_dwordx4 v99, s[28:29]
	v_mfma_f32_16x16x32_bf16 v[142:145], v[242:245], v[86:89], v[142:145]
	v_mfma_f32_16x16x32_bf16 v[166:169], v[246:249], v[86:89], v[166:169]
	v_mfma_f32_16x16x32_bf16 v[114:117], v[234:237], v[90:93], v[114:117]
	s_add_u32 m0, s4, 0x800
	v_mfma_f32_16x16x32_bf16 v[130:133], v[238:241], v[90:93], v[130:133]
	global_load_lds_dwordx4 v100, s[28:29]
	v_mfma_f32_16x16x32_bf16 v[154:157], v[242:245], v[90:93], v[154:157]
	v_mfma_f32_16x16x32_bf16 v[170:173], v[246:249], v[90:93], v[170:173]
	v_mfma_f32_16x16x32_bf16 v[118:121], v[234:237], v[94:97], v[118:121]
	s_add_u32 m0, s4, 0xc00
	v_mfma_f32_16x16x32_bf16 v[134:137], v[238:241], v[94:97], v[134:137]
	global_load_lds_dwordx4 v101, s[28:29]
	v_mfma_f32_16x16x32_bf16 v[158:161], v[242:245], v[94:97], v[158:161]
	v_mfma_f32_16x16x32_bf16 v[174:177], v[246:249], v[94:97], v[174:177]
	ds_read_b128 v[234:237], v103 offset:16384
	ds_read_b128 v[238:241], v103 offset:18432
	ds_read_b128 v[242:245], v103 offset:20480
	ds_read_b128 v[246:249], v103 offset:22528
	ds_read_b128 v[82:85], v251 offset:49152
	ds_read_b128 v[86:89], v251 offset:51200
	ds_read_b128 v[90:93], v251 offset:53248
	ds_read_b128 v[94:97], v251 offset:55296
	s_waitcnt lgkmcnt(8)
	v_mfma_f32_16x16x32_bf16 v[62:65], v[218:221], v[66:69], v[62:65]
	v_mfma_f32_16x16x32_bf16 v[46:49], v[222:225], v[66:69], v[46:49]
	v_mfma_f32_16x16x32_bf16 v[30:33], v[226:229], v[66:69], v[30:33]
	v_mfma_f32_16x16x32_bf16 v[14:17], v[230:233], v[66:69], v[14:17]
	v_mfma_f32_16x16x32_bf16 v[58:61], v[218:221], v[70:73], v[58:61]
	v_mfma_f32_16x16x32_bf16 v[42:45], v[222:225], v[70:73], v[42:45]
	v_mfma_f32_16x16x32_bf16 v[26:29], v[226:229], v[70:73], v[26:29]
	v_mfma_f32_16x16x32_bf16 v[10:13], v[230:233], v[70:73], v[10:13]
	v_mfma_f32_16x16x32_bf16 v[54:57], v[218:221], v[74:77], v[54:57]
	v_mfma_f32_16x16x32_bf16 v[38:41], v[222:225], v[74:77], v[38:41]
	v_mfma_f32_16x16x32_bf16 v[22:25], v[226:229], v[74:77], v[22:25]
	v_mfma_f32_16x16x32_bf16 v[6:9], v[230:233], v[74:77], v[6:9]
	v_mfma_f32_16x16x32_bf16 v[50:53], v[218:221], v[78:81], v[50:53]
	v_mfma_f32_16x16x32_bf16 v[34:37], v[222:225], v[78:81], v[34:37]
	v_mfma_f32_16x16x32_bf16 v[18:21], v[226:229], v[78:81], v[18:21]
	v_mfma_f32_16x16x32_bf16 v[2:5], v[230:233], v[78:81], v[2:5]
	s_waitcnt lgkmcnt(0)
	s_waitcnt vmcnt(8)
	s_barrier
	ds_read_b128 v[218:221], v102 offset:49152
	ds_read_b128 v[222:225], v102 offset:51200
	ds_read_b128 v[226:229], v102 offset:53248
	ds_read_b128 v[230:233], v102 offset:55296
	v_mfma_f32_16x16x32_bf16 v[62:65], v[234:237], v[82:85], v[62:65]
	s_add_u32 m0, s4, 0x4000
	v_mfma_f32_16x16x32_bf16 v[46:49], v[238:241], v[82:85], v[46:49]
	global_load_lds_dwordx4 v98, s[6:7]
	v_mfma_f32_16x16x32_bf16 v[30:33], v[242:245], v[82:85], v[30:33]
	v_mfma_f32_16x16x32_bf16 v[14:17], v[246:249], v[82:85], v[14:17]
	v_mfma_f32_16x16x32_bf16 v[58:61], v[234:237], v[86:89], v[58:61]
	s_add_u32 m0, s4, 0x4400
	v_mfma_f32_16x16x32_bf16 v[42:45], v[238:241], v[86:89], v[42:45]
	global_load_lds_dwordx4 v99, s[6:7]
	v_mfma_f32_16x16x32_bf16 v[26:29], v[242:245], v[86:89], v[26:29]
	v_mfma_f32_16x16x32_bf16 v[10:13], v[246:249], v[86:89], v[10:13]
	v_mfma_f32_16x16x32_bf16 v[54:57], v[234:237], v[90:93], v[54:57]
	s_add_u32 m0, s4, 0x4800
	v_mfma_f32_16x16x32_bf16 v[38:41], v[238:241], v[90:93], v[38:41]
	global_load_lds_dwordx4 v100, s[6:7]
	v_mfma_f32_16x16x32_bf16 v[22:25], v[242:245], v[90:93], v[22:25]
	v_mfma_f32_16x16x32_bf16 v[6:9], v[246:249], v[90:93], v[6:9]
	v_mfma_f32_16x16x32_bf16 v[50:53], v[234:237], v[94:97], v[50:53]
	s_add_u32 m0, s4, 0x4c00
	v_mfma_f32_16x16x32_bf16 v[34:37], v[238:241], v[94:97], v[34:37]
	global_load_lds_dwordx4 v101, s[6:7]
	v_mfma_f32_16x16x32_bf16 v[18:21], v[242:245], v[94:97], v[18:21]
	v_mfma_f32_16x16x32_bf16 v[2:5], v[246:249], v[94:97], v[2:5]
	v_add_u32_e32 v98, 0x80, v98
	v_add_u32_e32 v99, 0x80, v99
	v_add_u32_e32 v100, 0x80, v100
	v_add_u32_e32 v101, 0x80, v101
	ds_read_b128 v[234:237], v103 offset:49152
	ds_read_b128 v[238:241], v103 offset:51200
	ds_read_b128 v[242:245], v103 offset:53248
	ds_read_b128 v[246:249], v103 offset:55296
	s_waitcnt lgkmcnt(4)
	v_mfma_f32_16x16x32_bf16 v[106:109], v[218:221], v[66:69], v[106:109]
	s_add_u32 m0, s4, 0x10000
	v_mfma_f32_16x16x32_bf16 v[122:125], v[222:225], v[66:69], v[122:125]
	global_load_lds_dwordx4 v98, s[48:49]
	v_mfma_f32_16x16x32_bf16 v[138:141], v[226:229], v[66:69], v[138:141]
	v_mfma_f32_16x16x32_bf16 v[162:165], v[230:233], v[66:69], v[162:165]
	v_mfma_f32_16x16x32_bf16 v[110:113], v[218:221], v[70:73], v[110:113]
	s_add_u32 m0, s4, 0x10400
	v_mfma_f32_16x16x32_bf16 v[126:129], v[222:225], v[70:73], v[126:129]
	global_load_lds_dwordx4 v99, s[48:49]
	v_mfma_f32_16x16x32_bf16 v[142:145], v[226:229], v[70:73], v[142:145]
	v_mfma_f32_16x16x32_bf16 v[166:169], v[230:233], v[70:73], v[166:169]
	v_mfma_f32_16x16x32_bf16 v[114:117], v[218:221], v[74:77], v[114:117]
	s_add_u32 m0, s4, 0x10800
	v_mfma_f32_16x16x32_bf16 v[130:133], v[222:225], v[74:77], v[130:133]
	global_load_lds_dwordx4 v100, s[48:49]
	v_mfma_f32_16x16x32_bf16 v[154:157], v[226:229], v[74:77], v[154:157]
	v_mfma_f32_16x16x32_bf16 v[170:173], v[230:233], v[74:77], v[170:173]
	v_mfma_f32_16x16x32_bf16 v[118:121], v[218:221], v[78:81], v[118:121]
	s_add_u32 m0, s4, 0x10c00
	v_mfma_f32_16x16x32_bf16 v[134:137], v[222:225], v[78:81], v[134:137]
	global_load_lds_dwordx4 v101, s[48:49]
	v_mfma_f32_16x16x32_bf16 v[158:161], v[226:229], v[78:81], v[158:161]
	v_mfma_f32_16x16x32_bf16 v[174:177], v[230:233], v[78:81], v[174:177]
	s_waitcnt lgkmcnt(0)
	s_waitcnt vmcnt(8)
	s_barrier
	ds_read_b128 v[218:221], v102 offset:0
	ds_read_b128 v[222:225], v102 offset:2048
	ds_read_b128 v[226:229], v102 offset:4096
	ds_read_b128 v[230:233], v102 offset:6144
	ds_read_b128 v[66:69], v104 offset:32768
	ds_read_b128 v[70:73], v104 offset:34816
	ds_read_b128 v[74:77], v104 offset:36864
	ds_read_b128 v[78:81], v104 offset:38912
	v_mfma_f32_16x16x32_bf16 v[106:109], v[234:237], v[82:85], v[106:109]
	s_add_u32 m0, s4, 0xc000
	v_mfma_f32_16x16x32_bf16 v[122:125], v[238:241], v[82:85], v[122:125]
	global_load_lds_dwordx4 v98, s[28:29]
	v_mfma_f32_16x16x32_bf16 v[138:141], v[242:245], v[82:85], v[138:141]
	v_mfma_f32_16x16x32_bf16 v[162:165], v[246:249], v[82:85], v[162:165]
	v_mfma_f32_16x16x32_bf16 v[110:113], v[234:237], v[86:89], v[110:113]
	s_add_u32 m0, s4, 0xc400
	v_mfma_f32_16x16x32_bf16 v[126:129], v[238:241], v[86:89], v[126:129]
	global_load_lds_dwordx4 v99, s[28:29]
	v_mfma_f32_16x16x32_bf16 v[142:145], v[242:245], v[86:89], v[142:145]
	v_mfma_f32_16x16x32_bf16 v[166:169], v[246:249], v[86:89], v[166:169]
	v_mfma_f32_16x16x32_bf16 v[114:117], v[234:237], v[90:93], v[114:117]
	s_add_u32 m0, s4, 0xc800
	v_mfma_f32_16x16x32_bf16 v[130:133], v[238:241], v[90:93], v[130:133]
	global_load_lds_dwordx4 v100, s[28:29]
	v_mfma_f32_16x16x32_bf16 v[154:157], v[242:245], v[90:93], v[154:157]
	v_mfma_f32_16x16x32_bf16 v[170:173], v[246:249], v[90:93], v[170:173]
	v_mfma_f32_16x16x32_bf16 v[118:121], v[234:237], v[94:97], v[118:121]
	s_add_u32 m0, s4, 0xcc00
	v_mfma_f32_16x16x32_bf16 v[134:137], v[238:241], v[94:97], v[134:137]
	global_load_lds_dwordx4 v101, s[28:29]
	v_mfma_f32_16x16x32_bf16 v[158:161], v[242:245], v[94:97], v[158:161]
	v_mfma_f32_16x16x32_bf16 v[174:177], v[246:249], v[94:97], v[174:177]
	ds_read_b128 v[234:237], v103 offset:0
	ds_read_b128 v[238:241], v103 offset:2048
	ds_read_b128 v[242:245], v103 offset:4096
	ds_read_b128 v[246:249], v103 offset:6144
	ds_read_b128 v[82:85], v105 offset:32768
	ds_read_b128 v[86:89], v105 offset:34816
	ds_read_b128 v[90:93], v105 offset:36864
	ds_read_b128 v[94:97], v105 offset:38912
	s_waitcnt lgkmcnt(8)
	v_mfma_f32_16x16x32_bf16 v[62:65], v[218:221], v[66:69], v[62:65]
	v_mfma_f32_16x16x32_bf16 v[46:49], v[222:225], v[66:69], v[46:49]
	v_mfma_f32_16x16x32_bf16 v[30:33], v[226:229], v[66:69], v[30:33]
	v_mfma_f32_16x16x32_bf16 v[14:17], v[230:233], v[66:69], v[14:17]
	v_mfma_f32_16x16x32_bf16 v[58:61], v[218:221], v[70:73], v[58:61]
	v_mfma_f32_16x16x32_bf16 v[42:45], v[222:225], v[70:73], v[42:45]
	v_mfma_f32_16x16x32_bf16 v[26:29], v[226:229], v[70:73], v[26:29]
	v_mfma_f32_16x16x32_bf16 v[10:13], v[230:233], v[70:73], v[10:13]
	v_mfma_f32_16x16x32_bf16 v[54:57], v[218:221], v[74:77], v[54:57]
	v_mfma_f32_16x16x32_bf16 v[38:41], v[222:225], v[74:77], v[38:41]
	v_mfma_f32_16x16x32_bf16 v[22:25], v[226:229], v[74:77], v[22:25]
	v_mfma_f32_16x16x32_bf16 v[6:9], v[230:233], v[74:77], v[6:9]
	v_mfma_f32_16x16x32_bf16 v[50:53], v[218:221], v[78:81], v[50:53]
	v_mfma_f32_16x16x32_bf16 v[34:37], v[222:225], v[78:81], v[34:37]
	v_mfma_f32_16x16x32_bf16 v[18:21], v[226:229], v[78:81], v[18:21]
	v_mfma_f32_16x16x32_bf16 v[2:5], v[230:233], v[78:81], v[2:5]
	s_waitcnt lgkmcnt(0)
	s_waitcnt vmcnt(8)
	s_barrier
	ds_read_b128 v[218:221], v102 offset:16384
	ds_read_b128 v[222:225], v102 offset:18432
	ds_read_b128 v[226:229], v102 offset:20480
	ds_read_b128 v[230:233], v102 offset:22528
	v_mfma_f32_16x16x32_bf16 v[62:65], v[234:237], v[82:85], v[62:65]
	s_add_u32 m0, s4, 0x0
	v_mfma_f32_16x16x32_bf16 v[46:49], v[238:241], v[82:85], v[46:49]
	global_load_lds_dwordx4 v98, s[6:7]
	v_mfma_f32_16x16x32_bf16 v[30:33], v[242:245], v[82:85], v[30:33]
	v_mfma_f32_16x16x32_bf16 v[14:17], v[246:249], v[82:85], v[14:17]
	v_mfma_f32_16x16x32_bf16 v[58:61], v[234:237], v[86:89], v[58:61]
	s_add_u32 m0, s4, 0x400
	v_mfma_f32_16x16x32_bf16 v[42:45], v[238:241], v[86:89], v[42:45]
	global_load_lds_dwordx4 v99, s[6:7]
	v_mfma_f32_16x16x32_bf16 v[26:29], v[242:245], v[86:89], v[26:29]
	v_mfma_f32_16x16x32_bf16 v[10:13], v[246:249], v[86:89], v[10:13]
	v_mfma_f32_16x16x32_bf16 v[54:57], v[234:237], v[90:93], v[54:57]
	s_add_u32 m0, s4, 0x800
	v_mfma_f32_16x16x32_bf16 v[38:41], v[238:241], v[90:93], v[38:41]
	global_load_lds_dwordx4 v100, s[6:7]
	v_mfma_f32_16x16x32_bf16 v[22:25], v[242:245], v[90:93], v[22:25]
	v_mfma_f32_16x16x32_bf16 v[6:9], v[246:249], v[90:93], v[6:9]
	v_mfma_f32_16x16x32_bf16 v[50:53], v[234:237], v[94:97], v[50:53]
	s_add_u32 m0, s4, 0xc00
	v_mfma_f32_16x16x32_bf16 v[34:37], v[238:241], v[94:97], v[34:37]
	global_load_lds_dwordx4 v101, s[6:7]
	v_mfma_f32_16x16x32_bf16 v[18:21], v[242:245], v[94:97], v[18:21]
	v_mfma_f32_16x16x32_bf16 v[2:5], v[246:249], v[94:97], v[2:5]
	v_add_u32_e32 v98, 0x80, v98
	v_add_u32_e32 v99, 0x80, v99
	v_add_u32_e32 v100, 0x80, v100
	v_add_u32_e32 v101, 0x80, v101
	ds_read_b128 v[234:237], v103 offset:16384
	ds_read_b128 v[238:241], v103 offset:18432
	ds_read_b128 v[242:245], v103 offset:20480
	ds_read_b128 v[246:249], v103 offset:22528
	s_waitcnt lgkmcnt(4)
	v_mfma_f32_16x16x32_bf16 v[106:109], v[218:221], v[66:69], v[106:109]
	s_add_u32 m0, s4, 0x8000
	v_mfma_f32_16x16x32_bf16 v[122:125], v[222:225], v[66:69], v[122:125]
	global_load_lds_dwordx4 v98, s[48:49]
	v_mfma_f32_16x16x32_bf16 v[138:141], v[226:229], v[66:69], v[138:141]
	v_mfma_f32_16x16x32_bf16 v[162:165], v[230:233], v[66:69], v[162:165]
	v_mfma_f32_16x16x32_bf16 v[110:113], v[218:221], v[70:73], v[110:113]
	s_add_u32 m0, s4, 0x8400
	v_mfma_f32_16x16x32_bf16 v[126:129], v[222:225], v[70:73], v[126:129]
	global_load_lds_dwordx4 v99, s[48:49]
	v_mfma_f32_16x16x32_bf16 v[142:145], v[226:229], v[70:73], v[142:145]
	v_mfma_f32_16x16x32_bf16 v[166:169], v[230:233], v[70:73], v[166:169]
	v_mfma_f32_16x16x32_bf16 v[114:117], v[218:221], v[74:77], v[114:117]
	s_add_u32 m0, s4, 0x8800
	v_mfma_f32_16x16x32_bf16 v[130:133], v[222:225], v[74:77], v[130:133]
	global_load_lds_dwordx4 v100, s[48:49]
	v_mfma_f32_16x16x32_bf16 v[154:157], v[226:229], v[74:77], v[154:157]
	v_mfma_f32_16x16x32_bf16 v[170:173], v[230:233], v[74:77], v[170:173]
	v_mfma_f32_16x16x32_bf16 v[118:121], v[218:221], v[78:81], v[118:121]
	s_add_u32 m0, s4, 0x8c00
	v_mfma_f32_16x16x32_bf16 v[134:137], v[222:225], v[78:81], v[134:137]
	global_load_lds_dwordx4 v101, s[48:49]
	v_mfma_f32_16x16x32_bf16 v[158:161], v[226:229], v[78:81], v[158:161]
	v_mfma_f32_16x16x32_bf16 v[174:177], v[230:233], v[78:81], v[174:177]
	s_waitcnt lgkmcnt(0)
	s_waitcnt vmcnt(8)
	s_barrier
	ds_read_b128 v[218:221], v102 offset:49152
	ds_read_b128 v[222:225], v102 offset:51200
	ds_read_b128 v[226:229], v102 offset:53248
	ds_read_b128 v[230:233], v102 offset:55296
	ds_read_b128 v[66:69], v250 offset:49152
	ds_read_b128 v[70:73], v250 offset:51200
	ds_read_b128 v[74:77], v250 offset:53248
	ds_read_b128 v[78:81], v250 offset:55296
	v_mfma_f32_16x16x32_bf16 v[106:109], v[234:237], v[82:85], v[106:109]
	s_add_u32 m0, s4, 0x4000
	v_mfma_f32_16x16x32_bf16 v[122:125], v[238:241], v[82:85], v[122:125]
	global_load_lds_dwordx4 v98, s[28:29]
	v_mfma_f32_16x16x32_bf16 v[138:141], v[242:245], v[82:85], v[138:141]
	v_mfma_f32_16x16x32_bf16 v[162:165], v[246:249], v[82:85], v[162:165]
	v_mfma_f32_16x16x32_bf16 v[110:113], v[234:237], v[86:89], v[110:113]
	s_add_u32 m0, s4, 0x4400
	v_mfma_f32_16x16x32_bf16 v[126:129], v[238:241], v[86:89], v[126:129]
	global_load_lds_dwordx4 v99, s[28:29]
	v_mfma_f32_16x16x32_bf16 v[142:145], v[242:245], v[86:89], v[142:145]
	v_mfma_f32_16x16x32_bf16 v[166:169], v[246:249], v[86:89], v[166:169]
	v_mfma_f32_16x16x32_bf16 v[114:117], v[234:237], v[90:93], v[114:117]
	s_add_u32 m0, s4, 0x4800
	v_mfma_f32_16x16x32_bf16 v[130:133], v[238:241], v[90:93], v[130:133]
	global_load_lds_dwordx4 v100, s[28:29]
	v_mfma_f32_16x16x32_bf16 v[154:157], v[242:245], v[90:93], v[154:157]
	v_mfma_f32_16x16x32_bf16 v[170:173], v[246:249], v[90:93], v[170:173]
	v_mfma_f32_16x16x32_bf16 v[118:121], v[234:237], v[94:97], v[118:121]
	s_add_u32 m0, s4, 0x4c00
	v_mfma_f32_16x16x32_bf16 v[134:137], v[238:241], v[94:97], v[134:137]
	global_load_lds_dwordx4 v101, s[28:29]
	v_mfma_f32_16x16x32_bf16 v[158:161], v[242:245], v[94:97], v[158:161]
	v_mfma_f32_16x16x32_bf16 v[174:177], v[246:249], v[94:97], v[174:177]
	ds_read_b128 v[234:237], v103 offset:49152
	ds_read_b128 v[238:241], v103 offset:51200
	ds_read_b128 v[242:245], v103 offset:53248
	ds_read_b128 v[246:249], v103 offset:55296
	ds_read_b128 v[82:85], v251 offset:49152
	ds_read_b128 v[86:89], v251 offset:51200
	ds_read_b128 v[90:93], v251 offset:53248
	ds_read_b128 v[94:97], v251 offset:55296
	s_waitcnt lgkmcnt(8)
	v_mfma_f32_16x16x32_bf16 v[62:65], v[218:221], v[66:69], v[62:65]
	v_mfma_f32_16x16x32_bf16 v[46:49], v[222:225], v[66:69], v[46:49]
	v_mfma_f32_16x16x32_bf16 v[30:33], v[226:229], v[66:69], v[30:33]
	v_mfma_f32_16x16x32_bf16 v[14:17], v[230:233], v[66:69], v[14:17]
	v_mfma_f32_16x16x32_bf16 v[58:61], v[218:221], v[70:73], v[58:61]
	v_mfma_f32_16x16x32_bf16 v[42:45], v[222:225], v[70:73], v[42:45]
	v_mfma_f32_16x16x32_bf16 v[26:29], v[226:229], v[70:73], v[26:29]
	v_mfma_f32_16x16x32_bf16 v[10:13], v[230:233], v[70:73], v[10:13]
	v_mfma_f32_16x16x32_bf16 v[54:57], v[218:221], v[74:77], v[54:57]
	v_mfma_f32_16x16x32_bf16 v[38:41], v[222:225], v[74:77], v[38:41]
	v_mfma_f32_16x16x32_bf16 v[22:25], v[226:229], v[74:77], v[22:25]
	v_mfma_f32_16x16x32_bf16 v[6:9], v[230:233], v[74:77], v[6:9]
	v_mfma_f32_16x16x32_bf16 v[50:53], v[218:221], v[78:81], v[50:53]
	v_mfma_f32_16x16x32_bf16 v[34:37], v[222:225], v[78:81], v[34:37]
	v_mfma_f32_16x16x32_bf16 v[18:21], v[226:229], v[78:81], v[18:21]
	v_mfma_f32_16x16x32_bf16 v[2:5], v[230:233], v[78:81], v[2:5]
	s_waitcnt lgkmcnt(0)
	s_waitcnt vmcnt(8)
	s_barrier
	ds_read_b128 v[218:221], v102 offset:0
	ds_read_b128 v[222:225], v102 offset:2048
	ds_read_b128 v[226:229], v102 offset:4096
	ds_read_b128 v[230:233], v102 offset:6144
	v_mfma_f32_16x16x32_bf16 v[62:65], v[234:237], v[82:85], v[62:65]
	s_add_u32 m0, s4, 0xc000
	v_mfma_f32_16x16x32_bf16 v[46:49], v[238:241], v[82:85], v[46:49]
	global_load_lds_dwordx4 v98, s[6:7]
	v_mfma_f32_16x16x32_bf16 v[30:33], v[242:245], v[82:85], v[30:33]
	v_mfma_f32_16x16x32_bf16 v[14:17], v[246:249], v[82:85], v[14:17]
	v_mfma_f32_16x16x32_bf16 v[58:61], v[234:237], v[86:89], v[58:61]
	s_add_u32 m0, s4, 0xc400
	v_mfma_f32_16x16x32_bf16 v[42:45], v[238:241], v[86:89], v[42:45]
	global_load_lds_dwordx4 v99, s[6:7]
	v_mfma_f32_16x16x32_bf16 v[26:29], v[242:245], v[86:89], v[26:29]
	v_mfma_f32_16x16x32_bf16 v[10:13], v[246:249], v[86:89], v[10:13]
	v_mfma_f32_16x16x32_bf16 v[54:57], v[234:237], v[90:93], v[54:57]
	s_add_u32 m0, s4, 0xc800
	v_mfma_f32_16x16x32_bf16 v[38:41], v[238:241], v[90:93], v[38:41]
	global_load_lds_dwordx4 v100, s[6:7]
	v_mfma_f32_16x16x32_bf16 v[22:25], v[242:245], v[90:93], v[22:25]
	v_mfma_f32_16x16x32_bf16 v[6:9], v[246:249], v[90:93], v[6:9]
	v_mfma_f32_16x16x32_bf16 v[50:53], v[234:237], v[94:97], v[50:53]
	s_add_u32 m0, s4, 0xcc00
	v_mfma_f32_16x16x32_bf16 v[34:37], v[238:241], v[94:97], v[34:37]
	global_load_lds_dwordx4 v101, s[6:7]
	v_mfma_f32_16x16x32_bf16 v[18:21], v[242:245], v[94:97], v[18:21]
	v_mfma_f32_16x16x32_bf16 v[2:5], v[246:249], v[94:97], v[2:5]
	v_add_u32_e32 v98, 0x80, v98
	v_add_u32_e32 v99, 0x80, v99
	v_add_u32_e32 v100, 0x80, v100
	v_add_u32_e32 v101, 0x80, v101
	ds_read_b128 v[234:237], v103 offset:0
	ds_read_b128 v[238:241], v103 offset:2048
	ds_read_b128 v[242:245], v103 offset:4096
	ds_read_b128 v[246:249], v103 offset:6144
	s_waitcnt lgkmcnt(4)
	v_mfma_f32_16x16x32_bf16 v[106:109], v[218:221], v[66:69], v[106:109]
	s_add_u32 m0, s4, 0x10000
	v_mfma_f32_16x16x32_bf16 v[122:125], v[222:225], v[66:69], v[122:125]
	global_load_lds_dwordx4 v98, s[48:49]
	v_mfma_f32_16x16x32_bf16 v[138:141], v[226:229], v[66:69], v[138:141]
	v_mfma_f32_16x16x32_bf16 v[162:165], v[230:233], v[66:69], v[162:165]
	v_mfma_f32_16x16x32_bf16 v[110:113], v[218:221], v[70:73], v[110:113]
	s_add_u32 m0, s4, 0x10400
	v_mfma_f32_16x16x32_bf16 v[126:129], v[222:225], v[70:73], v[126:129]
	global_load_lds_dwordx4 v99, s[48:49]
	v_mfma_f32_16x16x32_bf16 v[142:145], v[226:229], v[70:73], v[142:145]
	v_mfma_f32_16x16x32_bf16 v[166:169], v[230:233], v[70:73], v[166:169]
	v_mfma_f32_16x16x32_bf16 v[114:117], v[218:221], v[74:77], v[114:117]
	s_add_u32 m0, s4, 0x10800
	v_mfma_f32_16x16x32_bf16 v[130:133], v[222:225], v[74:77], v[130:133]
	global_load_lds_dwordx4 v100, s[48:49]
	v_mfma_f32_16x16x32_bf16 v[154:157], v[226:229], v[74:77], v[154:157]
	v_mfma_f32_16x16x32_bf16 v[170:173], v[230:233], v[74:77], v[170:173]
	v_mfma_f32_16x16x32_bf16 v[118:121], v[218:221], v[78:81], v[118:121]
	s_add_u32 m0, s4, 0x10c00
	v_mfma_f32_16x16x32_bf16 v[134:137], v[222:225], v[78:81], v[134:137]
	global_load_lds_dwordx4 v101, s[48:49]
	v_mfma_f32_16x16x32_bf16 v[158:161], v[226:229], v[78:81], v[158:161]
	v_mfma_f32_16x16x32_bf16 v[174:177], v[230:233], v[78:81], v[174:177]
	s_waitcnt lgkmcnt(0)
	s_waitcnt vmcnt(8)
	s_barrier
	ds_read_b128 v[218:221], v102 offset:16384
	ds_read_b128 v[222:225], v102 offset:18432
	ds_read_b128 v[226:229], v102 offset:20480
	ds_read_b128 v[230:233], v102 offset:22528
	ds_read_b128 v[66:69], v104 offset:32768
	ds_read_b128 v[70:73], v104 offset:34816
	ds_read_b128 v[74:77], v104 offset:36864
	ds_read_b128 v[78:81], v104 offset:38912
	v_mfma_f32_16x16x32_bf16 v[106:109], v[234:237], v[82:85], v[106:109]
	s_add_u32 m0, s4, 0x0
	v_mfma_f32_16x16x32_bf16 v[122:125], v[238:241], v[82:85], v[122:125]
	global_load_lds_dwordx4 v98, s[28:29]
	v_mfma_f32_16x16x32_bf16 v[138:141], v[242:245], v[82:85], v[138:141]
	v_mfma_f32_16x16x32_bf16 v[162:165], v[246:249], v[82:85], v[162:165]
	v_mfma_f32_16x16x32_bf16 v[110:113], v[234:237], v[86:89], v[110:113]
	s_add_u32 m0, s4, 0x400
	v_mfma_f32_16x16x32_bf16 v[126:129], v[238:241], v[86:89], v[126:129]
	global_load_lds_dwordx4 v99, s[28:29]
	v_mfma_f32_16x16x32_bf16 v[142:145], v[242:245], v[86:89], v[142:145]
	v_mfma_f32_16x16x32_bf16 v[166:169], v[246:249], v[86:89], v[166:169]
	v_mfma_f32_16x16x32_bf16 v[114:117], v[234:237], v[90:93], v[114:117]
	s_add_u32 m0, s4, 0x800
	v_mfma_f32_16x16x32_bf16 v[130:133], v[238:241], v[90:93], v[130:133]
	global_load_lds_dwordx4 v100, s[28:29]
	v_mfma_f32_16x16x32_bf16 v[154:157], v[242:245], v[90:93], v[154:157]
	v_mfma_f32_16x16x32_bf16 v[170:173], v[246:249], v[90:93], v[170:173]
	v_mfma_f32_16x16x32_bf16 v[118:121], v[234:237], v[94:97], v[118:121]
	s_add_u32 m0, s4, 0xc00
	v_mfma_f32_16x16x32_bf16 v[134:137], v[238:241], v[94:97], v[134:137]
	global_load_lds_dwordx4 v101, s[28:29]
	v_mfma_f32_16x16x32_bf16 v[158:161], v[242:245], v[94:97], v[158:161]
	v_mfma_f32_16x16x32_bf16 v[174:177], v[246:249], v[94:97], v[174:177]
	ds_read_b128 v[234:237], v103 offset:16384
	ds_read_b128 v[238:241], v103 offset:18432
	ds_read_b128 v[242:245], v103 offset:20480
	ds_read_b128 v[246:249], v103 offset:22528
	ds_read_b128 v[82:85], v105 offset:32768
	ds_read_b128 v[86:89], v105 offset:34816
	ds_read_b128 v[90:93], v105 offset:36864
	ds_read_b128 v[94:97], v105 offset:38912
	s_waitcnt lgkmcnt(8)
	v_mfma_f32_16x16x32_bf16 v[62:65], v[218:221], v[66:69], v[62:65]
	v_mfma_f32_16x16x32_bf16 v[46:49], v[222:225], v[66:69], v[46:49]
	v_mfma_f32_16x16x32_bf16 v[30:33], v[226:229], v[66:69], v[30:33]
	v_mfma_f32_16x16x32_bf16 v[14:17], v[230:233], v[66:69], v[14:17]
	v_mfma_f32_16x16x32_bf16 v[58:61], v[218:221], v[70:73], v[58:61]
	v_mfma_f32_16x16x32_bf16 v[42:45], v[222:225], v[70:73], v[42:45]
	v_mfma_f32_16x16x32_bf16 v[26:29], v[226:229], v[70:73], v[26:29]
	v_mfma_f32_16x16x32_bf16 v[10:13], v[230:233], v[70:73], v[10:13]
	v_mfma_f32_16x16x32_bf16 v[54:57], v[218:221], v[74:77], v[54:57]
	v_mfma_f32_16x16x32_bf16 v[38:41], v[222:225], v[74:77], v[38:41]
	v_mfma_f32_16x16x32_bf16 v[22:25], v[226:229], v[74:77], v[22:25]
	v_mfma_f32_16x16x32_bf16 v[6:9], v[230:233], v[74:77], v[6:9]
	v_mfma_f32_16x16x32_bf16 v[50:53], v[218:221], v[78:81], v[50:53]
	v_mfma_f32_16x16x32_bf16 v[34:37], v[222:225], v[78:81], v[34:37]
	v_mfma_f32_16x16x32_bf16 v[18:21], v[226:229], v[78:81], v[18:21]
	v_mfma_f32_16x16x32_bf16 v[2:5], v[230:233], v[78:81], v[2:5]
	s_waitcnt lgkmcnt(0)
	s_waitcnt vmcnt(8)
	s_barrier
	ds_read_b128 v[218:221], v102 offset:49152
	ds_read_b128 v[222:225], v102 offset:51200
	ds_read_b128 v[226:229], v102 offset:53248
	ds_read_b128 v[230:233], v102 offset:55296
	v_mfma_f32_16x16x32_bf16 v[62:65], v[234:237], v[82:85], v[62:65]
	s_add_u32 m0, s4, 0x4000
	v_mfma_f32_16x16x32_bf16 v[46:49], v[238:241], v[82:85], v[46:49]
	global_load_lds_dwordx4 v98, s[6:7]
	v_mfma_f32_16x16x32_bf16 v[30:33], v[242:245], v[82:85], v[30:33]
	v_mfma_f32_16x16x32_bf16 v[14:17], v[246:249], v[82:85], v[14:17]
	v_mfma_f32_16x16x32_bf16 v[58:61], v[234:237], v[86:89], v[58:61]
	s_add_u32 m0, s4, 0x4400
	v_mfma_f32_16x16x32_bf16 v[42:45], v[238:241], v[86:89], v[42:45]
	global_load_lds_dwordx4 v99, s[6:7]
	v_mfma_f32_16x16x32_bf16 v[26:29], v[242:245], v[86:89], v[26:29]
	v_mfma_f32_16x16x32_bf16 v[10:13], v[246:249], v[86:89], v[10:13]
	v_mfma_f32_16x16x32_bf16 v[54:57], v[234:237], v[90:93], v[54:57]
	s_add_u32 m0, s4, 0x4800
	v_mfma_f32_16x16x32_bf16 v[38:41], v[238:241], v[90:93], v[38:41]
	global_load_lds_dwordx4 v100, s[6:7]
	v_mfma_f32_16x16x32_bf16 v[22:25], v[242:245], v[90:93], v[22:25]
	v_mfma_f32_16x16x32_bf16 v[6:9], v[246:249], v[90:93], v[6:9]
	v_mfma_f32_16x16x32_bf16 v[50:53], v[234:237], v[94:97], v[50:53]
	s_add_u32 m0, s4, 0x4c00
	v_mfma_f32_16x16x32_bf16 v[34:37], v[238:241], v[94:97], v[34:37]
	global_load_lds_dwordx4 v101, s[6:7]
	v_mfma_f32_16x16x32_bf16 v[18:21], v[242:245], v[94:97], v[18:21]
	v_mfma_f32_16x16x32_bf16 v[2:5], v[246:249], v[94:97], v[2:5]
	v_add_u32_e32 v98, 0x80, v98
	v_add_u32_e32 v99, 0x80, v99
	v_add_u32_e32 v100, 0x80, v100
	v_add_u32_e32 v101, 0x80, v101
	ds_read_b128 v[234:237], v103 offset:49152
	ds_read_b128 v[238:241], v103 offset:51200
	ds_read_b128 v[242:245], v103 offset:53248
	ds_read_b128 v[246:249], v103 offset:55296
	s_waitcnt lgkmcnt(4)
	v_mfma_f32_16x16x32_bf16 v[106:109], v[218:221], v[66:69], v[106:109]
	s_add_u32 m0, s4, 0x8000
	v_mfma_f32_16x16x32_bf16 v[122:125], v[222:225], v[66:69], v[122:125]
	global_load_lds_dwordx4 v98, s[48:49]
	v_mfma_f32_16x16x32_bf16 v[138:141], v[226:229], v[66:69], v[138:141]
	v_mfma_f32_16x16x32_bf16 v[162:165], v[230:233], v[66:69], v[162:165]
	v_mfma_f32_16x16x32_bf16 v[110:113], v[218:221], v[70:73], v[110:113]
	s_add_u32 m0, s4, 0x8400
	v_mfma_f32_16x16x32_bf16 v[126:129], v[222:225], v[70:73], v[126:129]
	global_load_lds_dwordx4 v99, s[48:49]
	v_mfma_f32_16x16x32_bf16 v[142:145], v[226:229], v[70:73], v[142:145]
	v_mfma_f32_16x16x32_bf16 v[166:169], v[230:233], v[70:73], v[166:169]
	v_mfma_f32_16x16x32_bf16 v[114:117], v[218:221], v[74:77], v[114:117]
	s_add_u32 m0, s4, 0x8800
	v_mfma_f32_16x16x32_bf16 v[130:133], v[222:225], v[74:77], v[130:133]
	global_load_lds_dwordx4 v100, s[48:49]
	v_mfma_f32_16x16x32_bf16 v[154:157], v[226:229], v[74:77], v[154:157]
	v_mfma_f32_16x16x32_bf16 v[170:173], v[230:233], v[74:77], v[170:173]
	v_mfma_f32_16x16x32_bf16 v[118:121], v[218:221], v[78:81], v[118:121]
	s_add_u32 m0, s4, 0x8c00
	v_mfma_f32_16x16x32_bf16 v[134:137], v[222:225], v[78:81], v[134:137]
	global_load_lds_dwordx4 v101, s[48:49]
	v_mfma_f32_16x16x32_bf16 v[158:161], v[226:229], v[78:81], v[158:161]
	v_mfma_f32_16x16x32_bf16 v[174:177], v[230:233], v[78:81], v[174:177]
	s_waitcnt lgkmcnt(0)
	s_waitcnt vmcnt(8)
	s_barrier
	ds_read_b128 v[218:221], v102 offset:0
	ds_read_b128 v[222:225], v102 offset:2048
	ds_read_b128 v[226:229], v102 offset:4096
	ds_read_b128 v[230:233], v102 offset:6144
	ds_read_b128 v[66:69], v250 offset:49152
	ds_read_b128 v[70:73], v250 offset:51200
	ds_read_b128 v[74:77], v250 offset:53248
	ds_read_b128 v[78:81], v250 offset:55296
	v_mfma_f32_16x16x32_bf16 v[106:109], v[234:237], v[82:85], v[106:109]
	s_add_u32 m0, s4, 0xc000
	v_mfma_f32_16x16x32_bf16 v[122:125], v[238:241], v[82:85], v[122:125]
	global_load_lds_dwordx4 v98, s[28:29]
	v_mfma_f32_16x16x32_bf16 v[138:141], v[242:245], v[82:85], v[138:141]
	v_mfma_f32_16x16x32_bf16 v[162:165], v[246:249], v[82:85], v[162:165]
	v_mfma_f32_16x16x32_bf16 v[110:113], v[234:237], v[86:89], v[110:113]
	s_add_u32 m0, s4, 0xc400
	v_mfma_f32_16x16x32_bf16 v[126:129], v[238:241], v[86:89], v[126:129]
	global_load_lds_dwordx4 v99, s[28:29]
	v_mfma_f32_16x16x32_bf16 v[142:145], v[242:245], v[86:89], v[142:145]
	v_mfma_f32_16x16x32_bf16 v[166:169], v[246:249], v[86:89], v[166:169]
	v_mfma_f32_16x16x32_bf16 v[114:117], v[234:237], v[90:93], v[114:117]
	s_add_u32 m0, s4, 0xc800
	v_mfma_f32_16x16x32_bf16 v[130:133], v[238:241], v[90:93], v[130:133]
	global_load_lds_dwordx4 v100, s[28:29]
	v_mfma_f32_16x16x32_bf16 v[154:157], v[242:245], v[90:93], v[154:157]
	v_mfma_f32_16x16x32_bf16 v[170:173], v[246:249], v[90:93], v[170:173]
	v_mfma_f32_16x16x32_bf16 v[118:121], v[234:237], v[94:97], v[118:121]
	s_add_u32 m0, s4, 0xcc00
	v_mfma_f32_16x16x32_bf16 v[134:137], v[238:241], v[94:97], v[134:137]
	global_load_lds_dwordx4 v101, s[28:29]
	v_mfma_f32_16x16x32_bf16 v[158:161], v[242:245], v[94:97], v[158:161]
	v_mfma_f32_16x16x32_bf16 v[174:177], v[246:249], v[94:97], v[174:177]
	ds_read_b128 v[234:237], v103 offset:0
	ds_read_b128 v[238:241], v103 offset:2048
	ds_read_b128 v[242:245], v103 offset:4096
	ds_read_b128 v[246:249], v103 offset:6144
	ds_read_b128 v[82:85], v251 offset:49152
	ds_read_b128 v[86:89], v251 offset:51200
	ds_read_b128 v[90:93], v251 offset:53248
	ds_read_b128 v[94:97], v251 offset:55296
	s_waitcnt lgkmcnt(8)
	v_mfma_f32_16x16x32_bf16 v[62:65], v[218:221], v[66:69], v[62:65]
	v_mfma_f32_16x16x32_bf16 v[46:49], v[222:225], v[66:69], v[46:49]
	v_mfma_f32_16x16x32_bf16 v[30:33], v[226:229], v[66:69], v[30:33]
	v_mfma_f32_16x16x32_bf16 v[14:17], v[230:233], v[66:69], v[14:17]
	v_mfma_f32_16x16x32_bf16 v[58:61], v[218:221], v[70:73], v[58:61]
	v_mfma_f32_16x16x32_bf16 v[42:45], v[222:225], v[70:73], v[42:45]
	v_mfma_f32_16x16x32_bf16 v[26:29], v[226:229], v[70:73], v[26:29]
	v_mfma_f32_16x16x32_bf16 v[10:13], v[230:233], v[70:73], v[10:13]
	v_mfma_f32_16x16x32_bf16 v[54:57], v[218:221], v[74:77], v[54:57]
	v_mfma_f32_16x16x32_bf16 v[38:41], v[222:225], v[74:77], v[38:41]
	v_mfma_f32_16x16x32_bf16 v[22:25], v[226:229], v[74:77], v[22:25]
	v_mfma_f32_16x16x32_bf16 v[6:9], v[230:233], v[74:77], v[6:9]
	v_mfma_f32_16x16x32_bf16 v[50:53], v[218:221], v[78:81], v[50:53]
	v_mfma_f32_16x16x32_bf16 v[34:37], v[222:225], v[78:81], v[34:37]
	v_mfma_f32_16x16x32_bf16 v[18:21], v[226:229], v[78:81], v[18:21]
	v_mfma_f32_16x16x32_bf16 v[2:5], v[230:233], v[78:81], v[2:5]
	s_waitcnt lgkmcnt(0)
	s_waitcnt vmcnt(8)
	s_barrier
	ds_read_b128 v[218:221], v102 offset:16384
	ds_read_b128 v[222:225], v102 offset:18432
	ds_read_b128 v[226:229], v102 offset:20480
	ds_read_b128 v[230:233], v102 offset:22528
	v_mfma_f32_16x16x32_bf16 v[62:65], v[234:237], v[82:85], v[62:65]
	s_add_u32 m0, s4, 0x0
	v_mfma_f32_16x16x32_bf16 v[46:49], v[238:241], v[82:85], v[46:49]
	global_load_lds_dwordx4 v98, s[6:7]
	v_mfma_f32_16x16x32_bf16 v[30:33], v[242:245], v[82:85], v[30:33]
	v_mfma_f32_16x16x32_bf16 v[14:17], v[246:249], v[82:85], v[14:17]
	v_mfma_f32_16x16x32_bf16 v[58:61], v[234:237], v[86:89], v[58:61]
	s_add_u32 m0, s4, 0x400
	v_mfma_f32_16x16x32_bf16 v[42:45], v[238:241], v[86:89], v[42:45]
	global_load_lds_dwordx4 v99, s[6:7]
	v_mfma_f32_16x16x32_bf16 v[26:29], v[242:245], v[86:89], v[26:29]
	v_mfma_f32_16x16x32_bf16 v[10:13], v[246:249], v[86:89], v[10:13]
	v_mfma_f32_16x16x32_bf16 v[54:57], v[234:237], v[90:93], v[54:57]
	s_add_u32 m0, s4, 0x800
	v_mfma_f32_16x16x32_bf16 v[38:41], v[238:241], v[90:93], v[38:41]
	global_load_lds_dwordx4 v100, s[6:7]
	v_mfma_f32_16x16x32_bf16 v[22:25], v[242:245], v[90:93], v[22:25]
	v_mfma_f32_16x16x32_bf16 v[6:9], v[246:249], v[90:93], v[6:9]
	v_mfma_f32_16x16x32_bf16 v[50:53], v[234:237], v[94:97], v[50:53]
	s_add_u32 m0, s4, 0xc00
	v_mfma_f32_16x16x32_bf16 v[34:37], v[238:241], v[94:97], v[34:37]
	global_load_lds_dwordx4 v101, s[6:7]
	v_mfma_f32_16x16x32_bf16 v[18:21], v[242:245], v[94:97], v[18:21]
	v_mfma_f32_16x16x32_bf16 v[2:5], v[246:249], v[94:97], v[2:5]
	v_add_u32_e32 v98, 0x80, v98
	v_add_u32_e32 v99, 0x80, v99
	v_add_u32_e32 v100, 0x80, v100
	v_add_u32_e32 v101, 0x80, v101
	ds_read_b128 v[234:237], v103 offset:16384
	ds_read_b128 v[238:241], v103 offset:18432
	ds_read_b128 v[242:245], v103 offset:20480
	ds_read_b128 v[246:249], v103 offset:22528
	s_waitcnt lgkmcnt(4)
	v_mfma_f32_16x16x32_bf16 v[106:109], v[218:221], v[66:69], v[106:109]
	s_add_u32 m0, s4, 0x10000
	v_mfma_f32_16x16x32_bf16 v[122:125], v[222:225], v[66:69], v[122:125]
	global_load_lds_dwordx4 v98, s[48:49]
	v_mfma_f32_16x16x32_bf16 v[138:141], v[226:229], v[66:69], v[138:141]
	v_mfma_f32_16x16x32_bf16 v[162:165], v[230:233], v[66:69], v[162:165]
	v_mfma_f32_16x16x32_bf16 v[110:113], v[218:221], v[70:73], v[110:113]
	s_add_u32 m0, s4, 0x10400
	v_mfma_f32_16x16x32_bf16 v[126:129], v[222:225], v[70:73], v[126:129]
	global_load_lds_dwordx4 v99, s[48:49]
	v_mfma_f32_16x16x32_bf16 v[142:145], v[226:229], v[70:73], v[142:145]
	v_mfma_f32_16x16x32_bf16 v[166:169], v[230:233], v[70:73], v[166:169]
	v_mfma_f32_16x16x32_bf16 v[114:117], v[218:221], v[74:77], v[114:117]
	s_add_u32 m0, s4, 0x10800
	v_mfma_f32_16x16x32_bf16 v[130:133], v[222:225], v[74:77], v[130:133]
	global_load_lds_dwordx4 v100, s[48:49]
	v_mfma_f32_16x16x32_bf16 v[154:157], v[226:229], v[74:77], v[154:157]
	v_mfma_f32_16x16x32_bf16 v[170:173], v[230:233], v[74:77], v[170:173]
	v_mfma_f32_16x16x32_bf16 v[118:121], v[218:221], v[78:81], v[118:121]
	s_add_u32 m0, s4, 0x10c00
	v_mfma_f32_16x16x32_bf16 v[134:137], v[222:225], v[78:81], v[134:137]
	global_load_lds_dwordx4 v101, s[48:49]
	v_mfma_f32_16x16x32_bf16 v[158:161], v[226:229], v[78:81], v[158:161]
	v_mfma_f32_16x16x32_bf16 v[174:177], v[230:233], v[78:81], v[174:177]
	s_waitcnt lgkmcnt(0)
	s_waitcnt vmcnt(8)
	s_barrier
	ds_read_b128 v[218:221], v102 offset:49152
	ds_read_b128 v[222:225], v102 offset:51200
	ds_read_b128 v[226:229], v102 offset:53248
	ds_read_b128 v[230:233], v102 offset:55296
	ds_read_b128 v[66:69], v104 offset:32768
	ds_read_b128 v[70:73], v104 offset:34816
	ds_read_b128 v[74:77], v104 offset:36864
	ds_read_b128 v[78:81], v104 offset:38912
	v_mfma_f32_16x16x32_bf16 v[106:109], v[234:237], v[82:85], v[106:109]
	s_add_u32 m0, s4, 0x4000
	v_mfma_f32_16x16x32_bf16 v[122:125], v[238:241], v[82:85], v[122:125]
	global_load_lds_dwordx4 v98, s[28:29]
	v_mfma_f32_16x16x32_bf16 v[138:141], v[242:245], v[82:85], v[138:141]
	v_mfma_f32_16x16x32_bf16 v[162:165], v[246:249], v[82:85], v[162:165]
	v_mfma_f32_16x16x32_bf16 v[110:113], v[234:237], v[86:89], v[110:113]
	s_add_u32 m0, s4, 0x4400
	v_mfma_f32_16x16x32_bf16 v[126:129], v[238:241], v[86:89], v[126:129]
	global_load_lds_dwordx4 v99, s[28:29]
	v_mfma_f32_16x16x32_bf16 v[142:145], v[242:245], v[86:89], v[142:145]
	v_mfma_f32_16x16x32_bf16 v[166:169], v[246:249], v[86:89], v[166:169]
	v_mfma_f32_16x16x32_bf16 v[114:117], v[234:237], v[90:93], v[114:117]
	s_add_u32 m0, s4, 0x4800
	v_mfma_f32_16x16x32_bf16 v[130:133], v[238:241], v[90:93], v[130:133]
	global_load_lds_dwordx4 v100, s[28:29]
	v_mfma_f32_16x16x32_bf16 v[154:157], v[242:245], v[90:93], v[154:157]
	v_mfma_f32_16x16x32_bf16 v[170:173], v[246:249], v[90:93], v[170:173]
	v_mfma_f32_16x16x32_bf16 v[118:121], v[234:237], v[94:97], v[118:121]
	s_add_u32 m0, s4, 0x4c00
	v_mfma_f32_16x16x32_bf16 v[134:137], v[238:241], v[94:97], v[134:137]
	global_load_lds_dwordx4 v101, s[28:29]
	v_mfma_f32_16x16x32_bf16 v[158:161], v[242:245], v[94:97], v[158:161]
	v_mfma_f32_16x16x32_bf16 v[174:177], v[246:249], v[94:97], v[174:177]
	ds_read_b128 v[234:237], v103 offset:49152
	ds_read_b128 v[238:241], v103 offset:51200
	ds_read_b128 v[242:245], v103 offset:53248
	ds_read_b128 v[246:249], v103 offset:55296
	ds_read_b128 v[82:85], v105 offset:32768
	ds_read_b128 v[86:89], v105 offset:34816
	ds_read_b128 v[90:93], v105 offset:36864
	ds_read_b128 v[94:97], v105 offset:38912
	s_waitcnt lgkmcnt(8)
	v_mfma_f32_16x16x32_bf16 v[62:65], v[218:221], v[66:69], v[62:65]
	v_mfma_f32_16x16x32_bf16 v[46:49], v[222:225], v[66:69], v[46:49]
	v_mfma_f32_16x16x32_bf16 v[30:33], v[226:229], v[66:69], v[30:33]
	v_mfma_f32_16x16x32_bf16 v[14:17], v[230:233], v[66:69], v[14:17]
	v_mfma_f32_16x16x32_bf16 v[58:61], v[218:221], v[70:73], v[58:61]
	v_mfma_f32_16x16x32_bf16 v[42:45], v[222:225], v[70:73], v[42:45]
	v_mfma_f32_16x16x32_bf16 v[26:29], v[226:229], v[70:73], v[26:29]
	v_mfma_f32_16x16x32_bf16 v[10:13], v[230:233], v[70:73], v[10:13]
	v_mfma_f32_16x16x32_bf16 v[54:57], v[218:221], v[74:77], v[54:57]
	v_mfma_f32_16x16x32_bf16 v[38:41], v[222:225], v[74:77], v[38:41]
	v_mfma_f32_16x16x32_bf16 v[22:25], v[226:229], v[74:77], v[22:25]
	v_mfma_f32_16x16x32_bf16 v[6:9], v[230:233], v[74:77], v[6:9]
	v_mfma_f32_16x16x32_bf16 v[50:53], v[218:221], v[78:81], v[50:53]
	v_mfma_f32_16x16x32_bf16 v[34:37], v[222:225], v[78:81], v[34:37]
	v_mfma_f32_16x16x32_bf16 v[18:21], v[226:229], v[78:81], v[18:21]
	v_mfma_f32_16x16x32_bf16 v[2:5], v[230:233], v[78:81], v[2:5]
	s_waitcnt lgkmcnt(0)
	s_waitcnt vmcnt(8)
	s_barrier
	ds_read_b128 v[218:221], v102 offset:0
	ds_read_b128 v[222:225], v102 offset:2048
	ds_read_b128 v[226:229], v102 offset:4096
	ds_read_b128 v[230:233], v102 offset:6144
	v_mfma_f32_16x16x32_bf16 v[62:65], v[234:237], v[82:85], v[62:65]
	s_add_u32 m0, s4, 0xc000
	v_mfma_f32_16x16x32_bf16 v[46:49], v[238:241], v[82:85], v[46:49]
	global_load_lds_dwordx4 v98, s[6:7]
	v_mfma_f32_16x16x32_bf16 v[30:33], v[242:245], v[82:85], v[30:33]
	v_mfma_f32_16x16x32_bf16 v[14:17], v[246:249], v[82:85], v[14:17]
	v_mfma_f32_16x16x32_bf16 v[58:61], v[234:237], v[86:89], v[58:61]
	s_add_u32 m0, s4, 0xc400
	v_mfma_f32_16x16x32_bf16 v[42:45], v[238:241], v[86:89], v[42:45]
	global_load_lds_dwordx4 v99, s[6:7]
	v_mfma_f32_16x16x32_bf16 v[26:29], v[242:245], v[86:89], v[26:29]
	v_mfma_f32_16x16x32_bf16 v[10:13], v[246:249], v[86:89], v[10:13]
	v_mfma_f32_16x16x32_bf16 v[54:57], v[234:237], v[90:93], v[54:57]
	s_add_u32 m0, s4, 0xc800
	v_mfma_f32_16x16x32_bf16 v[38:41], v[238:241], v[90:93], v[38:41]
	global_load_lds_dwordx4 v100, s[6:7]
	v_mfma_f32_16x16x32_bf16 v[22:25], v[242:245], v[90:93], v[22:25]
	v_mfma_f32_16x16x32_bf16 v[6:9], v[246:249], v[90:93], v[6:9]
	v_mfma_f32_16x16x32_bf16 v[50:53], v[234:237], v[94:97], v[50:53]
	s_add_u32 m0, s4, 0xcc00
	v_mfma_f32_16x16x32_bf16 v[34:37], v[238:241], v[94:97], v[34:37]
	global_load_lds_dwordx4 v101, s[6:7]
	v_mfma_f32_16x16x32_bf16 v[18:21], v[242:245], v[94:97], v[18:21]
	v_mfma_f32_16x16x32_bf16 v[2:5], v[246:249], v[94:97], v[2:5]
	v_add_u32_e32 v98, 0x80, v98
	v_add_u32_e32 v99, 0x80, v99
	v_add_u32_e32 v100, 0x80, v100
	v_add_u32_e32 v101, 0x80, v101
	ds_read_b128 v[234:237], v103 offset:0
	ds_read_b128 v[238:241], v103 offset:2048
	ds_read_b128 v[242:245], v103 offset:4096
	ds_read_b128 v[246:249], v103 offset:6144
	s_waitcnt lgkmcnt(4)
	v_mfma_f32_16x16x32_bf16 v[106:109], v[218:221], v[66:69], v[106:109]
	s_add_u32 m0, s4, 0x8000
	v_mfma_f32_16x16x32_bf16 v[122:125], v[222:225], v[66:69], v[122:125]
	global_load_lds_dwordx4 v98, s[48:49]
	v_mfma_f32_16x16x32_bf16 v[138:141], v[226:229], v[66:69], v[138:141]
	v_mfma_f32_16x16x32_bf16 v[162:165], v[230:233], v[66:69], v[162:165]
	v_mfma_f32_16x16x32_bf16 v[110:113], v[218:221], v[70:73], v[110:113]
	s_add_u32 m0, s4, 0x8400
	v_mfma_f32_16x16x32_bf16 v[126:129], v[222:225], v[70:73], v[126:129]
	global_load_lds_dwordx4 v99, s[48:49]
	v_mfma_f32_16x16x32_bf16 v[142:145], v[226:229], v[70:73], v[142:145]
	v_mfma_f32_16x16x32_bf16 v[166:169], v[230:233], v[70:73], v[166:169]
	v_mfma_f32_16x16x32_bf16 v[114:117], v[218:221], v[74:77], v[114:117]
	s_add_u32 m0, s4, 0x8800
	v_mfma_f32_16x16x32_bf16 v[130:133], v[222:225], v[74:77], v[130:133]
	global_load_lds_dwordx4 v100, s[48:49]
	v_mfma_f32_16x16x32_bf16 v[154:157], v[226:229], v[74:77], v[154:157]
	v_mfma_f32_16x16x32_bf16 v[170:173], v[230:233], v[74:77], v[170:173]
	v_mfma_f32_16x16x32_bf16 v[118:121], v[218:221], v[78:81], v[118:121]
	s_add_u32 m0, s4, 0x8c00
	v_mfma_f32_16x16x32_bf16 v[134:137], v[222:225], v[78:81], v[134:137]
	global_load_lds_dwordx4 v101, s[48:49]
	v_mfma_f32_16x16x32_bf16 v[158:161], v[226:229], v[78:81], v[158:161]
	v_mfma_f32_16x16x32_bf16 v[174:177], v[230:233], v[78:81], v[174:177]
	s_waitcnt lgkmcnt(0)
	s_waitcnt vmcnt(8)
	s_barrier
	ds_read_b128 v[218:221], v102 offset:16384
	ds_read_b128 v[222:225], v102 offset:18432
	ds_read_b128 v[226:229], v102 offset:20480
	ds_read_b128 v[230:233], v102 offset:22528
	ds_read_b128 v[66:69], v250 offset:49152
	ds_read_b128 v[70:73], v250 offset:51200
	ds_read_b128 v[74:77], v250 offset:53248
	ds_read_b128 v[78:81], v250 offset:55296
	v_mfma_f32_16x16x32_bf16 v[106:109], v[234:237], v[82:85], v[106:109]
	s_add_u32 m0, s4, 0x0
	v_mfma_f32_16x16x32_bf16 v[122:125], v[238:241], v[82:85], v[122:125]
	global_load_lds_dwordx4 v98, s[28:29]
	v_mfma_f32_16x16x32_bf16 v[138:141], v[242:245], v[82:85], v[138:141]
	v_mfma_f32_16x16x32_bf16 v[162:165], v[246:249], v[82:85], v[162:165]
	v_mfma_f32_16x16x32_bf16 v[110:113], v[234:237], v[86:89], v[110:113]
	s_add_u32 m0, s4, 0x400
	v_mfma_f32_16x16x32_bf16 v[126:129], v[238:241], v[86:89], v[126:129]
	global_load_lds_dwordx4 v99, s[28:29]
	v_mfma_f32_16x16x32_bf16 v[142:145], v[242:245], v[86:89], v[142:145]
	v_mfma_f32_16x16x32_bf16 v[166:169], v[246:249], v[86:89], v[166:169]
	v_mfma_f32_16x16x32_bf16 v[114:117], v[234:237], v[90:93], v[114:117]
	s_add_u32 m0, s4, 0x800
	v_mfma_f32_16x16x32_bf16 v[130:133], v[238:241], v[90:93], v[130:133]
	global_load_lds_dwordx4 v100, s[28:29]
	v_mfma_f32_16x16x32_bf16 v[154:157], v[242:245], v[90:93], v[154:157]
	v_mfma_f32_16x16x32_bf16 v[170:173], v[246:249], v[90:93], v[170:173]
	v_mfma_f32_16x16x32_bf16 v[118:121], v[234:237], v[94:97], v[118:121]
	s_add_u32 m0, s4, 0xc00
	v_mfma_f32_16x16x32_bf16 v[134:137], v[238:241], v[94:97], v[134:137]
	global_load_lds_dwordx4 v101, s[28:29]
	v_mfma_f32_16x16x32_bf16 v[158:161], v[242:245], v[94:97], v[158:161]
	v_mfma_f32_16x16x32_bf16 v[174:177], v[246:249], v[94:97], v[174:177]
	ds_read_b128 v[234:237], v103 offset:16384
	ds_read_b128 v[238:241], v103 offset:18432
	ds_read_b128 v[242:245], v103 offset:20480
	ds_read_b128 v[246:249], v103 offset:22528
	ds_read_b128 v[82:85], v251 offset:49152
	ds_read_b128 v[86:89], v251 offset:51200
	ds_read_b128 v[90:93], v251 offset:53248
	ds_read_b128 v[94:97], v251 offset:55296
	s_waitcnt lgkmcnt(8)
	v_mfma_f32_16x16x32_bf16 v[62:65], v[218:221], v[66:69], v[62:65]
	v_mfma_f32_16x16x32_bf16 v[46:49], v[222:225], v[66:69], v[46:49]
	v_mfma_f32_16x16x32_bf16 v[30:33], v[226:229], v[66:69], v[30:33]
	v_mfma_f32_16x16x32_bf16 v[14:17], v[230:233], v[66:69], v[14:17]
	v_mfma_f32_16x16x32_bf16 v[58:61], v[218:221], v[70:73], v[58:61]
	v_mfma_f32_16x16x32_bf16 v[42:45], v[222:225], v[70:73], v[42:45]
	v_mfma_f32_16x16x32_bf16 v[26:29], v[226:229], v[70:73], v[26:29]
	v_mfma_f32_16x16x32_bf16 v[10:13], v[230:233], v[70:73], v[10:13]
	v_mfma_f32_16x16x32_bf16 v[54:57], v[218:221], v[74:77], v[54:57]
	v_mfma_f32_16x16x32_bf16 v[38:41], v[222:225], v[74:77], v[38:41]
	v_mfma_f32_16x16x32_bf16 v[22:25], v[226:229], v[74:77], v[22:25]
	v_mfma_f32_16x16x32_bf16 v[6:9], v[230:233], v[74:77], v[6:9]
	v_mfma_f32_16x16x32_bf16 v[50:53], v[218:221], v[78:81], v[50:53]
	v_mfma_f32_16x16x32_bf16 v[34:37], v[222:225], v[78:81], v[34:37]
	v_mfma_f32_16x16x32_bf16 v[18:21], v[226:229], v[78:81], v[18:21]
	v_mfma_f32_16x16x32_bf16 v[2:5], v[230:233], v[78:81], v[2:5]
	s_waitcnt lgkmcnt(0)
	s_waitcnt vmcnt(8)
	s_barrier
	ds_read_b128 v[218:221], v102 offset:49152
	ds_read_b128 v[222:225], v102 offset:51200
	ds_read_b128 v[226:229], v102 offset:53248
	ds_read_b128 v[230:233], v102 offset:55296
	v_mfma_f32_16x16x32_bf16 v[62:65], v[234:237], v[82:85], v[62:65]
	s_add_u32 m0, s4, 0x4000
	v_mfma_f32_16x16x32_bf16 v[46:49], v[238:241], v[82:85], v[46:49]
	global_load_lds_dwordx4 v98, s[6:7]
	v_mfma_f32_16x16x32_bf16 v[30:33], v[242:245], v[82:85], v[30:33]
	v_mfma_f32_16x16x32_bf16 v[14:17], v[246:249], v[82:85], v[14:17]
	v_mfma_f32_16x16x32_bf16 v[58:61], v[234:237], v[86:89], v[58:61]
	s_add_u32 m0, s4, 0x4400
	v_mfma_f32_16x16x32_bf16 v[42:45], v[238:241], v[86:89], v[42:45]
	global_load_lds_dwordx4 v99, s[6:7]
	v_mfma_f32_16x16x32_bf16 v[26:29], v[242:245], v[86:89], v[26:29]
	v_mfma_f32_16x16x32_bf16 v[10:13], v[246:249], v[86:89], v[10:13]
	v_mfma_f32_16x16x32_bf16 v[54:57], v[234:237], v[90:93], v[54:57]
	s_add_u32 m0, s4, 0x4800
	v_mfma_f32_16x16x32_bf16 v[38:41], v[238:241], v[90:93], v[38:41]
	global_load_lds_dwordx4 v100, s[6:7]
	v_mfma_f32_16x16x32_bf16 v[22:25], v[242:245], v[90:93], v[22:25]
	v_mfma_f32_16x16x32_bf16 v[6:9], v[246:249], v[90:93], v[6:9]
	v_mfma_f32_16x16x32_bf16 v[50:53], v[234:237], v[94:97], v[50:53]
	s_add_u32 m0, s4, 0x4c00
	v_mfma_f32_16x16x32_bf16 v[34:37], v[238:241], v[94:97], v[34:37]
	global_load_lds_dwordx4 v101, s[6:7]
	v_mfma_f32_16x16x32_bf16 v[18:21], v[242:245], v[94:97], v[18:21]
	v_mfma_f32_16x16x32_bf16 v[2:5], v[246:249], v[94:97], v[2:5]
	v_add_u32_e32 v98, 0x80, v98
	v_add_u32_e32 v99, 0x80, v99
	v_add_u32_e32 v100, 0x80, v100
	v_add_u32_e32 v101, 0x80, v101
	ds_read_b128 v[234:237], v103 offset:49152
	ds_read_b128 v[238:241], v103 offset:51200
	ds_read_b128 v[242:245], v103 offset:53248
	ds_read_b128 v[246:249], v103 offset:55296
	s_waitcnt lgkmcnt(4)
	v_mfma_f32_16x16x32_bf16 v[106:109], v[218:221], v[66:69], v[106:109]
	s_add_u32 m0, s4, 0x10000
	v_mfma_f32_16x16x32_bf16 v[122:125], v[222:225], v[66:69], v[122:125]
	global_load_lds_dwordx4 v98, s[48:49]
	v_mfma_f32_16x16x32_bf16 v[138:141], v[226:229], v[66:69], v[138:141]
	v_mfma_f32_16x16x32_bf16 v[162:165], v[230:233], v[66:69], v[162:165]
	v_mfma_f32_16x16x32_bf16 v[110:113], v[218:221], v[70:73], v[110:113]
	s_add_u32 m0, s4, 0x10400
	v_mfma_f32_16x16x32_bf16 v[126:129], v[222:225], v[70:73], v[126:129]
	global_load_lds_dwordx4 v99, s[48:49]
	v_mfma_f32_16x16x32_bf16 v[142:145], v[226:229], v[70:73], v[142:145]
	v_mfma_f32_16x16x32_bf16 v[166:169], v[230:233], v[70:73], v[166:169]
	v_mfma_f32_16x16x32_bf16 v[114:117], v[218:221], v[74:77], v[114:117]
	s_add_u32 m0, s4, 0x10800
	v_mfma_f32_16x16x32_bf16 v[130:133], v[222:225], v[74:77], v[130:133]
	global_load_lds_dwordx4 v100, s[48:49]
	v_mfma_f32_16x16x32_bf16 v[154:157], v[226:229], v[74:77], v[154:157]
	v_mfma_f32_16x16x32_bf16 v[170:173], v[230:233], v[74:77], v[170:173]
	v_mfma_f32_16x16x32_bf16 v[118:121], v[218:221], v[78:81], v[118:121]
	s_add_u32 m0, s4, 0x10c00
	v_mfma_f32_16x16x32_bf16 v[134:137], v[222:225], v[78:81], v[134:137]
	global_load_lds_dwordx4 v101, s[48:49]
	v_mfma_f32_16x16x32_bf16 v[158:161], v[226:229], v[78:81], v[158:161]
	v_mfma_f32_16x16x32_bf16 v[174:177], v[230:233], v[78:81], v[174:177]
	s_waitcnt lgkmcnt(0)
	s_waitcnt vmcnt(8)
	s_barrier
	ds_read_b128 v[218:221], v102 offset:0
	ds_read_b128 v[222:225], v102 offset:2048
	ds_read_b128 v[226:229], v102 offset:4096
	ds_read_b128 v[230:233], v102 offset:6144
	ds_read_b128 v[66:69], v104 offset:32768
	ds_read_b128 v[70:73], v104 offset:34816
	ds_read_b128 v[74:77], v104 offset:36864
	ds_read_b128 v[78:81], v104 offset:38912
	v_mfma_f32_16x16x32_bf16 v[106:109], v[234:237], v[82:85], v[106:109]
	s_add_u32 m0, s4, 0xc000
	v_mfma_f32_16x16x32_bf16 v[122:125], v[238:241], v[82:85], v[122:125]
	global_load_lds_dwordx4 v98, s[28:29]
	v_mfma_f32_16x16x32_bf16 v[138:141], v[242:245], v[82:85], v[138:141]
	v_mfma_f32_16x16x32_bf16 v[162:165], v[246:249], v[82:85], v[162:165]
	v_mfma_f32_16x16x32_bf16 v[110:113], v[234:237], v[86:89], v[110:113]
	s_add_u32 m0, s4, 0xc400
	v_mfma_f32_16x16x32_bf16 v[126:129], v[238:241], v[86:89], v[126:129]
	global_load_lds_dwordx4 v99, s[28:29]
	v_mfma_f32_16x16x32_bf16 v[142:145], v[242:245], v[86:89], v[142:145]
	v_mfma_f32_16x16x32_bf16 v[166:169], v[246:249], v[86:89], v[166:169]
	v_mfma_f32_16x16x32_bf16 v[114:117], v[234:237], v[90:93], v[114:117]
	s_add_u32 m0, s4, 0xc800
	v_mfma_f32_16x16x32_bf16 v[130:133], v[238:241], v[90:93], v[130:133]
	global_load_lds_dwordx4 v100, s[28:29]
	v_mfma_f32_16x16x32_bf16 v[154:157], v[242:245], v[90:93], v[154:157]
	v_mfma_f32_16x16x32_bf16 v[170:173], v[246:249], v[90:93], v[170:173]
	v_mfma_f32_16x16x32_bf16 v[118:121], v[234:237], v[94:97], v[118:121]
	s_add_u32 m0, s4, 0xcc00
	v_mfma_f32_16x16x32_bf16 v[134:137], v[238:241], v[94:97], v[134:137]
	global_load_lds_dwordx4 v101, s[28:29]
	v_mfma_f32_16x16x32_bf16 v[158:161], v[242:245], v[94:97], v[158:161]
	v_mfma_f32_16x16x32_bf16 v[174:177], v[246:249], v[94:97], v[174:177]
	ds_read_b128 v[234:237], v103 offset:0
	ds_read_b128 v[238:241], v103 offset:2048
	ds_read_b128 v[242:245], v103 offset:4096
	ds_read_b128 v[246:249], v103 offset:6144
	ds_read_b128 v[82:85], v105 offset:32768
	ds_read_b128 v[86:89], v105 offset:34816
	ds_read_b128 v[90:93], v105 offset:36864
	ds_read_b128 v[94:97], v105 offset:38912
	s_waitcnt lgkmcnt(8)
	v_mfma_f32_16x16x32_bf16 v[62:65], v[218:221], v[66:69], v[62:65]
	v_mfma_f32_16x16x32_bf16 v[46:49], v[222:225], v[66:69], v[46:49]
	v_mfma_f32_16x16x32_bf16 v[30:33], v[226:229], v[66:69], v[30:33]
	v_mfma_f32_16x16x32_bf16 v[14:17], v[230:233], v[66:69], v[14:17]
	v_mfma_f32_16x16x32_bf16 v[58:61], v[218:221], v[70:73], v[58:61]
	v_mfma_f32_16x16x32_bf16 v[42:45], v[222:225], v[70:73], v[42:45]
	v_mfma_f32_16x16x32_bf16 v[26:29], v[226:229], v[70:73], v[26:29]
	v_mfma_f32_16x16x32_bf16 v[10:13], v[230:233], v[70:73], v[10:13]
	v_mfma_f32_16x16x32_bf16 v[54:57], v[218:221], v[74:77], v[54:57]
	v_mfma_f32_16x16x32_bf16 v[38:41], v[222:225], v[74:77], v[38:41]
	v_mfma_f32_16x16x32_bf16 v[22:25], v[226:229], v[74:77], v[22:25]
	v_mfma_f32_16x16x32_bf16 v[6:9], v[230:233], v[74:77], v[6:9]
	v_mfma_f32_16x16x32_bf16 v[50:53], v[218:221], v[78:81], v[50:53]
	v_mfma_f32_16x16x32_bf16 v[34:37], v[222:225], v[78:81], v[34:37]
	v_mfma_f32_16x16x32_bf16 v[18:21], v[226:229], v[78:81], v[18:21]
	v_mfma_f32_16x16x32_bf16 v[2:5], v[230:233], v[78:81], v[2:5]
	s_waitcnt lgkmcnt(0)
	s_waitcnt vmcnt(8)
	s_barrier
	ds_read_b128 v[218:221], v102 offset:16384
	ds_read_b128 v[222:225], v102 offset:18432
	ds_read_b128 v[226:229], v102 offset:20480
	ds_read_b128 v[230:233], v102 offset:22528
	v_mfma_f32_16x16x32_bf16 v[62:65], v[234:237], v[82:85], v[62:65]
	s_add_u32 m0, s4, 0x0
	v_mfma_f32_16x16x32_bf16 v[46:49], v[238:241], v[82:85], v[46:49]
	global_load_lds_dwordx4 v98, s[6:7]
	v_mfma_f32_16x16x32_bf16 v[30:33], v[242:245], v[82:85], v[30:33]
	v_mfma_f32_16x16x32_bf16 v[14:17], v[246:249], v[82:85], v[14:17]
	v_mfma_f32_16x16x32_bf16 v[58:61], v[234:237], v[86:89], v[58:61]
	s_add_u32 m0, s4, 0x400
	v_mfma_f32_16x16x32_bf16 v[42:45], v[238:241], v[86:89], v[42:45]
	global_load_lds_dwordx4 v99, s[6:7]
	v_mfma_f32_16x16x32_bf16 v[26:29], v[242:245], v[86:89], v[26:29]
	v_mfma_f32_16x16x32_bf16 v[10:13], v[246:249], v[86:89], v[10:13]
	v_mfma_f32_16x16x32_bf16 v[54:57], v[234:237], v[90:93], v[54:57]
	s_add_u32 m0, s4, 0x800
	v_mfma_f32_16x16x32_bf16 v[38:41], v[238:241], v[90:93], v[38:41]
	global_load_lds_dwordx4 v100, s[6:7]
	v_mfma_f32_16x16x32_bf16 v[22:25], v[242:245], v[90:93], v[22:25]
	v_mfma_f32_16x16x32_bf16 v[6:9], v[246:249], v[90:93], v[6:9]
	v_mfma_f32_16x16x32_bf16 v[50:53], v[234:237], v[94:97], v[50:53]
	s_add_u32 m0, s4, 0xc00
	v_mfma_f32_16x16x32_bf16 v[34:37], v[238:241], v[94:97], v[34:37]
	global_load_lds_dwordx4 v101, s[6:7]
	v_mfma_f32_16x16x32_bf16 v[18:21], v[242:245], v[94:97], v[18:21]
	v_mfma_f32_16x16x32_bf16 v[2:5], v[246:249], v[94:97], v[2:5]
	v_add_u32_e32 v98, 0x80, v98
	v_add_u32_e32 v99, 0x80, v99
	v_add_u32_e32 v100, 0x80, v100
	v_add_u32_e32 v101, 0x80, v101
	ds_read_b128 v[234:237], v103 offset:16384
	ds_read_b128 v[238:241], v103 offset:18432
	ds_read_b128 v[242:245], v103 offset:20480
	ds_read_b128 v[246:249], v103 offset:22528
	s_waitcnt lgkmcnt(4)
	v_mfma_f32_16x16x32_bf16 v[106:109], v[218:221], v[66:69], v[106:109]
	s_add_u32 m0, s4, 0x8000
	v_mfma_f32_16x16x32_bf16 v[122:125], v[222:225], v[66:69], v[122:125]
	global_load_lds_dwordx4 v98, s[48:49]
	v_mfma_f32_16x16x32_bf16 v[138:141], v[226:229], v[66:69], v[138:141]
	v_mfma_f32_16x16x32_bf16 v[162:165], v[230:233], v[66:69], v[162:165]
	v_mfma_f32_16x16x32_bf16 v[110:113], v[218:221], v[70:73], v[110:113]
	s_add_u32 m0, s4, 0x8400
	v_mfma_f32_16x16x32_bf16 v[126:129], v[222:225], v[70:73], v[126:129]
	global_load_lds_dwordx4 v99, s[48:49]
	v_mfma_f32_16x16x32_bf16 v[142:145], v[226:229], v[70:73], v[142:145]
	v_mfma_f32_16x16x32_bf16 v[166:169], v[230:233], v[70:73], v[166:169]
	v_mfma_f32_16x16x32_bf16 v[114:117], v[218:221], v[74:77], v[114:117]
	s_add_u32 m0, s4, 0x8800
	v_mfma_f32_16x16x32_bf16 v[130:133], v[222:225], v[74:77], v[130:133]
	global_load_lds_dwordx4 v100, s[48:49]
	v_mfma_f32_16x16x32_bf16 v[154:157], v[226:229], v[74:77], v[154:157]
	v_mfma_f32_16x16x32_bf16 v[170:173], v[230:233], v[74:77], v[170:173]
	v_mfma_f32_16x16x32_bf16 v[118:121], v[218:221], v[78:81], v[118:121]
	s_add_u32 m0, s4, 0x8c00
	v_mfma_f32_16x16x32_bf16 v[134:137], v[222:225], v[78:81], v[134:137]
	global_load_lds_dwordx4 v101, s[48:49]
	v_mfma_f32_16x16x32_bf16 v[158:161], v[226:229], v[78:81], v[158:161]
	v_mfma_f32_16x16x32_bf16 v[174:177], v[230:233], v[78:81], v[174:177]
	s_waitcnt lgkmcnt(0)
	s_waitcnt vmcnt(8)
	s_barrier
	ds_read_b128 v[218:221], v102 offset:49152
	ds_read_b128 v[222:225], v102 offset:51200
	ds_read_b128 v[226:229], v102 offset:53248
	ds_read_b128 v[230:233], v102 offset:55296
	ds_read_b128 v[66:69], v250 offset:49152
	ds_read_b128 v[70:73], v250 offset:51200
	ds_read_b128 v[74:77], v250 offset:53248
	ds_read_b128 v[78:81], v250 offset:55296
	v_mfma_f32_16x16x32_bf16 v[106:109], v[234:237], v[82:85], v[106:109]
	s_add_u32 m0, s4, 0x4000
	v_mfma_f32_16x16x32_bf16 v[122:125], v[238:241], v[82:85], v[122:125]
	global_load_lds_dwordx4 v98, s[28:29]
	v_mfma_f32_16x16x32_bf16 v[138:141], v[242:245], v[82:85], v[138:141]
	v_mfma_f32_16x16x32_bf16 v[162:165], v[246:249], v[82:85], v[162:165]
	v_mfma_f32_16x16x32_bf16 v[110:113], v[234:237], v[86:89], v[110:113]
	s_add_u32 m0, s4, 0x4400
	v_mfma_f32_16x16x32_bf16 v[126:129], v[238:241], v[86:89], v[126:129]
	global_load_lds_dwordx4 v99, s[28:29]
	v_mfma_f32_16x16x32_bf16 v[142:145], v[242:245], v[86:89], v[142:145]
	v_mfma_f32_16x16x32_bf16 v[166:169], v[246:249], v[86:89], v[166:169]
	v_mfma_f32_16x16x32_bf16 v[114:117], v[234:237], v[90:93], v[114:117]
	s_add_u32 m0, s4, 0x4800
	v_mfma_f32_16x16x32_bf16 v[130:133], v[238:241], v[90:93], v[130:133]
	global_load_lds_dwordx4 v100, s[28:29]
	v_mfma_f32_16x16x32_bf16 v[154:157], v[242:245], v[90:93], v[154:157]
	v_mfma_f32_16x16x32_bf16 v[170:173], v[246:249], v[90:93], v[170:173]
	v_mfma_f32_16x16x32_bf16 v[118:121], v[234:237], v[94:97], v[118:121]
	s_add_u32 m0, s4, 0x4c00
	v_mfma_f32_16x16x32_bf16 v[134:137], v[238:241], v[94:97], v[134:137]
	global_load_lds_dwordx4 v101, s[28:29]
	v_mfma_f32_16x16x32_bf16 v[158:161], v[242:245], v[94:97], v[158:161]
	v_mfma_f32_16x16x32_bf16 v[174:177], v[246:249], v[94:97], v[174:177]
	ds_read_b128 v[234:237], v103 offset:49152
	ds_read_b128 v[238:241], v103 offset:51200
	ds_read_b128 v[242:245], v103 offset:53248
	ds_read_b128 v[246:249], v103 offset:55296
	ds_read_b128 v[82:85], v251 offset:49152
	ds_read_b128 v[86:89], v251 offset:51200
	ds_read_b128 v[90:93], v251 offset:53248
	ds_read_b128 v[94:97], v251 offset:55296
	s_waitcnt lgkmcnt(8)
	v_mfma_f32_16x16x32_bf16 v[62:65], v[218:221], v[66:69], v[62:65]
	v_mfma_f32_16x16x32_bf16 v[46:49], v[222:225], v[66:69], v[46:49]
	v_mfma_f32_16x16x32_bf16 v[30:33], v[226:229], v[66:69], v[30:33]
	v_mfma_f32_16x16x32_bf16 v[14:17], v[230:233], v[66:69], v[14:17]
	v_mfma_f32_16x16x32_bf16 v[58:61], v[218:221], v[70:73], v[58:61]
	v_mfma_f32_16x16x32_bf16 v[42:45], v[222:225], v[70:73], v[42:45]
	v_mfma_f32_16x16x32_bf16 v[26:29], v[226:229], v[70:73], v[26:29]
	v_mfma_f32_16x16x32_bf16 v[10:13], v[230:233], v[70:73], v[10:13]
	v_mfma_f32_16x16x32_bf16 v[54:57], v[218:221], v[74:77], v[54:57]
	v_mfma_f32_16x16x32_bf16 v[38:41], v[222:225], v[74:77], v[38:41]
	v_mfma_f32_16x16x32_bf16 v[22:25], v[226:229], v[74:77], v[22:25]
	v_mfma_f32_16x16x32_bf16 v[6:9], v[230:233], v[74:77], v[6:9]
	v_mfma_f32_16x16x32_bf16 v[50:53], v[218:221], v[78:81], v[50:53]
	v_mfma_f32_16x16x32_bf16 v[34:37], v[222:225], v[78:81], v[34:37]
	v_mfma_f32_16x16x32_bf16 v[18:21], v[226:229], v[78:81], v[18:21]
	v_mfma_f32_16x16x32_bf16 v[2:5], v[230:233], v[78:81], v[2:5]
	s_waitcnt lgkmcnt(0)
	s_waitcnt vmcnt(8)
	s_barrier
	ds_read_b128 v[218:221], v102 offset:0
	ds_read_b128 v[222:225], v102 offset:2048
	ds_read_b128 v[226:229], v102 offset:4096
	ds_read_b128 v[230:233], v102 offset:6144
	v_mfma_f32_16x16x32_bf16 v[62:65], v[234:237], v[82:85], v[62:65]
	s_add_u32 m0, s4, 0xc000
	v_mfma_f32_16x16x32_bf16 v[46:49], v[238:241], v[82:85], v[46:49]
	global_load_lds_dwordx4 v98, s[6:7]
	v_mfma_f32_16x16x32_bf16 v[30:33], v[242:245], v[82:85], v[30:33]
	v_mfma_f32_16x16x32_bf16 v[14:17], v[246:249], v[82:85], v[14:17]
	v_mfma_f32_16x16x32_bf16 v[58:61], v[234:237], v[86:89], v[58:61]
	s_add_u32 m0, s4, 0xc400
	v_mfma_f32_16x16x32_bf16 v[42:45], v[238:241], v[86:89], v[42:45]
	global_load_lds_dwordx4 v99, s[6:7]
	v_mfma_f32_16x16x32_bf16 v[26:29], v[242:245], v[86:89], v[26:29]
	v_mfma_f32_16x16x32_bf16 v[10:13], v[246:249], v[86:89], v[10:13]
	v_mfma_f32_16x16x32_bf16 v[54:57], v[234:237], v[90:93], v[54:57]
	s_add_u32 m0, s4, 0xc800
	v_mfma_f32_16x16x32_bf16 v[38:41], v[238:241], v[90:93], v[38:41]
	global_load_lds_dwordx4 v100, s[6:7]
	v_mfma_f32_16x16x32_bf16 v[22:25], v[242:245], v[90:93], v[22:25]
	v_mfma_f32_16x16x32_bf16 v[6:9], v[246:249], v[90:93], v[6:9]
	v_mfma_f32_16x16x32_bf16 v[50:53], v[234:237], v[94:97], v[50:53]
	s_add_u32 m0, s4, 0xcc00
	v_mfma_f32_16x16x32_bf16 v[34:37], v[238:241], v[94:97], v[34:37]
	global_load_lds_dwordx4 v101, s[6:7]
	v_mfma_f32_16x16x32_bf16 v[18:21], v[242:245], v[94:97], v[18:21]
	v_mfma_f32_16x16x32_bf16 v[2:5], v[246:249], v[94:97], v[2:5]
	v_add_u32_e32 v98, 0x80, v98
	v_add_u32_e32 v99, 0x80, v99
	v_add_u32_e32 v100, 0x80, v100
	v_add_u32_e32 v101, 0x80, v101
	ds_read_b128 v[234:237], v103 offset:0
	ds_read_b128 v[238:241], v103 offset:2048
	ds_read_b128 v[242:245], v103 offset:4096
	ds_read_b128 v[246:249], v103 offset:6144
	s_waitcnt lgkmcnt(4)
	v_mfma_f32_16x16x32_bf16 v[106:109], v[218:221], v[66:69], v[106:109]
	s_add_u32 m0, s4, 0x10000
	v_mfma_f32_16x16x32_bf16 v[122:125], v[222:225], v[66:69], v[122:125]
	global_load_lds_dwordx4 v98, s[48:49]
	v_mfma_f32_16x16x32_bf16 v[138:141], v[226:229], v[66:69], v[138:141]
	v_mfma_f32_16x16x32_bf16 v[162:165], v[230:233], v[66:69], v[162:165]
	v_mfma_f32_16x16x32_bf16 v[110:113], v[218:221], v[70:73], v[110:113]
	s_add_u32 m0, s4, 0x10400
	v_mfma_f32_16x16x32_bf16 v[126:129], v[222:225], v[70:73], v[126:129]
	global_load_lds_dwordx4 v99, s[48:49]
	v_mfma_f32_16x16x32_bf16 v[142:145], v[226:229], v[70:73], v[142:145]
	v_mfma_f32_16x16x32_bf16 v[166:169], v[230:233], v[70:73], v[166:169]
	v_mfma_f32_16x16x32_bf16 v[114:117], v[218:221], v[74:77], v[114:117]
	s_add_u32 m0, s4, 0x10800
	v_mfma_f32_16x16x32_bf16 v[130:133], v[222:225], v[74:77], v[130:133]
	global_load_lds_dwordx4 v100, s[48:49]
	v_mfma_f32_16x16x32_bf16 v[154:157], v[226:229], v[74:77], v[154:157]
	v_mfma_f32_16x16x32_bf16 v[170:173], v[230:233], v[74:77], v[170:173]
	v_mfma_f32_16x16x32_bf16 v[118:121], v[218:221], v[78:81], v[118:121]
	s_add_u32 m0, s4, 0x10c00
	v_mfma_f32_16x16x32_bf16 v[134:137], v[222:225], v[78:81], v[134:137]
	global_load_lds_dwordx4 v101, s[48:49]
	v_mfma_f32_16x16x32_bf16 v[158:161], v[226:229], v[78:81], v[158:161]
	v_mfma_f32_16x16x32_bf16 v[174:177], v[230:233], v[78:81], v[174:177]
	s_waitcnt lgkmcnt(0)
	s_waitcnt vmcnt(8)
	s_barrier
	ds_read_b128 v[218:221], v102 offset:16384
	ds_read_b128 v[222:225], v102 offset:18432
	ds_read_b128 v[226:229], v102 offset:20480
	ds_read_b128 v[230:233], v102 offset:22528
	ds_read_b128 v[66:69], v104 offset:32768
	ds_read_b128 v[70:73], v104 offset:34816
	ds_read_b128 v[74:77], v104 offset:36864
	ds_read_b128 v[78:81], v104 offset:38912
	v_mfma_f32_16x16x32_bf16 v[106:109], v[234:237], v[82:85], v[106:109]
	s_add_u32 m0, s4, 0x0
	v_mfma_f32_16x16x32_bf16 v[122:125], v[238:241], v[82:85], v[122:125]
	global_load_lds_dwordx4 v98, s[28:29]
	v_mfma_f32_16x16x32_bf16 v[138:141], v[242:245], v[82:85], v[138:141]
	v_mfma_f32_16x16x32_bf16 v[162:165], v[246:249], v[82:85], v[162:165]
	v_mfma_f32_16x16x32_bf16 v[110:113], v[234:237], v[86:89], v[110:113]
	s_add_u32 m0, s4, 0x400
	v_mfma_f32_16x16x32_bf16 v[126:129], v[238:241], v[86:89], v[126:129]
	global_load_lds_dwordx4 v99, s[28:29]
	v_mfma_f32_16x16x32_bf16 v[142:145], v[242:245], v[86:89], v[142:145]
	v_mfma_f32_16x16x32_bf16 v[166:169], v[246:249], v[86:89], v[166:169]
	v_mfma_f32_16x16x32_bf16 v[114:117], v[234:237], v[90:93], v[114:117]
	s_add_u32 m0, s4, 0x800
	v_mfma_f32_16x16x32_bf16 v[130:133], v[238:241], v[90:93], v[130:133]
	global_load_lds_dwordx4 v100, s[28:29]
	v_mfma_f32_16x16x32_bf16 v[154:157], v[242:245], v[90:93], v[154:157]
	v_mfma_f32_16x16x32_bf16 v[170:173], v[246:249], v[90:93], v[170:173]
	v_mfma_f32_16x16x32_bf16 v[118:121], v[234:237], v[94:97], v[118:121]
	s_add_u32 m0, s4, 0xc00
	v_mfma_f32_16x16x32_bf16 v[134:137], v[238:241], v[94:97], v[134:137]
	global_load_lds_dwordx4 v101, s[28:29]
	v_mfma_f32_16x16x32_bf16 v[158:161], v[242:245], v[94:97], v[158:161]
	v_mfma_f32_16x16x32_bf16 v[174:177], v[246:249], v[94:97], v[174:177]
	ds_read_b128 v[234:237], v103 offset:16384
	ds_read_b128 v[238:241], v103 offset:18432
	ds_read_b128 v[242:245], v103 offset:20480
	ds_read_b128 v[246:249], v103 offset:22528
	ds_read_b128 v[82:85], v105 offset:32768
	ds_read_b128 v[86:89], v105 offset:34816
	ds_read_b128 v[90:93], v105 offset:36864
	ds_read_b128 v[94:97], v105 offset:38912
	s_waitcnt lgkmcnt(8)
	v_mfma_f32_16x16x32_bf16 v[62:65], v[218:221], v[66:69], v[62:65]
	v_mfma_f32_16x16x32_bf16 v[46:49], v[222:225], v[66:69], v[46:49]
	v_mfma_f32_16x16x32_bf16 v[30:33], v[226:229], v[66:69], v[30:33]
	v_mfma_f32_16x16x32_bf16 v[14:17], v[230:233], v[66:69], v[14:17]
	v_mfma_f32_16x16x32_bf16 v[58:61], v[218:221], v[70:73], v[58:61]
	v_mfma_f32_16x16x32_bf16 v[42:45], v[222:225], v[70:73], v[42:45]
	v_mfma_f32_16x16x32_bf16 v[26:29], v[226:229], v[70:73], v[26:29]
	v_mfma_f32_16x16x32_bf16 v[10:13], v[230:233], v[70:73], v[10:13]
	v_mfma_f32_16x16x32_bf16 v[54:57], v[218:221], v[74:77], v[54:57]
	v_mfma_f32_16x16x32_bf16 v[38:41], v[222:225], v[74:77], v[38:41]
	v_mfma_f32_16x16x32_bf16 v[22:25], v[226:229], v[74:77], v[22:25]
	v_mfma_f32_16x16x32_bf16 v[6:9], v[230:233], v[74:77], v[6:9]
	v_mfma_f32_16x16x32_bf16 v[50:53], v[218:221], v[78:81], v[50:53]
	v_mfma_f32_16x16x32_bf16 v[34:37], v[222:225], v[78:81], v[34:37]
	v_mfma_f32_16x16x32_bf16 v[18:21], v[226:229], v[78:81], v[18:21]
	v_mfma_f32_16x16x32_bf16 v[2:5], v[230:233], v[78:81], v[2:5]
	s_waitcnt lgkmcnt(0)
	s_waitcnt vmcnt(8)
	s_barrier
	ds_read_b128 v[218:221], v102 offset:49152
	ds_read_b128 v[222:225], v102 offset:51200
	ds_read_b128 v[226:229], v102 offset:53248
	ds_read_b128 v[230:233], v102 offset:55296
	v_mfma_f32_16x16x32_bf16 v[62:65], v[234:237], v[82:85], v[62:65]
	s_add_u32 m0, s4, 0x4000
	v_mfma_f32_16x16x32_bf16 v[46:49], v[238:241], v[82:85], v[46:49]
	global_load_lds_dwordx4 v98, s[6:7]
	v_mfma_f32_16x16x32_bf16 v[30:33], v[242:245], v[82:85], v[30:33]
	v_mfma_f32_16x16x32_bf16 v[14:17], v[246:249], v[82:85], v[14:17]
	v_mfma_f32_16x16x32_bf16 v[58:61], v[234:237], v[86:89], v[58:61]
	s_add_u32 m0, s4, 0x4400
	v_mfma_f32_16x16x32_bf16 v[42:45], v[238:241], v[86:89], v[42:45]
	global_load_lds_dwordx4 v99, s[6:7]
	v_mfma_f32_16x16x32_bf16 v[26:29], v[242:245], v[86:89], v[26:29]
	v_mfma_f32_16x16x32_bf16 v[10:13], v[246:249], v[86:89], v[10:13]
	v_mfma_f32_16x16x32_bf16 v[54:57], v[234:237], v[90:93], v[54:57]
	s_add_u32 m0, s4, 0x4800
	v_mfma_f32_16x16x32_bf16 v[38:41], v[238:241], v[90:93], v[38:41]
	global_load_lds_dwordx4 v100, s[6:7]
	v_mfma_f32_16x16x32_bf16 v[22:25], v[242:245], v[90:93], v[22:25]
	v_mfma_f32_16x16x32_bf16 v[6:9], v[246:249], v[90:93], v[6:9]
	v_mfma_f32_16x16x32_bf16 v[50:53], v[234:237], v[94:97], v[50:53]
	s_add_u32 m0, s4, 0x4c00
	v_mfma_f32_16x16x32_bf16 v[34:37], v[238:241], v[94:97], v[34:37]
	global_load_lds_dwordx4 v101, s[6:7]
	v_mfma_f32_16x16x32_bf16 v[18:21], v[242:245], v[94:97], v[18:21]
	v_mfma_f32_16x16x32_bf16 v[2:5], v[246:249], v[94:97], v[2:5]
	v_add_u32_e32 v98, 0x80, v98
	v_add_u32_e32 v99, 0x80, v99
	v_add_u32_e32 v100, 0x80, v100
	v_add_u32_e32 v101, 0x80, v101
	ds_read_b128 v[234:237], v103 offset:49152
	ds_read_b128 v[238:241], v103 offset:51200
	ds_read_b128 v[242:245], v103 offset:53248
	ds_read_b128 v[246:249], v103 offset:55296
	s_waitcnt lgkmcnt(4)
	v_mfma_f32_16x16x32_bf16 v[106:109], v[218:221], v[66:69], v[106:109]
	s_add_u32 m0, s4, 0x8000
	v_mfma_f32_16x16x32_bf16 v[122:125], v[222:225], v[66:69], v[122:125]
	global_load_lds_dwordx4 v98, s[48:49]
	v_mfma_f32_16x16x32_bf16 v[138:141], v[226:229], v[66:69], v[138:141]
	v_mfma_f32_16x16x32_bf16 v[162:165], v[230:233], v[66:69], v[162:165]
	v_mfma_f32_16x16x32_bf16 v[110:113], v[218:221], v[70:73], v[110:113]
	s_add_u32 m0, s4, 0x8400
	v_mfma_f32_16x16x32_bf16 v[126:129], v[222:225], v[70:73], v[126:129]
	global_load_lds_dwordx4 v99, s[48:49]
	v_mfma_f32_16x16x32_bf16 v[142:145], v[226:229], v[70:73], v[142:145]
	v_mfma_f32_16x16x32_bf16 v[166:169], v[230:233], v[70:73], v[166:169]
	v_mfma_f32_16x16x32_bf16 v[114:117], v[218:221], v[74:77], v[114:117]
	s_add_u32 m0, s4, 0x8800
	v_mfma_f32_16x16x32_bf16 v[130:133], v[222:225], v[74:77], v[130:133]
	global_load_lds_dwordx4 v100, s[48:49]
	v_mfma_f32_16x16x32_bf16 v[154:157], v[226:229], v[74:77], v[154:157]
	v_mfma_f32_16x16x32_bf16 v[170:173], v[230:233], v[74:77], v[170:173]
	v_mfma_f32_16x16x32_bf16 v[118:121], v[218:221], v[78:81], v[118:121]
	s_add_u32 m0, s4, 0x8c00
	v_mfma_f32_16x16x32_bf16 v[134:137], v[222:225], v[78:81], v[134:137]
	global_load_lds_dwordx4 v101, s[48:49]
	v_mfma_f32_16x16x32_bf16 v[158:161], v[226:229], v[78:81], v[158:161]
	v_mfma_f32_16x16x32_bf16 v[174:177], v[230:233], v[78:81], v[174:177]
	s_waitcnt lgkmcnt(0)
	s_waitcnt vmcnt(8)
	s_barrier
	ds_read_b128 v[218:221], v102 offset:0
	ds_read_b128 v[222:225], v102 offset:2048
	ds_read_b128 v[226:229], v102 offset:4096
	ds_read_b128 v[230:233], v102 offset:6144
	ds_read_b128 v[66:69], v250 offset:49152
	ds_read_b128 v[70:73], v250 offset:51200
	ds_read_b128 v[74:77], v250 offset:53248
	ds_read_b128 v[78:81], v250 offset:55296
	v_mfma_f32_16x16x32_bf16 v[106:109], v[234:237], v[82:85], v[106:109]
	s_add_u32 m0, s4, 0xc000
	v_mfma_f32_16x16x32_bf16 v[122:125], v[238:241], v[82:85], v[122:125]
	global_load_lds_dwordx4 v98, s[28:29]
	v_mfma_f32_16x16x32_bf16 v[138:141], v[242:245], v[82:85], v[138:141]
	v_mfma_f32_16x16x32_bf16 v[162:165], v[246:249], v[82:85], v[162:165]
	v_mfma_f32_16x16x32_bf16 v[110:113], v[234:237], v[86:89], v[110:113]
	s_add_u32 m0, s4, 0xc400
	v_mfma_f32_16x16x32_bf16 v[126:129], v[238:241], v[86:89], v[126:129]
	global_load_lds_dwordx4 v99, s[28:29]
	v_mfma_f32_16x16x32_bf16 v[142:145], v[242:245], v[86:89], v[142:145]
	v_mfma_f32_16x16x32_bf16 v[166:169], v[246:249], v[86:89], v[166:169]
	v_mfma_f32_16x16x32_bf16 v[114:117], v[234:237], v[90:93], v[114:117]
	s_add_u32 m0, s4, 0xc800
	v_mfma_f32_16x16x32_bf16 v[130:133], v[238:241], v[90:93], v[130:133]
	global_load_lds_dwordx4 v100, s[28:29]
	v_mfma_f32_16x16x32_bf16 v[154:157], v[242:245], v[90:93], v[154:157]
	v_mfma_f32_16x16x32_bf16 v[170:173], v[246:249], v[90:93], v[170:173]
	v_mfma_f32_16x16x32_bf16 v[118:121], v[234:237], v[94:97], v[118:121]
	s_add_u32 m0, s4, 0xcc00
	v_mfma_f32_16x16x32_bf16 v[134:137], v[238:241], v[94:97], v[134:137]
	global_load_lds_dwordx4 v101, s[28:29]
	v_mfma_f32_16x16x32_bf16 v[158:161], v[242:245], v[94:97], v[158:161]
	v_mfma_f32_16x16x32_bf16 v[174:177], v[246:249], v[94:97], v[174:177]
	ds_read_b128 v[234:237], v103 offset:0
	ds_read_b128 v[238:241], v103 offset:2048
	ds_read_b128 v[242:245], v103 offset:4096
	ds_read_b128 v[246:249], v103 offset:6144
	ds_read_b128 v[82:85], v251 offset:49152
	ds_read_b128 v[86:89], v251 offset:51200
	ds_read_b128 v[90:93], v251 offset:53248
	ds_read_b128 v[94:97], v251 offset:55296
	s_waitcnt lgkmcnt(8)
	v_mfma_f32_16x16x32_bf16 v[62:65], v[218:221], v[66:69], v[62:65]
	v_mfma_f32_16x16x32_bf16 v[46:49], v[222:225], v[66:69], v[46:49]
	v_mfma_f32_16x16x32_bf16 v[30:33], v[226:229], v[66:69], v[30:33]
	v_mfma_f32_16x16x32_bf16 v[14:17], v[230:233], v[66:69], v[14:17]
	v_mfma_f32_16x16x32_bf16 v[58:61], v[218:221], v[70:73], v[58:61]
	v_mfma_f32_16x16x32_bf16 v[42:45], v[222:225], v[70:73], v[42:45]
	v_mfma_f32_16x16x32_bf16 v[26:29], v[226:229], v[70:73], v[26:29]
	v_mfma_f32_16x16x32_bf16 v[10:13], v[230:233], v[70:73], v[10:13]
	v_mfma_f32_16x16x32_bf16 v[54:57], v[218:221], v[74:77], v[54:57]
	v_mfma_f32_16x16x32_bf16 v[38:41], v[222:225], v[74:77], v[38:41]
	v_mfma_f32_16x16x32_bf16 v[22:25], v[226:229], v[74:77], v[22:25]
	v_mfma_f32_16x16x32_bf16 v[6:9], v[230:233], v[74:77], v[6:9]
	v_mfma_f32_16x16x32_bf16 v[50:53], v[218:221], v[78:81], v[50:53]
	v_mfma_f32_16x16x32_bf16 v[34:37], v[222:225], v[78:81], v[34:37]
	v_mfma_f32_16x16x32_bf16 v[18:21], v[226:229], v[78:81], v[18:21]
	v_mfma_f32_16x16x32_bf16 v[2:5], v[230:233], v[78:81], v[2:5]
	s_waitcnt lgkmcnt(0)
	s_waitcnt vmcnt(8)
	s_barrier
	ds_read_b128 v[218:221], v102 offset:16384
	ds_read_b128 v[222:225], v102 offset:18432
	ds_read_b128 v[226:229], v102 offset:20480
	ds_read_b128 v[230:233], v102 offset:22528
	v_mfma_f32_16x16x32_bf16 v[62:65], v[234:237], v[82:85], v[62:65]
	s_add_u32 m0, s4, 0x0
	v_mfma_f32_16x16x32_bf16 v[46:49], v[238:241], v[82:85], v[46:49]
	global_load_lds_dwordx4 v98, s[6:7]
	v_mfma_f32_16x16x32_bf16 v[30:33], v[242:245], v[82:85], v[30:33]
	v_mfma_f32_16x16x32_bf16 v[14:17], v[246:249], v[82:85], v[14:17]
	v_mfma_f32_16x16x32_bf16 v[58:61], v[234:237], v[86:89], v[58:61]
	s_add_u32 m0, s4, 0x400
	v_mfma_f32_16x16x32_bf16 v[42:45], v[238:241], v[86:89], v[42:45]
	global_load_lds_dwordx4 v99, s[6:7]
	v_mfma_f32_16x16x32_bf16 v[26:29], v[242:245], v[86:89], v[26:29]
	v_mfma_f32_16x16x32_bf16 v[10:13], v[246:249], v[86:89], v[10:13]
	v_mfma_f32_16x16x32_bf16 v[54:57], v[234:237], v[90:93], v[54:57]
	s_add_u32 m0, s4, 0x800
	v_mfma_f32_16x16x32_bf16 v[38:41], v[238:241], v[90:93], v[38:41]
	global_load_lds_dwordx4 v100, s[6:7]
	v_mfma_f32_16x16x32_bf16 v[22:25], v[242:245], v[90:93], v[22:25]
	v_mfma_f32_16x16x32_bf16 v[6:9], v[246:249], v[90:93], v[6:9]
	v_mfma_f32_16x16x32_bf16 v[50:53], v[234:237], v[94:97], v[50:53]
	s_add_u32 m0, s4, 0xc00
	v_mfma_f32_16x16x32_bf16 v[34:37], v[238:241], v[94:97], v[34:37]
	global_load_lds_dwordx4 v101, s[6:7]
	v_mfma_f32_16x16x32_bf16 v[18:21], v[242:245], v[94:97], v[18:21]
	v_mfma_f32_16x16x32_bf16 v[2:5], v[246:249], v[94:97], v[2:5]
	v_add_u32_e32 v98, 0x80, v98
	v_add_u32_e32 v99, 0x80, v99
	v_add_u32_e32 v100, 0x80, v100
	v_add_u32_e32 v101, 0x80, v101
	ds_read_b128 v[234:237], v103 offset:16384
	ds_read_b128 v[238:241], v103 offset:18432
	ds_read_b128 v[242:245], v103 offset:20480
	ds_read_b128 v[246:249], v103 offset:22528
	s_waitcnt lgkmcnt(4)
	v_mfma_f32_16x16x32_bf16 v[106:109], v[218:221], v[66:69], v[106:109]
	v_mfma_f32_16x16x32_bf16 v[122:125], v[222:225], v[66:69], v[122:125]
	v_mfma_f32_16x16x32_bf16 v[138:141], v[226:229], v[66:69], v[138:141]
	v_mfma_f32_16x16x32_bf16 v[162:165], v[230:233], v[66:69], v[162:165]
	v_mfma_f32_16x16x32_bf16 v[110:113], v[218:221], v[70:73], v[110:113]
	v_mfma_f32_16x16x32_bf16 v[126:129], v[222:225], v[70:73], v[126:129]
	v_mfma_f32_16x16x32_bf16 v[142:145], v[226:229], v[70:73], v[142:145]
	v_mfma_f32_16x16x32_bf16 v[166:169], v[230:233], v[70:73], v[166:169]
	v_mfma_f32_16x16x32_bf16 v[114:117], v[218:221], v[74:77], v[114:117]
	v_mfma_f32_16x16x32_bf16 v[130:133], v[222:225], v[74:77], v[130:133]
	v_mfma_f32_16x16x32_bf16 v[154:157], v[226:229], v[74:77], v[154:157]
	v_mfma_f32_16x16x32_bf16 v[170:173], v[230:233], v[74:77], v[170:173]
	v_mfma_f32_16x16x32_bf16 v[118:121], v[218:221], v[78:81], v[118:121]
	v_mfma_f32_16x16x32_bf16 v[134:137], v[222:225], v[78:81], v[134:137]
	v_mfma_f32_16x16x32_bf16 v[158:161], v[226:229], v[78:81], v[158:161]
	v_mfma_f32_16x16x32_bf16 v[174:177], v[230:233], v[78:81], v[174:177]
	s_waitcnt lgkmcnt(0)
	s_waitcnt vmcnt(4)
	s_barrier
	ds_read_b128 v[218:221], v102 offset:49152
	ds_read_b128 v[222:225], v102 offset:51200
	ds_read_b128 v[226:229], v102 offset:53248
	ds_read_b128 v[230:233], v102 offset:55296
	ds_read_b128 v[66:69], v104 offset:32768
	ds_read_b128 v[70:73], v104 offset:34816
	ds_read_b128 v[74:77], v104 offset:36864
	ds_read_b128 v[78:81], v104 offset:38912
	v_mfma_f32_16x16x32_bf16 v[106:109], v[234:237], v[82:85], v[106:109]
	v_mfma_f32_16x16x32_bf16 v[122:125], v[238:241], v[82:85], v[122:125]
	v_mfma_f32_16x16x32_bf16 v[138:141], v[242:245], v[82:85], v[138:141]
	v_mfma_f32_16x16x32_bf16 v[162:165], v[246:249], v[82:85], v[162:165]
	v_mfma_f32_16x16x32_bf16 v[110:113], v[234:237], v[86:89], v[110:113]
	v_mfma_f32_16x16x32_bf16 v[126:129], v[238:241], v[86:89], v[126:129]
	v_mfma_f32_16x16x32_bf16 v[142:145], v[242:245], v[86:89], v[142:145]
	v_mfma_f32_16x16x32_bf16 v[166:169], v[246:249], v[86:89], v[166:169]
	v_mfma_f32_16x16x32_bf16 v[114:117], v[234:237], v[90:93], v[114:117]
	v_mfma_f32_16x16x32_bf16 v[130:133], v[238:241], v[90:93], v[130:133]
	v_mfma_f32_16x16x32_bf16 v[154:157], v[242:245], v[90:93], v[154:157]
	v_mfma_f32_16x16x32_bf16 v[170:173], v[246:249], v[90:93], v[170:173]
	v_mfma_f32_16x16x32_bf16 v[118:121], v[234:237], v[94:97], v[118:121]
	v_mfma_f32_16x16x32_bf16 v[134:137], v[238:241], v[94:97], v[134:137]
	v_mfma_f32_16x16x32_bf16 v[158:161], v[242:245], v[94:97], v[158:161]
	v_mfma_f32_16x16x32_bf16 v[174:177], v[246:249], v[94:97], v[174:177]
	ds_read_b128 v[234:237], v103 offset:49152
	ds_read_b128 v[238:241], v103 offset:51200
	ds_read_b128 v[242:245], v103 offset:53248
	ds_read_b128 v[246:249], v103 offset:55296
	ds_read_b128 v[82:85], v105 offset:32768
	ds_read_b128 v[86:89], v105 offset:34816
	ds_read_b128 v[90:93], v105 offset:36864
	ds_read_b128 v[94:97], v105 offset:38912
	s_waitcnt lgkmcnt(8)
	v_mfma_f32_16x16x32_bf16 v[62:65], v[218:221], v[66:69], v[62:65]
	v_mfma_f32_16x16x32_bf16 v[46:49], v[222:225], v[66:69], v[46:49]
	v_mfma_f32_16x16x32_bf16 v[30:33], v[226:229], v[66:69], v[30:33]
	v_mfma_f32_16x16x32_bf16 v[14:17], v[230:233], v[66:69], v[14:17]
	v_mfma_f32_16x16x32_bf16 v[58:61], v[218:221], v[70:73], v[58:61]
	v_mfma_f32_16x16x32_bf16 v[42:45], v[222:225], v[70:73], v[42:45]
	v_mfma_f32_16x16x32_bf16 v[26:29], v[226:229], v[70:73], v[26:29]
	v_mfma_f32_16x16x32_bf16 v[10:13], v[230:233], v[70:73], v[10:13]
	v_mfma_f32_16x16x32_bf16 v[54:57], v[218:221], v[74:77], v[54:57]
	v_mfma_f32_16x16x32_bf16 v[38:41], v[222:225], v[74:77], v[38:41]
	v_mfma_f32_16x16x32_bf16 v[22:25], v[226:229], v[74:77], v[22:25]
	v_mfma_f32_16x16x32_bf16 v[6:9], v[230:233], v[74:77], v[6:9]
	v_mfma_f32_16x16x32_bf16 v[50:53], v[218:221], v[78:81], v[50:53]
	v_mfma_f32_16x16x32_bf16 v[34:37], v[222:225], v[78:81], v[34:37]
	v_mfma_f32_16x16x32_bf16 v[18:21], v[226:229], v[78:81], v[18:21]
	v_mfma_f32_16x16x32_bf16 v[2:5], v[230:233], v[78:81], v[2:5]
	s_waitcnt lgkmcnt(0)
	s_waitcnt vmcnt(0)
	s_barrier
	ds_read_b128 v[218:221], v102 offset:0
	ds_read_b128 v[222:225], v102 offset:2048
	ds_read_b128 v[226:229], v102 offset:4096
	ds_read_b128 v[230:233], v102 offset:6144
	v_mfma_f32_16x16x32_bf16 v[62:65], v[234:237], v[82:85], v[62:65]
	v_mfma_f32_16x16x32_bf16 v[46:49], v[238:241], v[82:85], v[46:49]
	v_mfma_f32_16x16x32_bf16 v[30:33], v[242:245], v[82:85], v[30:33]
	v_mfma_f32_16x16x32_bf16 v[14:17], v[246:249], v[82:85], v[14:17]
	v_mfma_f32_16x16x32_bf16 v[58:61], v[234:237], v[86:89], v[58:61]
	v_mfma_f32_16x16x32_bf16 v[42:45], v[238:241], v[86:89], v[42:45]
	v_mfma_f32_16x16x32_bf16 v[26:29], v[242:245], v[86:89], v[26:29]
	v_mfma_f32_16x16x32_bf16 v[10:13], v[246:249], v[86:89], v[10:13]
	v_mfma_f32_16x16x32_bf16 v[54:57], v[234:237], v[90:93], v[54:57]
	v_mfma_f32_16x16x32_bf16 v[38:41], v[238:241], v[90:93], v[38:41]
	v_mfma_f32_16x16x32_bf16 v[22:25], v[242:245], v[90:93], v[22:25]
	v_mfma_f32_16x16x32_bf16 v[6:9], v[246:249], v[90:93], v[6:9]
	v_mfma_f32_16x16x32_bf16 v[50:53], v[234:237], v[94:97], v[50:53]
	v_mfma_f32_16x16x32_bf16 v[34:37], v[238:241], v[94:97], v[34:37]
	v_mfma_f32_16x16x32_bf16 v[18:21], v[242:245], v[94:97], v[18:21]
	v_mfma_f32_16x16x32_bf16 v[2:5], v[246:249], v[94:97], v[2:5]
	ds_read_b128 v[234:237], v103 offset:0
	ds_read_b128 v[238:241], v103 offset:2048
	ds_read_b128 v[242:245], v103 offset:4096
	ds_read_b128 v[246:249], v103 offset:6144
	s_waitcnt lgkmcnt(4)
	v_mfma_f32_16x16x32_bf16 v[106:109], v[218:221], v[66:69], v[106:109]
	v_mfma_f32_16x16x32_bf16 v[122:125], v[222:225], v[66:69], v[122:125]
	v_mfma_f32_16x16x32_bf16 v[138:141], v[226:229], v[66:69], v[138:141]
	v_mfma_f32_16x16x32_bf16 v[162:165], v[230:233], v[66:69], v[162:165]
	v_mfma_f32_16x16x32_bf16 v[110:113], v[218:221], v[70:73], v[110:113]
	v_mfma_f32_16x16x32_bf16 v[126:129], v[222:225], v[70:73], v[126:129]
	v_mfma_f32_16x16x32_bf16 v[142:145], v[226:229], v[70:73], v[142:145]
	v_mfma_f32_16x16x32_bf16 v[166:169], v[230:233], v[70:73], v[166:169]
	v_mfma_f32_16x16x32_bf16 v[114:117], v[218:221], v[74:77], v[114:117]
	v_mfma_f32_16x16x32_bf16 v[130:133], v[222:225], v[74:77], v[130:133]
	v_mfma_f32_16x16x32_bf16 v[154:157], v[226:229], v[74:77], v[154:157]
	v_mfma_f32_16x16x32_bf16 v[170:173], v[230:233], v[74:77], v[170:173]
	v_mfma_f32_16x16x32_bf16 v[118:121], v[218:221], v[78:81], v[118:121]
	v_mfma_f32_16x16x32_bf16 v[134:137], v[222:225], v[78:81], v[134:137]
	v_mfma_f32_16x16x32_bf16 v[158:161], v[226:229], v[78:81], v[158:161]
	v_mfma_f32_16x16x32_bf16 v[174:177], v[230:233], v[78:81], v[174:177]
	s_waitcnt lgkmcnt(0)
	v_mfma_f32_16x16x32_bf16 v[106:109], v[234:237], v[82:85], v[106:109]
	v_mfma_f32_16x16x32_bf16 v[122:125], v[238:241], v[82:85], v[122:125]
	v_mfma_f32_16x16x32_bf16 v[138:141], v[242:245], v[82:85], v[138:141]
	v_mfma_f32_16x16x32_bf16 v[162:165], v[246:249], v[82:85], v[162:165]
	v_mfma_f32_16x16x32_bf16 v[110:113], v[234:237], v[86:89], v[110:113]
	v_mfma_f32_16x16x32_bf16 v[126:129], v[238:241], v[86:89], v[126:129]
	v_mfma_f32_16x16x32_bf16 v[142:145], v[242:245], v[86:89], v[142:145]
	v_mfma_f32_16x16x32_bf16 v[166:169], v[246:249], v[86:89], v[166:169]
	v_mfma_f32_16x16x32_bf16 v[114:117], v[234:237], v[90:93], v[114:117]
	v_mfma_f32_16x16x32_bf16 v[130:133], v[238:241], v[90:93], v[130:133]
	v_mfma_f32_16x16x32_bf16 v[154:157], v[242:245], v[90:93], v[154:157]
	v_mfma_f32_16x16x32_bf16 v[170:173], v[246:249], v[90:93], v[170:173]
	v_mfma_f32_16x16x32_bf16 v[118:121], v[234:237], v[94:97], v[118:121]
	v_mfma_f32_16x16x32_bf16 v[134:137], v[238:241], v[94:97], v[134:137]
	v_mfma_f32_16x16x32_bf16 v[158:161], v[242:245], v[94:97], v[158:161]
	v_mfma_f32_16x16x32_bf16 v[174:177], v[246:249], v[94:97], v[174:177]
	s_nop 7
	s_barrier
	s_and_b32 s5, s100, 0xff
	s_cmp_lt_u32 s5, 4
	s_cbranch_scc0 .Lpk_tt_nopf
	s_add_i32 s5, s5, 1
	s_lshl_b32 s5, s5, 6
	v_readlane_b32 s6, v254, 7
	s_add_i32 s5, s5, s6
	s_mul_hi_u32 s6, s5, 0x924924a
	s_mul_i32 s7, s6, 28
	s_sub_u32 s5, s5, s7
	s_mul_hi_u32 s7, s5, 0x24924925
	s_mul_i32 s28, s7, 7
	s_sub_u32 s5, s5, s28
	s_and_b32 s28, s6, 3
	s_mul_i32 s28, s28, 7
	s_add_i32 s28, s28, s5
	s_lshl_b32 s48, s28, 18
	s_add_u32 s48, s12, s48
	s_addc_u32 s49, s13, 0
	s_lshr_b32 s6, s6, 2
	s_lshl_b32 s6, s6, 3
	v_readlane_b32 s5, v254, 6
	s_or_b32 s6, s6, s5
	s_lshl_b32 s6, s6, 3
	s_lshl_b32 s7, s7, 1
	s_add_i32 s6, s6, s7
	s_lshl_b32 s6, s6, 18
	s_add_u32 s28, s94, s6
	s_addc_u32 s29, s95, 0
	v_add_u32_e32 v98, 0xfffff800, v98
	v_add_u32_e32 v99, 0xfffff800, v99
	v_add_u32_e32 v100, 0xfffff800, v100
	v_add_u32_e32 v101, 0xfffff800, v101
	s_add_u32 m0, s4, 0xc000
	s_nop 0
	global_load_lds_dwordx4 v98, s[28:29]
	s_add_u32 m0, s4, 0xc400
	s_nop 0
	global_load_lds_dwordx4 v99, s[28:29]
	s_add_u32 m0, s4, 0xc800
	s_nop 0
	global_load_lds_dwordx4 v100, s[28:29]
	s_add_u32 m0, s4, 0xcc00
	s_nop 0
	global_load_lds_dwordx4 v101, s[28:29]
	s_add_u32 m0, s4, 0x10000
	s_nop 0
	global_load_lds_dwordx4 v98, s[48:49]
	s_add_u32 m0, s4, 0x10400
	s_nop 0
	global_load_lds_dwordx4 v99, s[48:49]
	s_add_u32 m0, s4, 0x10800
	s_nop 0
	global_load_lds_dwordx4 v100, s[48:49]
	s_add_u32 m0, s4, 0x10c00
	s_nop 0
	global_load_lds_dwordx4 v101, s[48:49]
	s_or_b32 s100, s100, 0x1000
	s_branch .Lpk_tt_end
